# removed per-phase s_setprio toggles in all 13 GEMM mainloops (plus relaxed vmcnt drains)
# speedup vs baseline: 1.0058x; 1.0058x over previous
; #define PG8_STAGE(bufoff, gbase, voff) do { _Pragma("unroll") for (int _i = 0; _i < 2; ++_i) \
;         __builtin_amdgcn_global_load_lds((const unsigned*)((const char*)(gbase) + (voff)[_i]), (LAS unsigned*)(lds + (bufoff) + ldsw + _i * 8192), 16, 0, 0); } while (0)
; #define PG8_LDA(dst, b, h) do { _Pragma("unroll") for (int m = 0; m < 4; ++m) _Pragma("unroll") for (int k = 0; k < 2; ++k) dst[m][k] = *(const LAS bf16x8*)(lds + PG8_SA(b, h) + aoff + m * 2048 + k * 1024); } while (0)
; #define PG8_LDB(dst, b, h) do { _Pragma("unroll") for (int n = 0; n < 2; ++n) _Pragma("unroll") for (int k = 0; k < 2; ++k) dst[n][k] = *(const LAS bf16x8*)(lds + PG8_SB(b, h) + boff + n * 2048 + k * 1024); } while (0)
; #define PG8_WAIT_V(n) asm volatile("s_waitcnt vmcnt(" #n ")" ::: "memory")
; #define PG8_WAIT_L(n) asm volatile("s_waitcnt lgkmcnt(" #n ")" ::: "memory")
; #define PG8_BAR __builtin_amdgcn_s_barrier()
; #define PG8_SCHED __builtin_amdgcn_sched_barrier(0)
; template <class Epi, class Sched, bool ALIGN_EPI = false, bool SP2 = false>
; __device__ __forceinline__ void gemm_phase(LAS unsigned char* lds, const Gemm g, const Sched S, const Epi E) {
;     ...
;         const char* nA = has_next ? (const char*)g.A + (size_t)nxt.pm * tstep : cA; const char* nB = has_next ? (const char*)g.Bt + (size_t)nxt.pn * tstep : cB;
;         for (int t = 0; t < nt; t += 2) {
;             const bool last = (t == nt - 2);
;             const char* a1 = cA + (size_t)(t + 1) * kstep;
;             const char* a2 = last ? nA : cA + (size_t)(t + 2) * kstep; const char* b2 = last ? nB : cB + (size_t)(t + 2) * kstep;
;             const char* a3 = a2 + kstep; const char* b3 = b2 + kstep;
;             if (last && has_next) S.a_ready(nxt);
;             if (last) E.prefetch(cur, wr, fr, pre);
;             if constexpr (SP2) {
;             PG8_LDB(B0, 0, 0); PG8_LDB(B1, 0, 1); PG8_SCHED; PG8_LDA(At, 0, 0); PG8_STAGE(PG8_SA(1, 1), a1 + hstep, voffA);
;             PG8_WAIT_V(8); PG8_WAIT_L(0); PG8_BAR; PG8_MMA(0, 0, At, B0); PG8_MMA(0, 1, At, B1); PG8_BAR; PG8_SCHED;
;             PG8_LDA(At, 0, 1); PG8_STAGE(PG8_SB(0, 0), b2, voffB); PG8_STAGE(PG8_SB(0, 1), b2 + hstep, voffB); PG8_STAGE(PG8_SA(0, 0), a2, voffA);
;             PG8_WAIT_V(8); PG8_WAIT_L(0); PG8_BAR; PG8_MMA(1, 0, At, B0); PG8_MMA(1, 1, At, B1); PG8_BAR; PG8_SCHED;
.LBB0_106:
	v_add_u32_e32 v145, s33, v149
	ds_read_b128 v[162:165], v145
	ds_read_b128 v[166:169], v145 offset:1024
	ds_read_b128 v[170:173], v145 offset:2048
	ds_read_b128 v[174:177], v145 offset:3072
	v_add_u32_e32 v145, s42, v149
	ds_read_b128 v[178:181], v145
	ds_read_b128 v[182:185], v145 offset:1024
	ds_read_b128 v[186:189], v145 offset:2048
	ds_read_b128 v[194:197], v145 offset:3072
	s_add_u32 s40, s36, 0xfff80080
	s_addc_u32 s41, s37, -1
	s_and_b64 s[38:39], s[38:39], exec
	s_cselect_b32 s41, s25, s41
	s_cselect_b32 s40, s45, s40
	s_cselect_b32 s39, s23, s48
	s_cselect_b32 s38, s46, s47
	v_lshl_add_u64 v[190:191], s[36:37], 0, v[136:137]
	s_add_i32 m0, s9, 0xc000
	ds_read_b128 v[198:201], v151
	ds_read_b128 v[202:205], v151 offset:1024
	ds_read_b128 v[206:209], v151 offset:2048
	ds_read_b128 v[210:213], v151 offset:3072
	ds_read_b128 v[214:217], v151 offset:4096
	ds_read_b128 v[218:221], v151 offset:5120
	ds_read_b128 v[222:225], v151 offset:6144
	ds_read_b128 v[226:229], v151 offset:7168
	global_load_lds_dwordx4 v[190:191], off
	v_lshl_add_u64 v[190:191], s[36:37], 0, v[138:139]
	s_add_i32 m0, s9, 0xe000
	s_nop 0
	global_load_lds_dwordx4 v[190:191], off
	s_waitcnt vmcnt(8)
	s_waitcnt lgkmcnt(0)
	s_barrier
	s_waitcnt lgkmcnt(0)
	v_mfma_f32_16x16x32_bf16 v[124:127], v[162:165], v[198:201], v[124:127]
	v_mfma_f32_16x16x32_bf16 v[120:123], v[170:173], v[198:201], v[120:123]
	v_mfma_f32_16x16x32_bf16 v[108:111], v[162:165], v[206:209], v[108:111]
	v_mfma_f32_16x16x32_bf16 v[104:107], v[170:173], v[206:209], v[104:107]
	v_mfma_f32_16x16x32_bf16 v[92:95], v[162:165], v[214:217], v[92:95]
	v_mfma_f32_16x16x32_bf16 v[88:91], v[170:173], v[214:217], v[88:91]
	v_mfma_f32_16x16x32_bf16 v[76:79], v[162:165], v[222:225], v[76:79]
	v_mfma_f32_16x16x32_bf16 v[72:75], v[170:173], v[222:225], v[72:75]
	v_mfma_f32_16x16x32_bf16 v[124:127], v[166:169], v[202:205], v[124:127]
	v_mfma_f32_16x16x32_bf16 v[120:123], v[174:177], v[202:205], v[120:123]
	v_mfma_f32_16x16x32_bf16 v[108:111], v[166:169], v[210:213], v[108:111]
	v_mfma_f32_16x16x32_bf16 v[104:107], v[174:177], v[210:213], v[104:107]
	v_mfma_f32_16x16x32_bf16 v[92:95], v[166:169], v[218:221], v[92:95]
	v_mfma_f32_16x16x32_bf16 v[88:91], v[174:177], v[218:221], v[88:91]
	v_mfma_f32_16x16x32_bf16 v[76:79], v[166:169], v[226:229], v[76:79]
	v_mfma_f32_16x16x32_bf16 v[72:75], v[174:177], v[226:229], v[72:75]
	v_mfma_f32_16x16x32_bf16 v[116:119], v[178:181], v[198:201], v[116:119]
	v_mfma_f32_16x16x32_bf16 v[112:115], v[186:189], v[198:201], v[112:115]
	v_mfma_f32_16x16x32_bf16 v[100:103], v[178:181], v[206:209], v[100:103]
	v_mfma_f32_16x16x32_bf16 v[96:99], v[186:189], v[206:209], v[96:99]
	v_mfma_f32_16x16x32_bf16 v[84:87], v[178:181], v[214:217], v[84:87]
	v_mfma_f32_16x16x32_bf16 v[80:83], v[186:189], v[214:217], v[80:83]
	v_mfma_f32_16x16x32_bf16 v[68:71], v[178:181], v[222:225], v[68:71]
	v_mfma_f32_16x16x32_bf16 v[64:67], v[186:189], v[222:225], v[64:67]
	v_mfma_f32_16x16x32_bf16 v[116:119], v[182:185], v[202:205], v[116:119]
	v_mfma_f32_16x16x32_bf16 v[112:115], v[194:197], v[202:205], v[112:115]
	v_mfma_f32_16x16x32_bf16 v[100:103], v[182:185], v[210:213], v[100:103]
	v_mfma_f32_16x16x32_bf16 v[96:99], v[194:197], v[210:213], v[96:99]
	v_mfma_f32_16x16x32_bf16 v[84:87], v[182:185], v[218:221], v[84:87]
	v_mfma_f32_16x16x32_bf16 v[80:83], v[194:197], v[218:221], v[80:83]
	v_mfma_f32_16x16x32_bf16 v[68:71], v[182:185], v[226:229], v[68:71]
	v_mfma_f32_16x16x32_bf16 v[64:67], v[194:197], v[226:229], v[64:67]
	s_barrier
	s_add_i32 s50, s33, s4
	v_lshl_add_u64 v[190:191], s[38:39], 0, v[132:133]
	s_mov_b32 m0, s50
	ds_read_b128 v[198:201], v151 offset:16384
	ds_read_b128 v[202:205], v151 offset:17408
	ds_read_b128 v[206:209], v151 offset:18432
	ds_read_b128 v[210:213], v151 offset:19456
	ds_read_b128 v[214:217], v151 offset:20480
	ds_read_b128 v[218:221], v151 offset:21504
	ds_read_b128 v[222:225], v151 offset:22528
	ds_read_b128 v[226:229], v151 offset:23552
	global_load_lds_dwordx4 v[190:191], off
	s_add_i32 m0, s50, 0x2000
	s_add_u32 s50, s38, 0x80000
	v_lshl_add_u64 v[230:231], s[38:39], 0, v[128:129]
	s_addc_u32 s51, s39, 0
	s_add_i32 s52, s42, s4
	global_load_lds_dwordx4 v[230:231], off
	v_lshl_add_u64 v[232:233], s[50:51], 0, v[132:133]
	s_mov_b32 m0, s52
	v_lshl_add_u64 v[234:235], s[40:41], 0, v[130:131]
	global_load_lds_dwordx4 v[232:233], off
	v_lshl_add_u64 v[232:233], s[50:51], 0, v[128:129]
	s_add_i32 m0, s52, 0x2000
	s_nop 0
	global_load_lds_dwordx4 v[232:233], off
	v_lshl_add_u64 v[232:233], s[40:41], 0, v[134:135]
	s_mov_b32 m0, s9
	s_nop 0
	global_load_lds_dwordx4 v[232:233], off
	s_mov_b32 m0, s11
	s_nop 0
	global_load_lds_dwordx4 v[234:235], off
	s_waitcnt vmcnt(8)
	s_waitcnt lgkmcnt(0)
	s_barrier
; #define PG8_STAGE(bufoff, gbase, voff) do { _Pragma("unroll") for (int _i = 0; _i < 2; ++_i) \
;         __builtin_amdgcn_global_load_lds((const unsigned*)((const char*)(gbase) + (voff)[_i]), (LAS unsigned*)(lds + (bufoff) + ldsw + _i * 8192), 16, 0, 0); } while (0)
; #define PG8_LDA(dst, b, h) do { _Pragma("unroll") for (int m = 0; m < 4; ++m) _Pragma("unroll") for (int k = 0; k < 2; ++k) dst[m][k] = *(const LAS bf16x8*)(lds + PG8_SA(b, h) + aoff + m * 2048 + k * 1024); } while (0)
; #define PG8_LDB(dst, b, h) do { _Pragma("unroll") for (int n = 0; n < 2; ++n) _Pragma("unroll") for (int k = 0; k < 2; ++k) dst[n][k] = *(const LAS bf16x8*)(lds + PG8_SB(b, h) + boff + n * 2048 + k * 1024); } while (0)
; #define PG8_MMA(ai, bj, At, Bt) do { __builtin_amdgcn_s_setprio(1); _Pragma("unroll") for (int m = 0; m < 4; ++m) _Pragma("unroll") for (int n = 0; n < 2; ++n) _Pragma("unroll") for (int k = 0; k < 2; ++k) \
;         acc[ai][bj][m][n] = __builtin_amdgcn_mfma_f32_16x16x32_bf16(Bt[n][k], At[m][k], acc[ai][bj][m][n], 0, 0, 0); __builtin_amdgcn_s_setprio(0); } while (0)
; #define PG8_WAIT_V(n) asm volatile("s_waitcnt vmcnt(" #n ")" ::: "memory")
; #define PG8_WAIT_L(n) asm volatile("s_waitcnt lgkmcnt(" #n ")" ::: "memory")
; #define PG8_BAR __builtin_amdgcn_s_barrier()
; #define PG8_SCHED __builtin_amdgcn_sched_barrier(0)
; template <class Epi, class Sched, bool ALIGN_EPI = false, bool SP2 = false>
; __device__ __forceinline__ void gemm_phase(LAS unsigned char* lds, const Gemm g, const Sched S, const Epi E) {
;     ...
;             PG8_WAIT_V(8); PG8_WAIT_L(0); PG8_BAR; PG8_MMA(1, 0, At, B0); PG8_MMA(1, 1, At, B1); PG8_BAR; PG8_SCHED;
;             PG8_LDB(B0, 1, 0); PG8_LDB(B1, 1, 1); PG8_SCHED; PG8_LDA(At, 1, 0); PG8_STAGE(PG8_SA(0, 1), a2 + hstep, voffA);
;             PG8_WAIT_V(8); PG8_WAIT_L(0); PG8_BAR; PG8_MMA(0, 0, At, B0); PG8_MMA(0, 1, At, B1); PG8_BAR; PG8_SCHED;
	s_waitcnt lgkmcnt(0)
	v_mfma_f32_16x16x32_bf16 v[60:63], v[162:165], v[198:201], v[60:63]
	v_mfma_f32_16x16x32_bf16 v[56:59], v[170:173], v[198:201], v[56:59]
	v_mfma_f32_16x16x32_bf16 v[44:47], v[162:165], v[206:209], v[44:47]
	v_mfma_f32_16x16x32_bf16 v[40:43], v[170:173], v[206:209], v[40:43]
	v_mfma_f32_16x16x32_bf16 v[28:31], v[162:165], v[214:217], v[28:31]
	v_mfma_f32_16x16x32_bf16 v[24:27], v[170:173], v[214:217], v[24:27]
	v_mfma_f32_16x16x32_bf16 v[12:15], v[162:165], v[222:225], v[12:15]
	v_mfma_f32_16x16x32_bf16 v[8:11], v[170:173], v[222:225], v[8:11]
	v_mfma_f32_16x16x32_bf16 v[60:63], v[166:169], v[202:205], v[60:63]
	v_mfma_f32_16x16x32_bf16 v[56:59], v[174:177], v[202:205], v[56:59]
	v_mfma_f32_16x16x32_bf16 v[44:47], v[166:169], v[210:213], v[44:47]
	v_mfma_f32_16x16x32_bf16 v[40:43], v[174:177], v[210:213], v[40:43]
	v_mfma_f32_16x16x32_bf16 v[28:31], v[166:169], v[218:221], v[28:31]
	v_mfma_f32_16x16x32_bf16 v[24:27], v[174:177], v[218:221], v[24:27]
	v_mfma_f32_16x16x32_bf16 v[12:15], v[166:169], v[226:229], v[12:15]
	v_mfma_f32_16x16x32_bf16 v[8:11], v[174:177], v[226:229], v[8:11]
	v_mfma_f32_16x16x32_bf16 v[52:55], v[178:181], v[198:201], v[52:55]
	v_mfma_f32_16x16x32_bf16 v[48:51], v[186:189], v[198:201], v[48:51]
	v_mfma_f32_16x16x32_bf16 v[36:39], v[178:181], v[206:209], v[36:39]
	v_mfma_f32_16x16x32_bf16 v[32:35], v[186:189], v[206:209], v[32:35]
	v_mfma_f32_16x16x32_bf16 v[20:23], v[178:181], v[214:217], v[20:23]
	v_mfma_f32_16x16x32_bf16 v[16:19], v[186:189], v[214:217], v[16:19]
	v_mfma_f32_16x16x32_bf16 v[4:7], v[178:181], v[222:225], v[4:7]
	v_mfma_f32_16x16x32_bf16 v[0:3], v[186:189], v[222:225], v[0:3]
	v_mfma_f32_16x16x32_bf16 v[52:55], v[182:185], v[202:205], v[52:55]
	v_mfma_f32_16x16x32_bf16 v[48:51], v[194:197], v[202:205], v[48:51]
	v_mfma_f32_16x16x32_bf16 v[36:39], v[182:185], v[210:213], v[36:39]
	v_mfma_f32_16x16x32_bf16 v[32:35], v[194:197], v[210:213], v[32:35]
	v_mfma_f32_16x16x32_bf16 v[20:23], v[182:185], v[218:221], v[20:23]
	v_mfma_f32_16x16x32_bf16 v[16:19], v[194:197], v[218:221], v[16:19]
	v_mfma_f32_16x16x32_bf16 v[4:7], v[182:185], v[226:229], v[4:7]
	v_mfma_f32_16x16x32_bf16 v[0:3], v[194:197], v[226:229], v[0:3]
	s_barrier
	s_add_i32 s50, 0, 0x18000
	v_add_u32_e32 v145, s50, v149
	s_add_i32 s51, 0, 0x1c000
	ds_read_b128 v[162:165], v145
	ds_read_b128 v[166:169], v145 offset:1024
	ds_read_b128 v[170:173], v145 offset:2048
	ds_read_b128 v[174:177], v145 offset:3072
	v_add_u32_e32 v145, s51, v149
	ds_read_b128 v[178:181], v145
	ds_read_b128 v[182:185], v145 offset:1024
	ds_read_b128 v[186:189], v145 offset:2048
	ds_read_b128 v[194:197], v145 offset:3072
	s_add_u32 s40, s40, 0x80000
	s_addc_u32 s41, s41, 0
	s_mov_b32 m0, s14
	v_lshl_add_u64 v[236:237], s[40:41], 0, v[134:135]
	ds_read_b128 v[198:201], v151 offset:32768
	ds_read_b128 v[202:205], v151 offset:33792
	ds_read_b128 v[206:209], v151 offset:34816
	ds_read_b128 v[210:213], v151 offset:35840
	ds_read_b128 v[214:217], v151 offset:36864
	ds_read_b128 v[218:221], v151 offset:37888
	ds_read_b128 v[222:225], v151 offset:38912
	ds_read_b128 v[226:229], v151 offset:39936
	global_load_lds_dwordx4 v[236:237], off
	v_lshl_add_u64 v[236:237], s[40:41], 0, v[130:131]
	s_mov_b32 m0, s15
	s_nop 0
	global_load_lds_dwordx4 v[236:237], off
	s_waitcnt vmcnt(8)
	s_waitcnt lgkmcnt(0)
	s_barrier
	s_waitcnt lgkmcnt(0)
	v_mfma_f32_16x16x32_bf16 v[124:127], v[162:165], v[198:201], v[124:127]
	v_mfma_f32_16x16x32_bf16 v[120:123], v[170:173], v[198:201], v[120:123]
	v_mfma_f32_16x16x32_bf16 v[108:111], v[162:165], v[206:209], v[108:111]
	v_mfma_f32_16x16x32_bf16 v[104:107], v[170:173], v[206:209], v[104:107]
	v_mfma_f32_16x16x32_bf16 v[92:95], v[162:165], v[214:217], v[92:95]
	v_mfma_f32_16x16x32_bf16 v[88:91], v[170:173], v[214:217], v[88:91]
	v_mfma_f32_16x16x32_bf16 v[76:79], v[162:165], v[222:225], v[76:79]
	v_mfma_f32_16x16x32_bf16 v[72:75], v[170:173], v[222:225], v[72:75]
	v_mfma_f32_16x16x32_bf16 v[124:127], v[166:169], v[202:205], v[124:127]
	v_mfma_f32_16x16x32_bf16 v[120:123], v[174:177], v[202:205], v[120:123]
	v_mfma_f32_16x16x32_bf16 v[108:111], v[166:169], v[210:213], v[108:111]
	v_mfma_f32_16x16x32_bf16 v[104:107], v[174:177], v[210:213], v[104:107]
	v_mfma_f32_16x16x32_bf16 v[92:95], v[166:169], v[218:221], v[92:95]
	v_mfma_f32_16x16x32_bf16 v[88:91], v[174:177], v[218:221], v[88:91]
	v_mfma_f32_16x16x32_bf16 v[76:79], v[166:169], v[226:229], v[76:79]
	v_mfma_f32_16x16x32_bf16 v[72:75], v[174:177], v[226:229], v[72:75]
	v_mfma_f32_16x16x32_bf16 v[116:119], v[178:181], v[198:201], v[116:119]
	v_mfma_f32_16x16x32_bf16 v[112:115], v[186:189], v[198:201], v[112:115]
	v_mfma_f32_16x16x32_bf16 v[100:103], v[178:181], v[206:209], v[100:103]
	v_mfma_f32_16x16x32_bf16 v[96:99], v[186:189], v[206:209], v[96:99]
	v_mfma_f32_16x16x32_bf16 v[84:87], v[178:181], v[214:217], v[84:87]
	v_mfma_f32_16x16x32_bf16 v[80:83], v[186:189], v[214:217], v[80:83]
	v_mfma_f32_16x16x32_bf16 v[68:71], v[178:181], v[222:225], v[68:71]
	v_mfma_f32_16x16x32_bf16 v[64:67], v[186:189], v[222:225], v[64:67]
	v_mfma_f32_16x16x32_bf16 v[116:119], v[182:185], v[202:205], v[116:119]
	v_mfma_f32_16x16x32_bf16 v[112:115], v[194:197], v[202:205], v[112:115]
	v_mfma_f32_16x16x32_bf16 v[100:103], v[182:185], v[210:213], v[100:103]
	v_mfma_f32_16x16x32_bf16 v[96:99], v[194:197], v[210:213], v[96:99]
	v_mfma_f32_16x16x32_bf16 v[84:87], v[182:185], v[218:221], v[84:87]
	v_mfma_f32_16x16x32_bf16 v[80:83], v[194:197], v[218:221], v[80:83]
	v_mfma_f32_16x16x32_bf16 v[68:71], v[182:185], v[226:229], v[68:71]
	v_mfma_f32_16x16x32_bf16 v[64:67], v[194:197], v[226:229], v[64:67]
	s_barrier
; #define PG8_STAGE(bufoff, gbase, voff) do { _Pragma("unroll") for (int _i = 0; _i < 2; ++_i) \
;         __builtin_amdgcn_global_load_lds((const unsigned*)((const char*)(gbase) + (voff)[_i]), (LAS unsigned*)(lds + (bufoff) + ldsw + _i * 8192), 16, 0, 0); } while (0)
; #define PG8_LDA(dst, b, h) do { _Pragma("unroll") for (int m = 0; m < 4; ++m) _Pragma("unroll") for (int k = 0; k < 2; ++k) dst[m][k] = *(const LAS bf16x8*)(lds + PG8_SA(b, h) + aoff + m * 2048 + k * 1024); } while (0)
; #define PG8_MMA(ai, bj, At, Bt) do { __builtin_amdgcn_s_setprio(1); _Pragma("unroll") for (int m = 0; m < 4; ++m) _Pragma("unroll") for (int n = 0; n < 2; ++n) _Pragma("unroll") for (int k = 0; k < 2; ++k) \
;         acc[ai][bj][m][n] = __builtin_amdgcn_mfma_f32_16x16x32_bf16(Bt[n][k], At[m][k], acc[ai][bj][m][n], 0, 0, 0); __builtin_amdgcn_s_setprio(0); } while (0)
; #define PG8_WAIT_V(n) asm volatile("s_waitcnt vmcnt(" #n ")" ::: "memory")
; #define PG8_WAIT_L(n) asm volatile("s_waitcnt lgkmcnt(" #n ")" ::: "memory")
; #define PG8_BAR __builtin_amdgcn_s_barrier()
; #define PG8_SCHED __builtin_amdgcn_sched_barrier(0)
; template <class Epi, class Sched, bool ALIGN_EPI = false, bool SP2 = false>
; __device__ __forceinline__ void gemm_phase(LAS unsigned char* lds, const Gemm g, const Sched S, const Epi E) {
;     ...
;         for (int t = 0; t < nt; t += 2) {
;             const bool last = (t == nt - 2);
;             const char* a1 = cA + (size_t)(t + 1) * kstep;
;             const char* a2 = last ? nA : cA + (size_t)(t + 2) * kstep; const char* b2 = last ? nB : cB + (size_t)(t + 2) * kstep;
;             const char* a3 = a2 + kstep; const char* b3 = b2 + kstep;
;     ...
;             PG8_LDA(At, 1, 1); PG8_STAGE(PG8_SB(1, 0), b3, voffB); PG8_STAGE(PG8_SB(1, 1), b3 + hstep, voffB); PG8_STAGE(PG8_SA(1, 0), a3, voffA);
;             PG8_WAIT_V(8); PG8_WAIT_L(0); PG8_BAR; PG8_MMA(1, 0, At, B0); PG8_MMA(1, 1, At, B1); PG8_BAR; PG8_SCHED;
	s_add_i32 s40, s50, s4
	v_lshl_add_u64 v[190:191], v[190:191], 0, s[18:19]
	s_mov_b32 m0, s40
	ds_read_b128 v[198:201], v151 offset:49152
	ds_read_b128 v[202:205], v151 offset:50176
	ds_read_b128 v[206:209], v151 offset:51200
	ds_read_b128 v[210:213], v151 offset:52224
	ds_read_b128 v[214:217], v151 offset:53248
	ds_read_b128 v[218:221], v151 offset:54272
	ds_read_b128 v[222:225], v151 offset:55296
	ds_read_b128 v[226:229], v151 offset:56320
	global_load_lds_dwordx4 v[190:191], off
	s_add_i32 m0, s40, 0x2000
	s_add_u32 s38, s38, 0x80080
	v_lshl_add_u64 v[190:191], v[230:231], 0, s[18:19]
	s_addc_u32 s39, s39, 0
	s_add_i32 s40, s51, s4
	global_load_lds_dwordx4 v[190:191], off
	v_lshl_add_u64 v[190:191], s[38:39], 0, v[132:133]
	s_mov_b32 m0, s40
	s_nop 0
	global_load_lds_dwordx4 v[190:191], off
	v_lshl_add_u64 v[190:191], s[38:39], 0, v[128:129]
	s_add_i32 m0, s40, 0x2000
	s_nop 0
	global_load_lds_dwordx4 v[190:191], off
	v_lshl_add_u64 v[190:191], v[232:233], 0, s[18:19]
	s_mov_b32 m0, s29
	s_nop 0
	global_load_lds_dwordx4 v[190:191], off
	v_lshl_add_u64 v[190:191], v[234:235], 0, s[18:19]
	s_mov_b32 m0, s30
	s_nop 0
	global_load_lds_dwordx4 v[190:191], off
	s_waitcnt vmcnt(8)
	s_waitcnt lgkmcnt(0)
	s_barrier
	s_waitcnt lgkmcnt(0)
	v_mfma_f32_16x16x32_bf16 v[60:63], v[162:165], v[198:201], v[60:63]
	v_mfma_f32_16x16x32_bf16 v[56:59], v[170:173], v[198:201], v[56:59]
	v_mfma_f32_16x16x32_bf16 v[44:47], v[162:165], v[206:209], v[44:47]
	v_mfma_f32_16x16x32_bf16 v[40:43], v[170:173], v[206:209], v[40:43]
	v_mfma_f32_16x16x32_bf16 v[28:31], v[162:165], v[214:217], v[28:31]
	v_mfma_f32_16x16x32_bf16 v[24:27], v[170:173], v[214:217], v[24:27]
	v_mfma_f32_16x16x32_bf16 v[12:15], v[162:165], v[222:225], v[12:15]
	v_mfma_f32_16x16x32_bf16 v[8:11], v[170:173], v[222:225], v[8:11]
	v_mfma_f32_16x16x32_bf16 v[60:63], v[166:169], v[202:205], v[60:63]
	v_mfma_f32_16x16x32_bf16 v[56:59], v[174:177], v[202:205], v[56:59]
	v_mfma_f32_16x16x32_bf16 v[44:47], v[166:169], v[210:213], v[44:47]
	v_mfma_f32_16x16x32_bf16 v[40:43], v[174:177], v[210:213], v[40:43]
	v_mfma_f32_16x16x32_bf16 v[28:31], v[166:169], v[218:221], v[28:31]
	v_mfma_f32_16x16x32_bf16 v[24:27], v[174:177], v[218:221], v[24:27]
	v_mfma_f32_16x16x32_bf16 v[12:15], v[166:169], v[226:229], v[12:15]
	v_mfma_f32_16x16x32_bf16 v[8:11], v[174:177], v[226:229], v[8:11]
	v_mfma_f32_16x16x32_bf16 v[52:55], v[178:181], v[198:201], v[52:55]
	v_mfma_f32_16x16x32_bf16 v[48:51], v[186:189], v[198:201], v[48:51]
	v_mfma_f32_16x16x32_bf16 v[36:39], v[178:181], v[206:209], v[36:39]
	v_mfma_f32_16x16x32_bf16 v[32:35], v[186:189], v[206:209], v[32:35]
	v_mfma_f32_16x16x32_bf16 v[20:23], v[178:181], v[214:217], v[20:23]
	v_mfma_f32_16x16x32_bf16 v[16:19], v[186:189], v[214:217], v[16:19]
	v_mfma_f32_16x16x32_bf16 v[4:7], v[178:181], v[222:225], v[4:7]
	v_mfma_f32_16x16x32_bf16 v[0:3], v[186:189], v[222:225], v[0:3]
	v_mfma_f32_16x16x32_bf16 v[52:55], v[182:185], v[202:205], v[52:55]
	v_mfma_f32_16x16x32_bf16 v[48:51], v[194:197], v[202:205], v[48:51]
	v_mfma_f32_16x16x32_bf16 v[36:39], v[182:185], v[210:213], v[36:39]
	v_mfma_f32_16x16x32_bf16 v[32:35], v[194:197], v[210:213], v[32:35]
	v_mfma_f32_16x16x32_bf16 v[20:23], v[182:185], v[218:221], v[20:23]
	v_mfma_f32_16x16x32_bf16 v[16:19], v[194:197], v[218:221], v[16:19]
	v_mfma_f32_16x16x32_bf16 v[4:7], v[182:185], v[226:229], v[4:7]
	v_mfma_f32_16x16x32_bf16 v[0:3], v[194:197], v[226:229], v[0:3]
	s_barrier
	s_add_i32 s49, s49, 2
	s_add_u32 s36, s36, 0x100
	s_addc_u32 s37, s37, 0
	s_add_u32 s47, s47, 0x100
	s_addc_u32 s48, s48, 0
	s_cmp_gt_u32 s49, 29
	s_cbranch_scc1 .LBB0_109

; #define PG8_STAGE(bufoff, gbase, voff) do { _Pragma("unroll") for (int _i = 0; _i < 2; ++_i) \
;         __builtin_amdgcn_global_load_lds((const unsigned*)((const char*)(gbase) + (voff)[_i]), (LAS unsigned*)(lds + (bufoff) + ldsw + _i * 8192), 16, 0, 0); } while (0)
; #define PG8_LDA(dst, b, h) do { _Pragma("unroll") for (int m = 0; m < 4; ++m) _Pragma("unroll") for (int k = 0; k < 2; ++k) dst[m][k] = *(const LAS bf16x8*)(lds + PG8_SA(b, h) + aoff + m * 2048 + k * 1024); } while (0)
; #define PG8_LDB(dst, b, h) do { _Pragma("unroll") for (int n = 0; n < 2; ++n) _Pragma("unroll") for (int k = 0; k < 2; ++k) dst[n][k] = *(const LAS bf16x8*)(lds + PG8_SB(b, h) + boff + n * 2048 + k * 1024); } while (0)
; #define PG8_WAIT_V(n) asm volatile("s_waitcnt vmcnt(" #n ")" ::: "memory")
; #define PG8_WAIT_L(n) asm volatile("s_waitcnt lgkmcnt(" #n ")" ::: "memory")
; #define PG8_BAR __builtin_amdgcn_s_barrier()
; #define PG8_SCHED __builtin_amdgcn_sched_barrier(0)
; template <class Epi, class Sched, bool ALIGN_EPI = false, bool SP2 = false>
; __device__ __forceinline__ void gemm_phase(LAS unsigned char* lds, const Gemm g, const Sched S, const Epi E) {
;     ...
;         const char* nA = has_next ? (const char*)g.A + (size_t)nxt.pm * tstep : cA; const char* nB = has_next ? (const char*)g.Bt + (size_t)nxt.pn * tstep : cB;
;         for (int t = 0; t < nt; t += 2) {
;             const bool last = (t == nt - 2);
;             const char* a1 = cA + (size_t)(t + 1) * kstep;
;             const char* a2 = last ? nA : cA + (size_t)(t + 2) * kstep; const char* b2 = last ? nB : cB + (size_t)(t + 2) * kstep;
;             const char* a3 = a2 + kstep; const char* b3 = b2 + kstep;
;             if (last && has_next) S.a_ready(nxt);
;             if (last) E.prefetch(cur, wr, fr, pre);
;             if constexpr (SP2) {
;             PG8_LDB(B0, 0, 0); PG8_LDB(B1, 0, 1); PG8_SCHED; PG8_LDA(At, 0, 0); PG8_STAGE(PG8_SA(1, 1), a1 + hstep, voffA);
;             PG8_WAIT_V(8); PG8_WAIT_L(0); PG8_BAR; PG8_MMA(0, 0, At, B0); PG8_MMA(0, 1, At, B1); PG8_BAR; PG8_SCHED;
;             PG8_LDA(At, 0, 1); PG8_STAGE(PG8_SB(0, 0), b2, voffB); PG8_STAGE(PG8_SB(0, 1), b2 + hstep, voffB); PG8_STAGE(PG8_SA(0, 0), a2, voffA);
;             PG8_WAIT_V(8); PG8_WAIT_L(0); PG8_BAR; PG8_MMA(1, 0, At, B0); PG8_MMA(1, 1, At, B1); PG8_BAR; PG8_SCHED;
.LBB0_193:
	ds_read_b128 v[128:131], v205
	ds_read_b128 v[132:135], v205 offset:1024
	ds_read_b128 v[136:139], v205 offset:2048
	ds_read_b128 v[140:143], v205 offset:3072
	ds_read_b128 v[144:147], v206
	ds_read_b128 v[148:151], v206 offset:1024
	ds_read_b128 v[152:155], v206 offset:2048
	ds_read_b128 v[156:159], v206 offset:3072
	s_add_u32 s36, s34, 0xffea8080
	s_addc_u32 s37, s35, -1
	s_cmpk_eq_i32 s48, 0x52
	s_cselect_b32 s39, s1, s37
	s_cselect_b32 s38, s0, s36
	s_cselect_b32 s37, s27, s47
	s_cselect_b32 s36, s26, s46
	v_lshl_add_u64 v[214:215], s[34:35], 0, v[180:181]
	s_add_i32 m0, s9, 0xc000
	ds_read_b128 v[160:163], v207
	ds_read_b128 v[164:167], v207 offset:1024
	ds_read_b128 v[168:171], v207 offset:2048
	ds_read_b128 v[172:175], v207 offset:3072
	ds_read_b128 v[188:191], v207 offset:4096
	ds_read_b128 v[194:197], v207 offset:5120
	ds_read_b128 v[198:201], v207 offset:6144
	ds_read_b128 v[210:213], v207 offset:7168
	global_load_lds_dwordx4 v[214:215], off
	v_lshl_add_u64 v[214:215], s[34:35], 0, v[182:183]
	s_add_i32 m0, s9, 0xe000
	s_nop 0
	global_load_lds_dwordx4 v[214:215], off
	s_waitcnt vmcnt(8)
	s_waitcnt lgkmcnt(0)
	s_barrier
	s_waitcnt lgkmcnt(0)
	v_mfma_f32_16x16x32_bf16 v[124:127], v[128:131], v[160:163], v[124:127]
	v_mfma_f32_16x16x32_bf16 v[120:123], v[136:139], v[160:163], v[120:123]
	v_mfma_f32_16x16x32_bf16 v[108:111], v[128:131], v[168:171], v[108:111]
	v_mfma_f32_16x16x32_bf16 v[104:107], v[136:139], v[168:171], v[104:107]
	v_mfma_f32_16x16x32_bf16 v[92:95], v[128:131], v[188:191], v[92:95]
	v_mfma_f32_16x16x32_bf16 v[88:91], v[136:139], v[188:191], v[88:91]
	v_mfma_f32_16x16x32_bf16 v[76:79], v[128:131], v[198:201], v[76:79]
	v_mfma_f32_16x16x32_bf16 v[72:75], v[136:139], v[198:201], v[72:75]
	v_mfma_f32_16x16x32_bf16 v[124:127], v[132:135], v[164:167], v[124:127]
	v_mfma_f32_16x16x32_bf16 v[120:123], v[140:143], v[164:167], v[120:123]
	v_mfma_f32_16x16x32_bf16 v[108:111], v[132:135], v[172:175], v[108:111]
	v_mfma_f32_16x16x32_bf16 v[104:107], v[140:143], v[172:175], v[104:107]
	v_mfma_f32_16x16x32_bf16 v[92:95], v[132:135], v[194:197], v[92:95]
	v_mfma_f32_16x16x32_bf16 v[88:91], v[140:143], v[194:197], v[88:91]
	v_mfma_f32_16x16x32_bf16 v[76:79], v[132:135], v[210:213], v[76:79]
	v_mfma_f32_16x16x32_bf16 v[72:75], v[140:143], v[210:213], v[72:75]
	v_mfma_f32_16x16x32_bf16 v[116:119], v[144:147], v[160:163], v[116:119]
	v_mfma_f32_16x16x32_bf16 v[112:115], v[152:155], v[160:163], v[112:115]
	v_mfma_f32_16x16x32_bf16 v[100:103], v[144:147], v[168:171], v[100:103]
	v_mfma_f32_16x16x32_bf16 v[96:99], v[152:155], v[168:171], v[96:99]
	v_mfma_f32_16x16x32_bf16 v[84:87], v[144:147], v[188:191], v[84:87]
	v_mfma_f32_16x16x32_bf16 v[80:83], v[152:155], v[188:191], v[80:83]
	v_mfma_f32_16x16x32_bf16 v[68:71], v[144:147], v[198:201], v[68:71]
	v_mfma_f32_16x16x32_bf16 v[64:67], v[152:155], v[198:201], v[64:67]
	v_mfma_f32_16x16x32_bf16 v[116:119], v[148:151], v[164:167], v[116:119]
	v_mfma_f32_16x16x32_bf16 v[112:115], v[156:159], v[164:167], v[112:115]
	v_mfma_f32_16x16x32_bf16 v[100:103], v[148:151], v[172:175], v[100:103]
	v_mfma_f32_16x16x32_bf16 v[96:99], v[156:159], v[172:175], v[96:99]
	v_mfma_f32_16x16x32_bf16 v[84:87], v[148:151], v[194:197], v[84:87]
	v_mfma_f32_16x16x32_bf16 v[80:83], v[156:159], v[194:197], v[80:83]
	v_mfma_f32_16x16x32_bf16 v[68:71], v[148:151], v[210:213], v[68:71]
	v_mfma_f32_16x16x32_bf16 v[64:67], v[156:159], v[210:213], v[64:67]
	s_barrier
	s_add_i32 s49, s40, s8
	v_lshl_add_u64 v[214:215], s[36:37], 0, v[176:177]
	s_mov_b32 m0, s49
	ds_read_b128 v[160:163], v207 offset:16384
	ds_read_b128 v[164:167], v207 offset:17408
	ds_read_b128 v[168:171], v207 offset:18432
	ds_read_b128 v[172:175], v207 offset:19456
	ds_read_b128 v[188:191], v207 offset:20480
	ds_read_b128 v[194:197], v207 offset:21504
	ds_read_b128 v[198:201], v207 offset:22528
	ds_read_b128 v[210:213], v207 offset:23552
	global_load_lds_dwordx4 v[214:215], off
	s_add_i32 m0, s49, 0x2000
	s_add_u32 s50, s36, 0x158000
	v_lshl_add_u64 v[216:217], s[36:37], 0, v[178:179]
	s_addc_u32 s51, s37, 0
	s_add_i32 s49, s41, s8
	global_load_lds_dwordx4 v[216:217], off
	v_lshl_add_u64 v[218:219], s[50:51], 0, v[176:177]
	s_mov_b32 m0, s49
	v_lshl_add_u64 v[220:221], s[38:39], 0, v[178:179]
	global_load_lds_dwordx4 v[218:219], off
	v_lshl_add_u64 v[218:219], s[50:51], 0, v[178:179]
	s_add_i32 m0, s49, 0x2000
	s_nop 0
	global_load_lds_dwordx4 v[218:219], off
	v_lshl_add_u64 v[218:219], s[38:39], 0, v[176:177]
	s_mov_b32 m0, s9
	s_nop 0
	global_load_lds_dwordx4 v[218:219], off
	s_mov_b32 m0, s11
	s_nop 0
	global_load_lds_dwordx4 v[220:221], off
	s_waitcnt vmcnt(8)
	s_waitcnt lgkmcnt(0)
	s_barrier
; #define PG8_STAGE(bufoff, gbase, voff) do { _Pragma("unroll") for (int _i = 0; _i < 2; ++_i) \
;         __builtin_amdgcn_global_load_lds((const unsigned*)((const char*)(gbase) + (voff)[_i]), (LAS unsigned*)(lds + (bufoff) + ldsw + _i * 8192), 16, 0, 0); } while (0)
; #define PG8_LDA(dst, b, h) do { _Pragma("unroll") for (int m = 0; m < 4; ++m) _Pragma("unroll") for (int k = 0; k < 2; ++k) dst[m][k] = *(const LAS bf16x8*)(lds + PG8_SA(b, h) + aoff + m * 2048 + k * 1024); } while (0)
; #define PG8_LDB(dst, b, h) do { _Pragma("unroll") for (int n = 0; n < 2; ++n) _Pragma("unroll") for (int k = 0; k < 2; ++k) dst[n][k] = *(const LAS bf16x8*)(lds + PG8_SB(b, h) + boff + n * 2048 + k * 1024); } while (0)
; #define PG8_MMA(ai, bj, At, Bt) do { __builtin_amdgcn_s_setprio(1); _Pragma("unroll") for (int m = 0; m < 4; ++m) _Pragma("unroll") for (int n = 0; n < 2; ++n) _Pragma("unroll") for (int k = 0; k < 2; ++k) \
;         acc[ai][bj][m][n] = __builtin_amdgcn_mfma_f32_16x16x32_bf16(Bt[n][k], At[m][k], acc[ai][bj][m][n], 0, 0, 0); __builtin_amdgcn_s_setprio(0); } while (0)
; #define PG8_WAIT_V(n) asm volatile("s_waitcnt vmcnt(" #n ")" ::: "memory")
; #define PG8_WAIT_L(n) asm volatile("s_waitcnt lgkmcnt(" #n ")" ::: "memory")
; #define PG8_BAR __builtin_amdgcn_s_barrier()
; #define PG8_SCHED __builtin_amdgcn_sched_barrier(0)
; template <class Epi, class Sched, bool ALIGN_EPI = false, bool SP2 = false>
; __device__ __forceinline__ void gemm_phase(LAS unsigned char* lds, const Gemm g, const Sched S, const Epi E) {
;     ...
;             PG8_WAIT_V(8); PG8_WAIT_L(0); PG8_BAR; PG8_MMA(1, 0, At, B0); PG8_MMA(1, 1, At, B1); PG8_BAR; PG8_SCHED;
;             PG8_LDB(B0, 1, 0); PG8_LDB(B1, 1, 1); PG8_SCHED; PG8_LDA(At, 1, 0); PG8_STAGE(PG8_SA(0, 1), a2 + hstep, voffA);
;             PG8_WAIT_V(8); PG8_WAIT_L(0); PG8_BAR; PG8_MMA(0, 0, At, B0); PG8_MMA(0, 1, At, B1); PG8_BAR; PG8_SCHED;
	s_waitcnt lgkmcnt(0)
	v_mfma_f32_16x16x32_bf16 v[60:63], v[128:131], v[160:163], v[60:63]
	v_mfma_f32_16x16x32_bf16 v[56:59], v[136:139], v[160:163], v[56:59]
	v_mfma_f32_16x16x32_bf16 v[44:47], v[128:131], v[168:171], v[44:47]
	v_mfma_f32_16x16x32_bf16 v[40:43], v[136:139], v[168:171], v[40:43]
	v_mfma_f32_16x16x32_bf16 v[28:31], v[128:131], v[188:191], v[28:31]
	v_mfma_f32_16x16x32_bf16 v[24:27], v[136:139], v[188:191], v[24:27]
	v_mfma_f32_16x16x32_bf16 v[12:15], v[128:131], v[198:201], v[12:15]
	v_mfma_f32_16x16x32_bf16 v[8:11], v[136:139], v[198:201], v[8:11]
	v_mfma_f32_16x16x32_bf16 v[60:63], v[132:135], v[164:167], v[60:63]
	v_mfma_f32_16x16x32_bf16 v[56:59], v[140:143], v[164:167], v[56:59]
	v_mfma_f32_16x16x32_bf16 v[44:47], v[132:135], v[172:175], v[44:47]
	v_mfma_f32_16x16x32_bf16 v[40:43], v[140:143], v[172:175], v[40:43]
	v_mfma_f32_16x16x32_bf16 v[28:31], v[132:135], v[194:197], v[28:31]
	v_mfma_f32_16x16x32_bf16 v[24:27], v[140:143], v[194:197], v[24:27]
	v_mfma_f32_16x16x32_bf16 v[12:15], v[132:135], v[210:213], v[12:15]
	v_mfma_f32_16x16x32_bf16 v[8:11], v[140:143], v[210:213], v[8:11]
	v_mfma_f32_16x16x32_bf16 v[52:55], v[144:147], v[160:163], v[52:55]
	v_mfma_f32_16x16x32_bf16 v[48:51], v[152:155], v[160:163], v[48:51]
	v_mfma_f32_16x16x32_bf16 v[36:39], v[144:147], v[168:171], v[36:39]
	v_mfma_f32_16x16x32_bf16 v[32:35], v[152:155], v[168:171], v[32:35]
	v_mfma_f32_16x16x32_bf16 v[20:23], v[144:147], v[188:191], v[20:23]
	v_mfma_f32_16x16x32_bf16 v[16:19], v[152:155], v[188:191], v[16:19]
	v_mfma_f32_16x16x32_bf16 v[4:7], v[144:147], v[198:201], v[4:7]
	v_mfma_f32_16x16x32_bf16 v[0:3], v[152:155], v[198:201], v[0:3]
	v_mfma_f32_16x16x32_bf16 v[52:55], v[148:151], v[164:167], v[52:55]
	v_mfma_f32_16x16x32_bf16 v[48:51], v[156:159], v[164:167], v[48:51]
	v_mfma_f32_16x16x32_bf16 v[36:39], v[148:151], v[172:175], v[36:39]
	v_mfma_f32_16x16x32_bf16 v[32:35], v[156:159], v[172:175], v[32:35]
	v_mfma_f32_16x16x32_bf16 v[20:23], v[148:151], v[194:197], v[20:23]
	v_mfma_f32_16x16x32_bf16 v[16:19], v[156:159], v[194:197], v[16:19]
	v_mfma_f32_16x16x32_bf16 v[4:7], v[148:151], v[210:213], v[4:7]
	v_mfma_f32_16x16x32_bf16 v[0:3], v[156:159], v[210:213], v[0:3]
	s_barrier
	s_add_i32 s49, 0, 0x18000
	s_add_i32 s50, 0, 0x1c000
	v_add_u32_e32 v140, s49, v203
	v_add_u32_e32 v156, s50, v203
	ds_read_b128 v[128:131], v140
	ds_read_b128 v[132:135], v140 offset:1024
	ds_read_b128 v[136:139], v140 offset:2048
	ds_read_b128 v[140:143], v140 offset:3072
	ds_read_b128 v[144:147], v156
	ds_read_b128 v[148:151], v156 offset:1024
	ds_read_b128 v[152:155], v156 offset:2048
	ds_read_b128 v[156:159], v156 offset:3072
	s_add_u32 s38, s38, 0x158000
	s_addc_u32 s39, s39, 0
	s_mov_b32 m0, s14
	v_lshl_add_u64 v[222:223], s[38:39], 0, v[176:177]
	ds_read_b128 v[160:163], v207 offset:32768
	ds_read_b128 v[164:167], v207 offset:33792
	ds_read_b128 v[168:171], v207 offset:34816
	ds_read_b128 v[172:175], v207 offset:35840
	ds_read_b128 v[188:191], v207 offset:36864
	ds_read_b128 v[194:197], v207 offset:37888
	ds_read_b128 v[198:201], v207 offset:38912
	ds_read_b128 v[210:213], v207 offset:39936
	global_load_lds_dwordx4 v[222:223], off
	v_lshl_add_u64 v[222:223], s[38:39], 0, v[178:179]
	s_mov_b32 m0, s15
	s_nop 0
	global_load_lds_dwordx4 v[222:223], off
	s_waitcnt vmcnt(8)
	s_waitcnt lgkmcnt(0)
	s_barrier
	s_waitcnt lgkmcnt(0)
	v_mfma_f32_16x16x32_bf16 v[124:127], v[128:131], v[160:163], v[124:127]
	v_mfma_f32_16x16x32_bf16 v[120:123], v[136:139], v[160:163], v[120:123]
	v_mfma_f32_16x16x32_bf16 v[108:111], v[128:131], v[168:171], v[108:111]
	v_mfma_f32_16x16x32_bf16 v[104:107], v[136:139], v[168:171], v[104:107]
	v_mfma_f32_16x16x32_bf16 v[92:95], v[128:131], v[188:191], v[92:95]
	v_mfma_f32_16x16x32_bf16 v[88:91], v[136:139], v[188:191], v[88:91]
	v_mfma_f32_16x16x32_bf16 v[76:79], v[128:131], v[198:201], v[76:79]
	v_mfma_f32_16x16x32_bf16 v[72:75], v[136:139], v[198:201], v[72:75]
	v_mfma_f32_16x16x32_bf16 v[124:127], v[132:135], v[164:167], v[124:127]
	v_mfma_f32_16x16x32_bf16 v[120:123], v[140:143], v[164:167], v[120:123]
	v_mfma_f32_16x16x32_bf16 v[108:111], v[132:135], v[172:175], v[108:111]
	v_mfma_f32_16x16x32_bf16 v[104:107], v[140:143], v[172:175], v[104:107]
	v_mfma_f32_16x16x32_bf16 v[92:95], v[132:135], v[194:197], v[92:95]
	v_mfma_f32_16x16x32_bf16 v[88:91], v[140:143], v[194:197], v[88:91]
	v_mfma_f32_16x16x32_bf16 v[76:79], v[132:135], v[210:213], v[76:79]
	v_mfma_f32_16x16x32_bf16 v[72:75], v[140:143], v[210:213], v[72:75]
	v_mfma_f32_16x16x32_bf16 v[116:119], v[144:147], v[160:163], v[116:119]
	v_mfma_f32_16x16x32_bf16 v[112:115], v[152:155], v[160:163], v[112:115]
	v_mfma_f32_16x16x32_bf16 v[100:103], v[144:147], v[168:171], v[100:103]
	v_mfma_f32_16x16x32_bf16 v[96:99], v[152:155], v[168:171], v[96:99]
	v_mfma_f32_16x16x32_bf16 v[84:87], v[144:147], v[188:191], v[84:87]
	v_mfma_f32_16x16x32_bf16 v[80:83], v[152:155], v[188:191], v[80:83]
	v_mfma_f32_16x16x32_bf16 v[68:71], v[144:147], v[198:201], v[68:71]
	v_mfma_f32_16x16x32_bf16 v[64:67], v[152:155], v[198:201], v[64:67]
	v_mfma_f32_16x16x32_bf16 v[116:119], v[148:151], v[164:167], v[116:119]
	v_mfma_f32_16x16x32_bf16 v[112:115], v[156:159], v[164:167], v[112:115]
	v_mfma_f32_16x16x32_bf16 v[100:103], v[148:151], v[172:175], v[100:103]
	v_mfma_f32_16x16x32_bf16 v[96:99], v[156:159], v[172:175], v[96:99]
	v_mfma_f32_16x16x32_bf16 v[84:87], v[148:151], v[194:197], v[84:87]
	v_mfma_f32_16x16x32_bf16 v[80:83], v[156:159], v[194:197], v[80:83]
	v_mfma_f32_16x16x32_bf16 v[68:71], v[148:151], v[210:213], v[68:71]
	v_mfma_f32_16x16x32_bf16 v[64:67], v[156:159], v[210:213], v[64:67]
	s_barrier
; #define PG8_STAGE(bufoff, gbase, voff) do { _Pragma("unroll") for (int _i = 0; _i < 2; ++_i) \
;         __builtin_amdgcn_global_load_lds((const unsigned*)((const char*)(gbase) + (voff)[_i]), (LAS unsigned*)(lds + (bufoff) + ldsw + _i * 8192), 16, 0, 0); } while (0)
; #define PG8_LDA(dst, b, h) do { _Pragma("unroll") for (int m = 0; m < 4; ++m) _Pragma("unroll") for (int k = 0; k < 2; ++k) dst[m][k] = *(const LAS bf16x8*)(lds + PG8_SA(b, h) + aoff + m * 2048 + k * 1024); } while (0)
; #define PG8_MMA(ai, bj, At, Bt) do { __builtin_amdgcn_s_setprio(1); _Pragma("unroll") for (int m = 0; m < 4; ++m) _Pragma("unroll") for (int n = 0; n < 2; ++n) _Pragma("unroll") for (int k = 0; k < 2; ++k) \
;         acc[ai][bj][m][n] = __builtin_amdgcn_mfma_f32_16x16x32_bf16(Bt[n][k], At[m][k], acc[ai][bj][m][n], 0, 0, 0); __builtin_amdgcn_s_setprio(0); } while (0)
; #define PG8_WAIT_V(n) asm volatile("s_waitcnt vmcnt(" #n ")" ::: "memory")
; #define PG8_WAIT_L(n) asm volatile("s_waitcnt lgkmcnt(" #n ")" ::: "memory")
; #define PG8_BAR __builtin_amdgcn_s_barrier()
; #define PG8_SCHED __builtin_amdgcn_sched_barrier(0)
; template <class Epi, class Sched, bool ALIGN_EPI = false, bool SP2 = false>
; __device__ __forceinline__ void gemm_phase(LAS unsigned char* lds, const Gemm g, const Sched S, const Epi E) {
;     ...
;             PG8_LDA(At, 1, 1); PG8_STAGE(PG8_SB(1, 0), b3, voffB); PG8_STAGE(PG8_SB(1, 1), b3 + hstep, voffB); PG8_STAGE(PG8_SA(1, 0), a3, voffA);
;             PG8_WAIT_V(8); PG8_WAIT_L(0); PG8_BAR; PG8_MMA(1, 0, At, B0); PG8_MMA(1, 1, At, B1); PG8_BAR; PG8_SCHED;
;     ...
;         if constexpr (ALIGN_EPI) { if (wr == 0) PG8_BAR; }
	s_add_i32 s38, s49, s8
	v_lshl_add_u64 v[214:215], v[214:215], 0, s[22:23]
	s_mov_b32 m0, s38
	ds_read_b128 v[160:163], v207 offset:49152
	ds_read_b128 v[164:167], v207 offset:50176
	ds_read_b128 v[168:171], v207 offset:51200
	ds_read_b128 v[172:175], v207 offset:52224
	ds_read_b128 v[188:191], v207 offset:53248
	ds_read_b128 v[194:197], v207 offset:54272
	ds_read_b128 v[198:201], v207 offset:55296
	ds_read_b128 v[210:213], v207 offset:56320
	global_load_lds_dwordx4 v[214:215], off
	s_add_i32 m0, s38, 0x2000
	s_add_u32 s36, s36, 0x158080
	v_lshl_add_u64 v[214:215], v[216:217], 0, s[22:23]
	s_addc_u32 s37, s37, 0
	s_add_i32 s38, s50, s8
	global_load_lds_dwordx4 v[214:215], off
	v_lshl_add_u64 v[214:215], s[36:37], 0, v[176:177]
	s_mov_b32 m0, s38
	s_nop 0
	global_load_lds_dwordx4 v[214:215], off
	v_lshl_add_u64 v[214:215], s[36:37], 0, v[178:179]
	s_add_i32 m0, s38, 0x2000
	s_nop 0
	global_load_lds_dwordx4 v[214:215], off
	v_lshl_add_u64 v[214:215], v[218:219], 0, s[22:23]
	s_mov_b32 m0, s30
	s_nop 0
	global_load_lds_dwordx4 v[214:215], off
	v_lshl_add_u64 v[214:215], v[220:221], 0, s[22:23]
	s_mov_b32 m0, s31
	s_nop 0
	global_load_lds_dwordx4 v[214:215], off
	s_waitcnt vmcnt(8)
	s_waitcnt lgkmcnt(0)
	s_barrier
	s_waitcnt lgkmcnt(0)
	v_mfma_f32_16x16x32_bf16 v[60:63], v[128:131], v[160:163], v[60:63]
	v_mfma_f32_16x16x32_bf16 v[56:59], v[136:139], v[160:163], v[56:59]
	v_mfma_f32_16x16x32_bf16 v[44:47], v[128:131], v[168:171], v[44:47]
	v_mfma_f32_16x16x32_bf16 v[40:43], v[136:139], v[168:171], v[40:43]
	v_mfma_f32_16x16x32_bf16 v[28:31], v[128:131], v[188:191], v[28:31]
	v_mfma_f32_16x16x32_bf16 v[24:27], v[136:139], v[188:191], v[24:27]
	v_mfma_f32_16x16x32_bf16 v[12:15], v[128:131], v[198:201], v[12:15]
	v_mfma_f32_16x16x32_bf16 v[8:11], v[136:139], v[198:201], v[8:11]
	v_mfma_f32_16x16x32_bf16 v[60:63], v[132:135], v[164:167], v[60:63]
	v_mfma_f32_16x16x32_bf16 v[56:59], v[140:143], v[164:167], v[56:59]
	v_mfma_f32_16x16x32_bf16 v[44:47], v[132:135], v[172:175], v[44:47]
	v_mfma_f32_16x16x32_bf16 v[40:43], v[140:143], v[172:175], v[40:43]
	v_mfma_f32_16x16x32_bf16 v[28:31], v[132:135], v[194:197], v[28:31]
	v_mfma_f32_16x16x32_bf16 v[24:27], v[140:143], v[194:197], v[24:27]
	v_mfma_f32_16x16x32_bf16 v[12:15], v[132:135], v[210:213], v[12:15]
	v_mfma_f32_16x16x32_bf16 v[8:11], v[140:143], v[210:213], v[8:11]
	v_mfma_f32_16x16x32_bf16 v[52:55], v[144:147], v[160:163], v[52:55]
	v_mfma_f32_16x16x32_bf16 v[48:51], v[152:155], v[160:163], v[48:51]
	v_mfma_f32_16x16x32_bf16 v[36:39], v[144:147], v[168:171], v[36:39]
	v_mfma_f32_16x16x32_bf16 v[32:35], v[152:155], v[168:171], v[32:35]
	v_mfma_f32_16x16x32_bf16 v[20:23], v[144:147], v[188:191], v[20:23]
	v_mfma_f32_16x16x32_bf16 v[16:19], v[152:155], v[188:191], v[16:19]
	v_mfma_f32_16x16x32_bf16 v[4:7], v[144:147], v[198:201], v[4:7]
	v_mfma_f32_16x16x32_bf16 v[0:3], v[152:155], v[198:201], v[0:3]
	v_mfma_f32_16x16x32_bf16 v[52:55], v[148:151], v[164:167], v[52:55]
	v_mfma_f32_16x16x32_bf16 v[48:51], v[156:159], v[164:167], v[48:51]
	v_mfma_f32_16x16x32_bf16 v[36:39], v[148:151], v[172:175], v[36:39]
	v_mfma_f32_16x16x32_bf16 v[32:35], v[156:159], v[172:175], v[32:35]
	v_mfma_f32_16x16x32_bf16 v[20:23], v[148:151], v[194:197], v[20:23]
	v_mfma_f32_16x16x32_bf16 v[16:19], v[156:159], v[194:197], v[16:19]
	v_mfma_f32_16x16x32_bf16 v[4:7], v[148:151], v[210:213], v[4:7]
	v_mfma_f32_16x16x32_bf16 v[0:3], v[156:159], v[210:213], v[0:3]
	s_barrier
	s_add_i32 s48, s48, 2
	s_add_u32 s34, s34, 0x100
	s_addc_u32 s35, s35, 0
	s_add_u32 s46, s46, 0x100
	s_addc_u32 s47, s47, 0
	s_cmpk_gt_u32 s48, 0x53
	s_cbranch_scc0 .LBB0_193
	s_and_b64 vcc, exec, s[24:25]
	s_cbranch_vccz .LBB0_196
	s_barrier

; #define PG8_STAGE(bufoff, gbase, voff) do { _Pragma("unroll") for (int _i = 0; _i < 2; ++_i) \
;         __builtin_amdgcn_global_load_lds((const unsigned*)((const char*)(gbase) + (voff)[_i]), (LAS unsigned*)(lds + (bufoff) + ldsw + _i * 8192), 16, 0, 0); } while (0)
; #define PG8_LDA(dst, b, h) do { _Pragma("unroll") for (int m = 0; m < 4; ++m) _Pragma("unroll") for (int k = 0; k < 2; ++k) dst[m][k] = *(const LAS bf16x8*)(lds + PG8_SA(b, h) + aoff + m * 2048 + k * 1024); } while (0)
; #define PG8_LDB(dst, b, h) do { _Pragma("unroll") for (int n = 0; n < 2; ++n) _Pragma("unroll") for (int k = 0; k < 2; ++k) dst[n][k] = *(const LAS bf16x8*)(lds + PG8_SB(b, h) + boff + n * 2048 + k * 1024); } while (0)
; #define PG8_WAIT_V(n) asm volatile("s_waitcnt vmcnt(" #n ")" ::: "memory")
; #define PG8_WAIT_L(n) asm volatile("s_waitcnt lgkmcnt(" #n ")" ::: "memory")
; #define PG8_BAR __builtin_amdgcn_s_barrier()
; #define PG8_SCHED __builtin_amdgcn_sched_barrier(0)
; template <class Epi, class Sched, bool ALIGN_EPI = false, bool SP2 = false>
; __device__ __forceinline__ void gemm_phase(LAS unsigned char* lds, const Gemm g, const Sched S, const Epi E) {
;     ...
;         const char* nA = has_next ? (const char*)g.A + (size_t)nxt.pm * tstep : cA; const char* nB = has_next ? (const char*)g.Bt + (size_t)nxt.pn * tstep : cB;
;         for (int t = 0; t < nt; t += 2) {
;             const bool last = (t == nt - 2);
;             const char* a1 = cA + (size_t)(t + 1) * kstep;
;             const char* a2 = last ? nA : cA + (size_t)(t + 2) * kstep; const char* b2 = last ? nB : cB + (size_t)(t + 2) * kstep;
;             const char* a3 = a2 + kstep; const char* b3 = b2 + kstep;
;             if (last && has_next) S.a_ready(nxt);
;             if (last) E.prefetch(cur, wr, fr, pre);
;             if constexpr (SP2) {
;             PG8_LDB(B0, 0, 0); PG8_LDB(B1, 0, 1); PG8_SCHED; PG8_LDA(At, 0, 0); PG8_STAGE(PG8_SA(1, 1), a1 + hstep, voffA);
;             PG8_WAIT_V(8); PG8_WAIT_L(0); PG8_BAR; PG8_MMA(0, 0, At, B0); PG8_MMA(0, 1, At, B1); PG8_BAR; PG8_SCHED;
;             PG8_LDA(At, 0, 1); PG8_STAGE(PG8_SB(0, 0), b2, voffB); PG8_STAGE(PG8_SB(0, 1), b2 + hstep, voffB); PG8_STAGE(PG8_SA(0, 0), a2, voffA);
;             PG8_WAIT_V(8); PG8_WAIT_L(0); PG8_BAR; PG8_MMA(1, 0, At, B0); PG8_MMA(1, 1, At, B1); PG8_BAR; PG8_SCHED;
.LBB0_282:
	v_add_u32_e32 v142, s45, v219
	v_add_u32_e32 v158, s46, v219
	ds_read_b128 v[130:133], v142
	ds_read_b128 v[134:137], v142 offset:1024
	ds_read_b128 v[138:141], v142 offset:2048
	ds_read_b128 v[142:145], v142 offset:3072
	ds_read_b128 v[146:149], v158
	ds_read_b128 v[150:153], v158 offset:1024
	ds_read_b128 v[154:157], v158 offset:2048
	ds_read_b128 v[158:161], v158 offset:3072
	s_add_u32 s42, s4, 0xfff80080
	s_addc_u32 s43, s5, -1
	s_and_b64 s[40:41], s[40:41], exec
	s_cselect_b32 s43, s27, s43
	s_cselect_b32 s42, s39, s42
	s_cselect_b32 s41, s25, s50
	s_cselect_b32 s40, s48, s49
	v_lshl_add_u64 v[190:191], s[4:5], 0, v[208:209]
	s_add_i32 m0, s9, 0xc000
	ds_read_b128 v[162:165], v221
	ds_read_b128 v[166:169], v221 offset:1024
	ds_read_b128 v[170:173], v221 offset:2048
	ds_read_b128 v[174:177], v221 offset:3072
	ds_read_b128 v[178:181], v221 offset:4096
	ds_read_b128 v[182:185], v221 offset:5120
	ds_read_b128 v[186:189], v221 offset:6144
	ds_read_b128 v[234:237], v221 offset:7168
	global_load_lds_dwordx4 v[190:191], off
	v_lshl_add_u64 v[190:191], s[4:5], 0, v[210:211]
	s_add_i32 m0, s9, 0xe000
	s_nop 0
	global_load_lds_dwordx4 v[190:191], off
	s_waitcnt vmcnt(8)
	s_waitcnt lgkmcnt(0)
	s_barrier
	s_waitcnt lgkmcnt(0)
	v_mfma_f32_16x16x32_bf16 v[124:127], v[130:133], v[162:165], v[124:127]
	v_mfma_f32_16x16x32_bf16 v[120:123], v[138:141], v[162:165], v[120:123]
	v_mfma_f32_16x16x32_bf16 v[108:111], v[130:133], v[170:173], v[108:111]
	v_mfma_f32_16x16x32_bf16 v[104:107], v[138:141], v[170:173], v[104:107]
	v_mfma_f32_16x16x32_bf16 v[92:95], v[130:133], v[178:181], v[92:95]
	v_mfma_f32_16x16x32_bf16 v[88:91], v[138:141], v[178:181], v[88:91]
	v_mfma_f32_16x16x32_bf16 v[76:79], v[130:133], v[186:189], v[76:79]
	v_mfma_f32_16x16x32_bf16 v[72:75], v[138:141], v[186:189], v[72:75]
	v_mfma_f32_16x16x32_bf16 v[124:127], v[134:137], v[166:169], v[124:127]
	v_mfma_f32_16x16x32_bf16 v[120:123], v[142:145], v[166:169], v[120:123]
	v_mfma_f32_16x16x32_bf16 v[108:111], v[134:137], v[174:177], v[108:111]
	v_mfma_f32_16x16x32_bf16 v[104:107], v[142:145], v[174:177], v[104:107]
	v_mfma_f32_16x16x32_bf16 v[92:95], v[134:137], v[182:185], v[92:95]
	v_mfma_f32_16x16x32_bf16 v[88:91], v[142:145], v[182:185], v[88:91]
	v_mfma_f32_16x16x32_bf16 v[76:79], v[134:137], v[234:237], v[76:79]
	v_mfma_f32_16x16x32_bf16 v[72:75], v[142:145], v[234:237], v[72:75]
	v_mfma_f32_16x16x32_bf16 v[116:119], v[146:149], v[162:165], v[116:119]
	v_mfma_f32_16x16x32_bf16 v[112:115], v[154:157], v[162:165], v[112:115]
	v_mfma_f32_16x16x32_bf16 v[100:103], v[146:149], v[170:173], v[100:103]
	v_mfma_f32_16x16x32_bf16 v[96:99], v[154:157], v[170:173], v[96:99]
	v_mfma_f32_16x16x32_bf16 v[84:87], v[146:149], v[178:181], v[84:87]
	v_mfma_f32_16x16x32_bf16 v[80:83], v[154:157], v[178:181], v[80:83]
	v_mfma_f32_16x16x32_bf16 v[68:71], v[146:149], v[186:189], v[68:71]
	v_mfma_f32_16x16x32_bf16 v[64:67], v[154:157], v[186:189], v[64:67]
	v_mfma_f32_16x16x32_bf16 v[116:119], v[150:153], v[166:169], v[116:119]
	v_mfma_f32_16x16x32_bf16 v[112:115], v[158:161], v[166:169], v[112:115]
	v_mfma_f32_16x16x32_bf16 v[100:103], v[150:153], v[174:177], v[100:103]
	v_mfma_f32_16x16x32_bf16 v[96:99], v[158:161], v[174:177], v[96:99]
	v_mfma_f32_16x16x32_bf16 v[84:87], v[150:153], v[182:185], v[84:87]
	v_mfma_f32_16x16x32_bf16 v[80:83], v[158:161], v[182:185], v[80:83]
	v_mfma_f32_16x16x32_bf16 v[68:71], v[150:153], v[234:237], v[68:71]
	v_mfma_f32_16x16x32_bf16 v[64:67], v[158:161], v[234:237], v[64:67]
	s_barrier
	s_add_i32 s52, s45, s8
	v_lshl_add_u64 v[190:191], s[40:41], 0, v[196:197]
	s_mov_b32 m0, s52
	ds_read_b128 v[162:165], v221 offset:16384
	ds_read_b128 v[166:169], v221 offset:17408
	ds_read_b128 v[170:173], v221 offset:18432
	ds_read_b128 v[174:177], v221 offset:19456
	ds_read_b128 v[178:181], v221 offset:20480
	ds_read_b128 v[182:185], v221 offset:21504
	ds_read_b128 v[186:189], v221 offset:22528
	ds_read_b128 v[234:237], v221 offset:23552
	global_load_lds_dwordx4 v[190:191], off
	s_add_i32 m0, s52, 0x2000
	s_add_u32 s52, s40, 0x80000
	v_lshl_add_u64 v[238:239], s[40:41], 0, v[200:201]
	s_addc_u32 s53, s41, 0
	s_add_i32 s54, s46, s8
	global_load_lds_dwordx4 v[238:239], off
	v_lshl_add_u64 v[240:241], s[52:53], 0, v[196:197]
	s_mov_b32 m0, s54
	v_lshl_add_u64 v[242:243], s[42:43], 0, v[198:199]
	global_load_lds_dwordx4 v[240:241], off
	v_lshl_add_u64 v[240:241], s[52:53], 0, v[200:201]
	s_add_i32 m0, s54, 0x2000
	s_nop 0
	global_load_lds_dwordx4 v[240:241], off
	v_lshl_add_u64 v[240:241], s[42:43], 0, v[194:195]
	s_mov_b32 m0, s9
	s_nop 0
	global_load_lds_dwordx4 v[240:241], off
	s_mov_b32 m0, s11
	s_nop 0
	global_load_lds_dwordx4 v[242:243], off
	s_waitcnt vmcnt(8)
	s_waitcnt lgkmcnt(0)
	s_barrier
; #define PG8_STAGE(bufoff, gbase, voff) do { _Pragma("unroll") for (int _i = 0; _i < 2; ++_i) \
;         __builtin_amdgcn_global_load_lds((const unsigned*)((const char*)(gbase) + (voff)[_i]), (LAS unsigned*)(lds + (bufoff) + ldsw + _i * 8192), 16, 0, 0); } while (0)
; #define PG8_LDA(dst, b, h) do { _Pragma("unroll") for (int m = 0; m < 4; ++m) _Pragma("unroll") for (int k = 0; k < 2; ++k) dst[m][k] = *(const LAS bf16x8*)(lds + PG8_SA(b, h) + aoff + m * 2048 + k * 1024); } while (0)
; #define PG8_LDB(dst, b, h) do { _Pragma("unroll") for (int n = 0; n < 2; ++n) _Pragma("unroll") for (int k = 0; k < 2; ++k) dst[n][k] = *(const LAS bf16x8*)(lds + PG8_SB(b, h) + boff + n * 2048 + k * 1024); } while (0)
; #define PG8_MMA(ai, bj, At, Bt) do { __builtin_amdgcn_s_setprio(1); _Pragma("unroll") for (int m = 0; m < 4; ++m) _Pragma("unroll") for (int n = 0; n < 2; ++n) _Pragma("unroll") for (int k = 0; k < 2; ++k) \
;         acc[ai][bj][m][n] = __builtin_amdgcn_mfma_f32_16x16x32_bf16(Bt[n][k], At[m][k], acc[ai][bj][m][n], 0, 0, 0); __builtin_amdgcn_s_setprio(0); } while (0)
; #define PG8_WAIT_V(n) asm volatile("s_waitcnt vmcnt(" #n ")" ::: "memory")
; #define PG8_WAIT_L(n) asm volatile("s_waitcnt lgkmcnt(" #n ")" ::: "memory")
; #define PG8_BAR __builtin_amdgcn_s_barrier()
; #define PG8_SCHED __builtin_amdgcn_sched_barrier(0)
; template <class Epi, class Sched, bool ALIGN_EPI = false, bool SP2 = false>
; __device__ __forceinline__ void gemm_phase(LAS unsigned char* lds, const Gemm g, const Sched S, const Epi E) {
;     ...
;             PG8_WAIT_V(8); PG8_WAIT_L(0); PG8_BAR; PG8_MMA(1, 0, At, B0); PG8_MMA(1, 1, At, B1); PG8_BAR; PG8_SCHED;
;             PG8_LDB(B0, 1, 0); PG8_LDB(B1, 1, 1); PG8_SCHED; PG8_LDA(At, 1, 0); PG8_STAGE(PG8_SA(0, 1), a2 + hstep, voffA);
;             PG8_WAIT_V(8); PG8_WAIT_L(0); PG8_BAR; PG8_MMA(0, 0, At, B0); PG8_MMA(0, 1, At, B1); PG8_BAR; PG8_SCHED;
	s_waitcnt lgkmcnt(0)
	v_mfma_f32_16x16x32_bf16 v[60:63], v[130:133], v[162:165], v[60:63]
	v_mfma_f32_16x16x32_bf16 v[56:59], v[138:141], v[162:165], v[56:59]
	v_mfma_f32_16x16x32_bf16 v[44:47], v[130:133], v[170:173], v[44:47]
	v_mfma_f32_16x16x32_bf16 v[40:43], v[138:141], v[170:173], v[40:43]
	v_mfma_f32_16x16x32_bf16 v[28:31], v[130:133], v[178:181], v[28:31]
	v_mfma_f32_16x16x32_bf16 v[24:27], v[138:141], v[178:181], v[24:27]
	v_mfma_f32_16x16x32_bf16 v[12:15], v[130:133], v[186:189], v[12:15]
	v_mfma_f32_16x16x32_bf16 v[8:11], v[138:141], v[186:189], v[8:11]
	v_mfma_f32_16x16x32_bf16 v[60:63], v[134:137], v[166:169], v[60:63]
	v_mfma_f32_16x16x32_bf16 v[56:59], v[142:145], v[166:169], v[56:59]
	v_mfma_f32_16x16x32_bf16 v[44:47], v[134:137], v[174:177], v[44:47]
	v_mfma_f32_16x16x32_bf16 v[40:43], v[142:145], v[174:177], v[40:43]
	v_mfma_f32_16x16x32_bf16 v[28:31], v[134:137], v[182:185], v[28:31]
	v_mfma_f32_16x16x32_bf16 v[24:27], v[142:145], v[182:185], v[24:27]
	v_mfma_f32_16x16x32_bf16 v[12:15], v[134:137], v[234:237], v[12:15]
	v_mfma_f32_16x16x32_bf16 v[8:11], v[142:145], v[234:237], v[8:11]
	v_mfma_f32_16x16x32_bf16 v[52:55], v[146:149], v[162:165], v[52:55]
	v_mfma_f32_16x16x32_bf16 v[48:51], v[154:157], v[162:165], v[48:51]
	v_mfma_f32_16x16x32_bf16 v[36:39], v[146:149], v[170:173], v[36:39]
	v_mfma_f32_16x16x32_bf16 v[32:35], v[154:157], v[170:173], v[32:35]
	v_mfma_f32_16x16x32_bf16 v[20:23], v[146:149], v[178:181], v[20:23]
	v_mfma_f32_16x16x32_bf16 v[16:19], v[154:157], v[178:181], v[16:19]
	v_mfma_f32_16x16x32_bf16 v[4:7], v[146:149], v[186:189], v[4:7]
	v_mfma_f32_16x16x32_bf16 v[0:3], v[154:157], v[186:189], v[0:3]
	v_mfma_f32_16x16x32_bf16 v[52:55], v[150:153], v[166:169], v[52:55]
	v_mfma_f32_16x16x32_bf16 v[48:51], v[158:161], v[166:169], v[48:51]
	v_mfma_f32_16x16x32_bf16 v[36:39], v[150:153], v[174:177], v[36:39]
	v_mfma_f32_16x16x32_bf16 v[32:35], v[158:161], v[174:177], v[32:35]
	v_mfma_f32_16x16x32_bf16 v[20:23], v[150:153], v[182:185], v[20:23]
	v_mfma_f32_16x16x32_bf16 v[16:19], v[158:161], v[182:185], v[16:19]
	v_mfma_f32_16x16x32_bf16 v[4:7], v[150:153], v[234:237], v[4:7]
	v_mfma_f32_16x16x32_bf16 v[0:3], v[158:161], v[234:237], v[0:3]
	s_barrier
	s_add_i32 s52, 0, 0x18000
	s_add_i32 s53, 0, 0x1c000
	v_add_u32_e32 v142, s52, v219
	v_add_u32_e32 v158, s53, v219
	ds_read_b128 v[130:133], v142
	ds_read_b128 v[134:137], v142 offset:1024
	ds_read_b128 v[138:141], v142 offset:2048
	ds_read_b128 v[142:145], v142 offset:3072
	ds_read_b128 v[146:149], v158
	ds_read_b128 v[150:153], v158 offset:1024
	ds_read_b128 v[154:157], v158 offset:2048
	ds_read_b128 v[158:161], v158 offset:3072
	s_add_u32 s42, s42, 0x80000
	s_addc_u32 s43, s43, 0
	s_mov_b32 m0, s14
	v_lshl_add_u64 v[244:245], s[42:43], 0, v[194:195]
	ds_read_b128 v[162:165], v221 offset:32768
	ds_read_b128 v[166:169], v221 offset:33792
	ds_read_b128 v[170:173], v221 offset:34816
	ds_read_b128 v[174:177], v221 offset:35840
	ds_read_b128 v[178:181], v221 offset:36864
	ds_read_b128 v[182:185], v221 offset:37888
	ds_read_b128 v[186:189], v221 offset:38912
	ds_read_b128 v[234:237], v221 offset:39936
	global_load_lds_dwordx4 v[244:245], off
	v_lshl_add_u64 v[244:245], s[42:43], 0, v[198:199]
	s_mov_b32 m0, s15
	s_nop 0
	global_load_lds_dwordx4 v[244:245], off
	s_waitcnt vmcnt(8)
	s_waitcnt lgkmcnt(0)
	s_barrier
	s_waitcnt lgkmcnt(0)
	v_mfma_f32_16x16x32_bf16 v[124:127], v[130:133], v[162:165], v[124:127]
	v_mfma_f32_16x16x32_bf16 v[120:123], v[138:141], v[162:165], v[120:123]
	v_mfma_f32_16x16x32_bf16 v[108:111], v[130:133], v[170:173], v[108:111]
	v_mfma_f32_16x16x32_bf16 v[104:107], v[138:141], v[170:173], v[104:107]
	v_mfma_f32_16x16x32_bf16 v[92:95], v[130:133], v[178:181], v[92:95]
	v_mfma_f32_16x16x32_bf16 v[88:91], v[138:141], v[178:181], v[88:91]
	v_mfma_f32_16x16x32_bf16 v[76:79], v[130:133], v[186:189], v[76:79]
	v_mfma_f32_16x16x32_bf16 v[72:75], v[138:141], v[186:189], v[72:75]
	v_mfma_f32_16x16x32_bf16 v[124:127], v[134:137], v[166:169], v[124:127]
	v_mfma_f32_16x16x32_bf16 v[120:123], v[142:145], v[166:169], v[120:123]
	v_mfma_f32_16x16x32_bf16 v[108:111], v[134:137], v[174:177], v[108:111]
	v_mfma_f32_16x16x32_bf16 v[104:107], v[142:145], v[174:177], v[104:107]
	v_mfma_f32_16x16x32_bf16 v[92:95], v[134:137], v[182:185], v[92:95]
	v_mfma_f32_16x16x32_bf16 v[88:91], v[142:145], v[182:185], v[88:91]
	v_mfma_f32_16x16x32_bf16 v[76:79], v[134:137], v[234:237], v[76:79]
	v_mfma_f32_16x16x32_bf16 v[72:75], v[142:145], v[234:237], v[72:75]
	v_mfma_f32_16x16x32_bf16 v[116:119], v[146:149], v[162:165], v[116:119]
	v_mfma_f32_16x16x32_bf16 v[112:115], v[154:157], v[162:165], v[112:115]
	v_mfma_f32_16x16x32_bf16 v[100:103], v[146:149], v[170:173], v[100:103]
	v_mfma_f32_16x16x32_bf16 v[96:99], v[154:157], v[170:173], v[96:99]
	v_mfma_f32_16x16x32_bf16 v[84:87], v[146:149], v[178:181], v[84:87]
	v_mfma_f32_16x16x32_bf16 v[80:83], v[154:157], v[178:181], v[80:83]
	v_mfma_f32_16x16x32_bf16 v[68:71], v[146:149], v[186:189], v[68:71]
	v_mfma_f32_16x16x32_bf16 v[64:67], v[154:157], v[186:189], v[64:67]
	v_mfma_f32_16x16x32_bf16 v[116:119], v[150:153], v[166:169], v[116:119]
	v_mfma_f32_16x16x32_bf16 v[112:115], v[158:161], v[166:169], v[112:115]
	v_mfma_f32_16x16x32_bf16 v[100:103], v[150:153], v[174:177], v[100:103]
	v_mfma_f32_16x16x32_bf16 v[96:99], v[158:161], v[174:177], v[96:99]
	v_mfma_f32_16x16x32_bf16 v[84:87], v[150:153], v[182:185], v[84:87]
	v_mfma_f32_16x16x32_bf16 v[80:83], v[158:161], v[182:185], v[80:83]
	v_mfma_f32_16x16x32_bf16 v[68:71], v[150:153], v[234:237], v[68:71]
	v_mfma_f32_16x16x32_bf16 v[64:67], v[158:161], v[234:237], v[64:67]
	s_barrier
; #define PG8_STAGE(bufoff, gbase, voff) do { _Pragma("unroll") for (int _i = 0; _i < 2; ++_i) \
;         __builtin_amdgcn_global_load_lds((const unsigned*)((const char*)(gbase) + (voff)[_i]), (LAS unsigned*)(lds + (bufoff) + ldsw + _i * 8192), 16, 0, 0); } while (0)
; #define PG8_LDA(dst, b, h) do { _Pragma("unroll") for (int m = 0; m < 4; ++m) _Pragma("unroll") for (int k = 0; k < 2; ++k) dst[m][k] = *(const LAS bf16x8*)(lds + PG8_SA(b, h) + aoff + m * 2048 + k * 1024); } while (0)
; #define PG8_MMA(ai, bj, At, Bt) do { __builtin_amdgcn_s_setprio(1); _Pragma("unroll") for (int m = 0; m < 4; ++m) _Pragma("unroll") for (int n = 0; n < 2; ++n) _Pragma("unroll") for (int k = 0; k < 2; ++k) \
;         acc[ai][bj][m][n] = __builtin_amdgcn_mfma_f32_16x16x32_bf16(Bt[n][k], At[m][k], acc[ai][bj][m][n], 0, 0, 0); __builtin_amdgcn_s_setprio(0); } while (0)
; #define PG8_WAIT_V(n) asm volatile("s_waitcnt vmcnt(" #n ")" ::: "memory")
; #define PG8_WAIT_L(n) asm volatile("s_waitcnt lgkmcnt(" #n ")" ::: "memory")
; #define PG8_BAR __builtin_amdgcn_s_barrier()
; #define PG8_SCHED __builtin_amdgcn_sched_barrier(0)
; template <class Epi, class Sched, bool ALIGN_EPI = false, bool SP2 = false>
; __device__ __forceinline__ void gemm_phase(LAS unsigned char* lds, const Gemm g, const Sched S, const Epi E) {
;     ...
;         for (int t = 0; t < nt; t += 2) {
;             const bool last = (t == nt - 2);
;             const char* a1 = cA + (size_t)(t + 1) * kstep;
;             const char* a2 = last ? nA : cA + (size_t)(t + 2) * kstep; const char* b2 = last ? nB : cB + (size_t)(t + 2) * kstep;
;             const char* a3 = a2 + kstep; const char* b3 = b2 + kstep;
;     ...
;             PG8_LDA(At, 1, 1); PG8_STAGE(PG8_SB(1, 0), b3, voffB); PG8_STAGE(PG8_SB(1, 1), b3 + hstep, voffB); PG8_STAGE(PG8_SA(1, 0), a3, voffA);
;             PG8_WAIT_V(8); PG8_WAIT_L(0); PG8_BAR; PG8_MMA(1, 0, At, B0); PG8_MMA(1, 1, At, B1); PG8_BAR; PG8_SCHED;
	s_add_i32 s42, s52, s8
	v_lshl_add_u64 v[190:191], v[190:191], 0, s[20:21]
	s_mov_b32 m0, s42
	ds_read_b128 v[162:165], v221 offset:49152
	ds_read_b128 v[166:169], v221 offset:50176
	ds_read_b128 v[170:173], v221 offset:51200
	ds_read_b128 v[174:177], v221 offset:52224
	ds_read_b128 v[178:181], v221 offset:53248
	ds_read_b128 v[182:185], v221 offset:54272
	ds_read_b128 v[186:189], v221 offset:55296
	ds_read_b128 v[234:237], v221 offset:56320
	global_load_lds_dwordx4 v[190:191], off
	s_add_i32 m0, s42, 0x2000
	s_add_u32 s40, s40, 0x80080
	v_lshl_add_u64 v[190:191], v[238:239], 0, s[20:21]
	s_addc_u32 s41, s41, 0
	s_add_i32 s42, s53, s8
	global_load_lds_dwordx4 v[190:191], off
	v_lshl_add_u64 v[190:191], s[40:41], 0, v[196:197]
	s_mov_b32 m0, s42
	s_nop 0
	global_load_lds_dwordx4 v[190:191], off
	v_lshl_add_u64 v[190:191], s[40:41], 0, v[200:201]
	s_add_i32 m0, s42, 0x2000
	s_nop 0
	global_load_lds_dwordx4 v[190:191], off
	v_lshl_add_u64 v[190:191], v[240:241], 0, s[20:21]
	s_mov_b32 m0, s30
	s_nop 0
	global_load_lds_dwordx4 v[190:191], off
	v_lshl_add_u64 v[190:191], v[242:243], 0, s[20:21]
	s_mov_b32 m0, s31
	s_nop 0
	global_load_lds_dwordx4 v[190:191], off
	s_waitcnt vmcnt(8)
	s_waitcnt lgkmcnt(0)
	s_barrier
	s_waitcnt lgkmcnt(0)
	v_mfma_f32_16x16x32_bf16 v[60:63], v[130:133], v[162:165], v[60:63]
	v_mfma_f32_16x16x32_bf16 v[56:59], v[138:141], v[162:165], v[56:59]
	v_mfma_f32_16x16x32_bf16 v[44:47], v[130:133], v[170:173], v[44:47]
	v_mfma_f32_16x16x32_bf16 v[40:43], v[138:141], v[170:173], v[40:43]
	v_mfma_f32_16x16x32_bf16 v[28:31], v[130:133], v[178:181], v[28:31]
	v_mfma_f32_16x16x32_bf16 v[24:27], v[138:141], v[178:181], v[24:27]
	v_mfma_f32_16x16x32_bf16 v[12:15], v[130:133], v[186:189], v[12:15]
	v_mfma_f32_16x16x32_bf16 v[8:11], v[138:141], v[186:189], v[8:11]
	v_mfma_f32_16x16x32_bf16 v[60:63], v[134:137], v[166:169], v[60:63]
	v_mfma_f32_16x16x32_bf16 v[56:59], v[142:145], v[166:169], v[56:59]
	v_mfma_f32_16x16x32_bf16 v[44:47], v[134:137], v[174:177], v[44:47]
	v_mfma_f32_16x16x32_bf16 v[40:43], v[142:145], v[174:177], v[40:43]
	v_mfma_f32_16x16x32_bf16 v[28:31], v[134:137], v[182:185], v[28:31]
	v_mfma_f32_16x16x32_bf16 v[24:27], v[142:145], v[182:185], v[24:27]
	v_mfma_f32_16x16x32_bf16 v[12:15], v[134:137], v[234:237], v[12:15]
	v_mfma_f32_16x16x32_bf16 v[8:11], v[142:145], v[234:237], v[8:11]
	v_mfma_f32_16x16x32_bf16 v[52:55], v[146:149], v[162:165], v[52:55]
	v_mfma_f32_16x16x32_bf16 v[48:51], v[154:157], v[162:165], v[48:51]
	v_mfma_f32_16x16x32_bf16 v[36:39], v[146:149], v[170:173], v[36:39]
	v_mfma_f32_16x16x32_bf16 v[32:35], v[154:157], v[170:173], v[32:35]
	v_mfma_f32_16x16x32_bf16 v[20:23], v[146:149], v[178:181], v[20:23]
	v_mfma_f32_16x16x32_bf16 v[16:19], v[154:157], v[178:181], v[16:19]
	v_mfma_f32_16x16x32_bf16 v[4:7], v[146:149], v[186:189], v[4:7]
	v_mfma_f32_16x16x32_bf16 v[0:3], v[154:157], v[186:189], v[0:3]
	v_mfma_f32_16x16x32_bf16 v[52:55], v[150:153], v[166:169], v[52:55]
	v_mfma_f32_16x16x32_bf16 v[48:51], v[158:161], v[166:169], v[48:51]
	v_mfma_f32_16x16x32_bf16 v[36:39], v[150:153], v[174:177], v[36:39]
	v_mfma_f32_16x16x32_bf16 v[32:35], v[158:161], v[174:177], v[32:35]
	v_mfma_f32_16x16x32_bf16 v[20:23], v[150:153], v[182:185], v[20:23]
	v_mfma_f32_16x16x32_bf16 v[16:19], v[158:161], v[182:185], v[16:19]
	v_mfma_f32_16x16x32_bf16 v[4:7], v[150:153], v[234:237], v[4:7]
	v_mfma_f32_16x16x32_bf16 v[0:3], v[158:161], v[234:237], v[0:3]
	s_barrier
	s_add_i32 s51, s51, 2
	s_add_u32 s4, s4, 0x100
	s_addc_u32 s5, s5, 0
	s_add_u32 s49, s49, 0x100
	s_addc_u32 s50, s50, 0
	s_cmp_gt_u32 s51, 29
	s_cbranch_scc1 .LBB0_285

; #define PG8_STAGE(bufoff, gbase, voff) do { _Pragma("unroll") for (int _i = 0; _i < 2; ++_i) \
;         __builtin_amdgcn_global_load_lds((const unsigned*)((const char*)(gbase) + (voff)[_i]), (LAS unsigned*)(lds + (bufoff) + ldsw + _i * 8192), 16, 0, 0); } while (0)
; #define PG8_LDA(dst, b, h) do { _Pragma("unroll") for (int m = 0; m < 4; ++m) _Pragma("unroll") for (int k = 0; k < 2; ++k) dst[m][k] = *(const LAS bf16x8*)(lds + PG8_SA(b, h) + aoff + m * 2048 + k * 1024); } while (0)
; #define PG8_LDB(dst, b, h) do { _Pragma("unroll") for (int n = 0; n < 2; ++n) _Pragma("unroll") for (int k = 0; k < 2; ++k) dst[n][k] = *(const LAS bf16x8*)(lds + PG8_SB(b, h) + boff + n * 2048 + k * 1024); } while (0)
; #define PG8_WAIT_V(n) asm volatile("s_waitcnt vmcnt(" #n ")" ::: "memory")
; #define PG8_WAIT_L(n) asm volatile("s_waitcnt lgkmcnt(" #n ")" ::: "memory")
; #define PG8_BAR __builtin_amdgcn_s_barrier()
; #define PG8_SCHED __builtin_amdgcn_sched_barrier(0)
; template <class Epi, class Sched, bool ALIGN_EPI = false, bool SP2 = false>
; __device__ __forceinline__ void gemm_phase(LAS unsigned char* lds, const Gemm g, const Sched S, const Epi E) {
;     ...
;         const char* nA = has_next ? (const char*)g.A + (size_t)nxt.pm * tstep : cA; const char* nB = has_next ? (const char*)g.Bt + (size_t)nxt.pn * tstep : cB;
;         for (int t = 0; t < nt; t += 2) {
;             const bool last = (t == nt - 2);
;             const char* a1 = cA + (size_t)(t + 1) * kstep;
;             const char* a2 = last ? nA : cA + (size_t)(t + 2) * kstep; const char* b2 = last ? nB : cB + (size_t)(t + 2) * kstep;
;             const char* a3 = a2 + kstep; const char* b3 = b2 + kstep;
;             if (last && has_next) S.a_ready(nxt);
;             if (last) E.prefetch(cur, wr, fr, pre);
;             if constexpr (SP2) {
;             PG8_LDB(B0, 0, 0); PG8_LDB(B1, 0, 1); PG8_SCHED; PG8_LDA(At, 0, 0); PG8_STAGE(PG8_SA(1, 1), a1 + hstep, voffA);
;             PG8_WAIT_V(8); PG8_WAIT_L(0); PG8_BAR; PG8_MMA(0, 0, At, B0); PG8_MMA(0, 1, At, B1); PG8_BAR; PG8_SCHED;
;             PG8_LDA(At, 0, 1); PG8_STAGE(PG8_SB(0, 0), b2, voffB); PG8_STAGE(PG8_SB(0, 1), b2 + hstep, voffB); PG8_STAGE(PG8_SA(0, 0), a2, voffA);
;             PG8_WAIT_V(8); PG8_WAIT_L(0); PG8_BAR; PG8_MMA(1, 0, At, B0); PG8_MMA(1, 1, At, B1); PG8_BAR; PG8_SCHED;
.LBB0_478:
	ds_read_b128 v[128:131], v215
	ds_read_b128 v[132:135], v215 offset:1024
	ds_read_b128 v[136:139], v215 offset:2048
	ds_read_b128 v[140:143], v215 offset:3072
	ds_read_b128 v[144:147], v216
	ds_read_b128 v[148:151], v216 offset:1024
	ds_read_b128 v[152:155], v216 offset:2048
	ds_read_b128 v[156:159], v216 offset:3072
	s_add_u32 s42, s40, 0xfffc0080
	s_addc_u32 s43, s41, -1
	s_cmp_eq_u32 s52, 12
	s_cselect_b32 s45, s27, s43
	s_cselect_b32 s44, s48, s42
	s_cselect_b32 s43, s25, s51
	s_cselect_b32 s42, s49, s50
	v_lshl_add_u64 v[210:211], s[40:41], 0, v[168:169]
	s_add_i32 m0, s11, 0xc000
	ds_read_b128 v[176:179], v217
	ds_read_b128 v[180:183], v217 offset:1024
	ds_read_b128 v[184:187], v217 offset:2048
	ds_read_b128 v[188:191], v217 offset:3072
	ds_read_b128 v[194:197], v217 offset:4096
	ds_read_b128 v[198:201], v217 offset:5120
	ds_read_b128 v[202:205], v217 offset:6144
	ds_read_b128 v[206:209], v217 offset:7168
	global_load_lds_dwordx4 v[210:211], off
	v_lshl_add_u64 v[210:211], s[40:41], 0, v[170:171]
	s_add_i32 m0, s11, 0xe000
	s_nop 0
	global_load_lds_dwordx4 v[210:211], off
	s_waitcnt vmcnt(8)
	s_waitcnt lgkmcnt(0)
	s_barrier
	s_waitcnt lgkmcnt(0)
	v_mfma_f32_16x16x32_bf16 v[124:127], v[128:131], v[176:179], v[124:127]
	v_mfma_f32_16x16x32_bf16 v[120:123], v[136:139], v[176:179], v[120:123]
	v_mfma_f32_16x16x32_bf16 v[116:119], v[128:131], v[184:187], v[116:119]
	v_mfma_f32_16x16x32_bf16 v[112:115], v[136:139], v[184:187], v[112:115]
	v_mfma_f32_16x16x32_bf16 v[108:111], v[128:131], v[194:197], v[108:111]
	v_mfma_f32_16x16x32_bf16 v[104:107], v[136:139], v[194:197], v[104:107]
	v_mfma_f32_16x16x32_bf16 v[100:103], v[128:131], v[202:205], v[100:103]
	v_mfma_f32_16x16x32_bf16 v[96:99], v[136:139], v[202:205], v[96:99]
	v_mfma_f32_16x16x32_bf16 v[124:127], v[132:135], v[180:183], v[124:127]
	v_mfma_f32_16x16x32_bf16 v[120:123], v[140:143], v[180:183], v[120:123]
	v_mfma_f32_16x16x32_bf16 v[116:119], v[132:135], v[188:191], v[116:119]
	v_mfma_f32_16x16x32_bf16 v[112:115], v[140:143], v[188:191], v[112:115]
	v_mfma_f32_16x16x32_bf16 v[108:111], v[132:135], v[198:201], v[108:111]
	v_mfma_f32_16x16x32_bf16 v[104:107], v[140:143], v[198:201], v[104:107]
	v_mfma_f32_16x16x32_bf16 v[100:103], v[132:135], v[206:209], v[100:103]
	v_mfma_f32_16x16x32_bf16 v[96:99], v[140:143], v[206:209], v[96:99]
	v_mfma_f32_16x16x32_bf16 v[60:63], v[144:147], v[176:179], v[60:63]
	v_mfma_f32_16x16x32_bf16 v[56:59], v[152:155], v[176:179], v[56:59]
	v_mfma_f32_16x16x32_bf16 v[52:55], v[144:147], v[184:187], v[52:55]
	v_mfma_f32_16x16x32_bf16 v[48:51], v[152:155], v[184:187], v[48:51]
	v_mfma_f32_16x16x32_bf16 v[44:47], v[144:147], v[194:197], v[44:47]
	v_mfma_f32_16x16x32_bf16 v[40:43], v[152:155], v[194:197], v[40:43]
	v_mfma_f32_16x16x32_bf16 v[36:39], v[144:147], v[202:205], v[36:39]
	v_mfma_f32_16x16x32_bf16 v[32:35], v[152:155], v[202:205], v[32:35]
	v_mfma_f32_16x16x32_bf16 v[60:63], v[148:151], v[180:183], v[60:63]
	v_mfma_f32_16x16x32_bf16 v[56:59], v[156:159], v[180:183], v[56:59]
	v_mfma_f32_16x16x32_bf16 v[52:55], v[148:151], v[188:191], v[52:55]
	v_mfma_f32_16x16x32_bf16 v[48:51], v[156:159], v[188:191], v[48:51]
	v_mfma_f32_16x16x32_bf16 v[44:47], v[148:151], v[198:201], v[44:47]
	v_mfma_f32_16x16x32_bf16 v[40:43], v[156:159], v[198:201], v[40:43]
	v_mfma_f32_16x16x32_bf16 v[36:39], v[148:151], v[206:209], v[36:39]
	v_mfma_f32_16x16x32_bf16 v[32:35], v[156:159], v[206:209], v[32:35]
	s_barrier
	s_add_i32 s53, s39, s9
	v_lshl_add_u64 v[210:211], s[42:43], 0, v[162:163]
	s_mov_b32 m0, s53
	ds_read_b128 v[176:179], v217 offset:16384
	ds_read_b128 v[180:183], v217 offset:17408
	ds_read_b128 v[184:187], v217 offset:18432
	ds_read_b128 v[188:191], v217 offset:19456
	ds_read_b128 v[194:197], v217 offset:20480
	ds_read_b128 v[198:201], v217 offset:21504
	ds_read_b128 v[202:205], v217 offset:22528
	ds_read_b128 v[206:209], v217 offset:23552
	global_load_lds_dwordx4 v[210:211], off
	s_add_i32 m0, s53, 0x2000
	s_add_u32 s54, s42, 0x40000
	v_lshl_add_u64 v[218:219], s[42:43], 0, v[166:167]
	s_addc_u32 s55, s43, 0
	s_add_i32 s53, s46, s9
	global_load_lds_dwordx4 v[218:219], off
	v_lshl_add_u64 v[220:221], s[54:55], 0, v[162:163]
	s_mov_b32 m0, s53
	v_lshl_add_u64 v[222:223], s[44:45], 0, v[164:165]
	global_load_lds_dwordx4 v[220:221], off
	v_lshl_add_u64 v[220:221], s[54:55], 0, v[166:167]
	s_add_i32 m0, s53, 0x2000
	s_nop 0
	global_load_lds_dwordx4 v[220:221], off
	v_lshl_add_u64 v[220:221], s[44:45], 0, v[160:161]
	s_mov_b32 m0, s11
	s_nop 0
	global_load_lds_dwordx4 v[220:221], off
	s_mov_b32 m0, s14
	s_nop 0
	global_load_lds_dwordx4 v[222:223], off
	s_waitcnt vmcnt(8)
	s_waitcnt lgkmcnt(0)
	s_barrier
; #define PG8_STAGE(bufoff, gbase, voff) do { _Pragma("unroll") for (int _i = 0; _i < 2; ++_i) \
;         __builtin_amdgcn_global_load_lds((const unsigned*)((const char*)(gbase) + (voff)[_i]), (LAS unsigned*)(lds + (bufoff) + ldsw + _i * 8192), 16, 0, 0); } while (0)
; #define PG8_LDA(dst, b, h) do { _Pragma("unroll") for (int m = 0; m < 4; ++m) _Pragma("unroll") for (int k = 0; k < 2; ++k) dst[m][k] = *(const LAS bf16x8*)(lds + PG8_SA(b, h) + aoff + m * 2048 + k * 1024); } while (0)
; #define PG8_LDB(dst, b, h) do { _Pragma("unroll") for (int n = 0; n < 2; ++n) _Pragma("unroll") for (int k = 0; k < 2; ++k) dst[n][k] = *(const LAS bf16x8*)(lds + PG8_SB(b, h) + boff + n * 2048 + k * 1024); } while (0)
; #define PG8_MMA(ai, bj, At, Bt) do { __builtin_amdgcn_s_setprio(1); _Pragma("unroll") for (int m = 0; m < 4; ++m) _Pragma("unroll") for (int n = 0; n < 2; ++n) _Pragma("unroll") for (int k = 0; k < 2; ++k) \
;         acc[ai][bj][m][n] = __builtin_amdgcn_mfma_f32_16x16x32_bf16(Bt[n][k], At[m][k], acc[ai][bj][m][n], 0, 0, 0); __builtin_amdgcn_s_setprio(0); } while (0)
; #define PG8_WAIT_V(n) asm volatile("s_waitcnt vmcnt(" #n ")" ::: "memory")
; #define PG8_WAIT_L(n) asm volatile("s_waitcnt lgkmcnt(" #n ")" ::: "memory")
; #define PG8_BAR __builtin_amdgcn_s_barrier()
; #define PG8_SCHED __builtin_amdgcn_sched_barrier(0)
; template <class Epi, class Sched, bool ALIGN_EPI = false, bool SP2 = false>
; __device__ __forceinline__ void gemm_phase(LAS unsigned char* lds, const Gemm g, const Sched S, const Epi E) {
;     ...
;             PG8_WAIT_V(8); PG8_WAIT_L(0); PG8_BAR; PG8_MMA(1, 0, At, B0); PG8_MMA(1, 1, At, B1); PG8_BAR; PG8_SCHED;
;             PG8_LDB(B0, 1, 0); PG8_LDB(B1, 1, 1); PG8_SCHED; PG8_LDA(At, 1, 0); PG8_STAGE(PG8_SA(0, 1), a2 + hstep, voffA);
;             PG8_WAIT_V(8); PG8_WAIT_L(0); PG8_BAR; PG8_MMA(0, 0, At, B0); PG8_MMA(0, 1, At, B1); PG8_BAR; PG8_SCHED;
	s_waitcnt lgkmcnt(0)
	v_mfma_f32_16x16x32_bf16 v[92:95], v[128:131], v[176:179], v[92:95]
	v_mfma_f32_16x16x32_bf16 v[88:91], v[136:139], v[176:179], v[88:91]
	v_mfma_f32_16x16x32_bf16 v[84:87], v[128:131], v[184:187], v[84:87]
	v_mfma_f32_16x16x32_bf16 v[80:83], v[136:139], v[184:187], v[80:83]
	v_mfma_f32_16x16x32_bf16 v[76:79], v[128:131], v[194:197], v[76:79]
	v_mfma_f32_16x16x32_bf16 v[72:75], v[136:139], v[194:197], v[72:75]
	v_mfma_f32_16x16x32_bf16 v[68:71], v[128:131], v[202:205], v[68:71]
	v_mfma_f32_16x16x32_bf16 v[64:67], v[136:139], v[202:205], v[64:67]
	v_mfma_f32_16x16x32_bf16 v[92:95], v[132:135], v[180:183], v[92:95]
	v_mfma_f32_16x16x32_bf16 v[88:91], v[140:143], v[180:183], v[88:91]
	v_mfma_f32_16x16x32_bf16 v[84:87], v[132:135], v[188:191], v[84:87]
	v_mfma_f32_16x16x32_bf16 v[80:83], v[140:143], v[188:191], v[80:83]
	v_mfma_f32_16x16x32_bf16 v[76:79], v[132:135], v[198:201], v[76:79]
	v_mfma_f32_16x16x32_bf16 v[72:75], v[140:143], v[198:201], v[72:75]
	v_mfma_f32_16x16x32_bf16 v[68:71], v[132:135], v[206:209], v[68:71]
	v_mfma_f32_16x16x32_bf16 v[64:67], v[140:143], v[206:209], v[64:67]
	v_mfma_f32_16x16x32_bf16 v[28:31], v[144:147], v[176:179], v[28:31]
	v_mfma_f32_16x16x32_bf16 v[24:27], v[152:155], v[176:179], v[24:27]
	v_mfma_f32_16x16x32_bf16 v[20:23], v[144:147], v[184:187], v[20:23]
	v_mfma_f32_16x16x32_bf16 v[16:19], v[152:155], v[184:187], v[16:19]
	v_mfma_f32_16x16x32_bf16 v[12:15], v[144:147], v[194:197], v[12:15]
	v_mfma_f32_16x16x32_bf16 v[8:11], v[152:155], v[194:197], v[8:11]
	v_mfma_f32_16x16x32_bf16 v[4:7], v[144:147], v[202:205], v[4:7]
	v_mfma_f32_16x16x32_bf16 v[0:3], v[152:155], v[202:205], v[0:3]
	v_mfma_f32_16x16x32_bf16 v[28:31], v[148:151], v[180:183], v[28:31]
	v_mfma_f32_16x16x32_bf16 v[24:27], v[156:159], v[180:183], v[24:27]
	v_mfma_f32_16x16x32_bf16 v[20:23], v[148:151], v[188:191], v[20:23]
	v_mfma_f32_16x16x32_bf16 v[16:19], v[156:159], v[188:191], v[16:19]
	v_mfma_f32_16x16x32_bf16 v[12:15], v[148:151], v[198:201], v[12:15]
	v_mfma_f32_16x16x32_bf16 v[8:11], v[156:159], v[198:201], v[8:11]
	v_mfma_f32_16x16x32_bf16 v[4:7], v[148:151], v[206:209], v[4:7]
	v_mfma_f32_16x16x32_bf16 v[0:3], v[156:159], v[206:209], v[0:3]
	s_barrier
	s_add_i32 s53, 0, 0x18000
	s_add_i32 s54, 0, 0x1c000
	v_add_u32_e32 v140, s53, v213
	v_add_u32_e32 v156, s54, v213
	ds_read_b128 v[128:131], v140
	ds_read_b128 v[132:135], v140 offset:1024
	ds_read_b128 v[136:139], v140 offset:2048
	ds_read_b128 v[140:143], v140 offset:3072
	ds_read_b128 v[144:147], v156
	ds_read_b128 v[148:151], v156 offset:1024
	ds_read_b128 v[152:155], v156 offset:2048
	ds_read_b128 v[156:159], v156 offset:3072
	s_add_u32 s44, s44, 0x40000
	s_addc_u32 s45, s45, 0
	s_mov_b32 m0, s15
	v_lshl_add_u64 v[224:225], s[44:45], 0, v[160:161]
	ds_read_b128 v[176:179], v217 offset:32768
	ds_read_b128 v[180:183], v217 offset:33792
	ds_read_b128 v[184:187], v217 offset:34816
	ds_read_b128 v[188:191], v217 offset:35840
	ds_read_b128 v[194:197], v217 offset:36864
	ds_read_b128 v[198:201], v217 offset:37888
	ds_read_b128 v[202:205], v217 offset:38912
	ds_read_b128 v[206:209], v217 offset:39936
	global_load_lds_dwordx4 v[224:225], off
	v_lshl_add_u64 v[224:225], s[44:45], 0, v[164:165]
	s_mov_b32 m0, s28
	s_nop 0
	global_load_lds_dwordx4 v[224:225], off
	s_waitcnt vmcnt(8)
	s_waitcnt lgkmcnt(0)
	s_barrier
	s_waitcnt lgkmcnt(0)
	v_mfma_f32_16x16x32_bf16 v[124:127], v[128:131], v[176:179], v[124:127]
	v_mfma_f32_16x16x32_bf16 v[120:123], v[136:139], v[176:179], v[120:123]
	v_mfma_f32_16x16x32_bf16 v[116:119], v[128:131], v[184:187], v[116:119]
	v_mfma_f32_16x16x32_bf16 v[112:115], v[136:139], v[184:187], v[112:115]
	v_mfma_f32_16x16x32_bf16 v[108:111], v[128:131], v[194:197], v[108:111]
	v_mfma_f32_16x16x32_bf16 v[104:107], v[136:139], v[194:197], v[104:107]
	v_mfma_f32_16x16x32_bf16 v[100:103], v[128:131], v[202:205], v[100:103]
	v_mfma_f32_16x16x32_bf16 v[96:99], v[136:139], v[202:205], v[96:99]
	v_mfma_f32_16x16x32_bf16 v[124:127], v[132:135], v[180:183], v[124:127]
	v_mfma_f32_16x16x32_bf16 v[120:123], v[140:143], v[180:183], v[120:123]
	v_mfma_f32_16x16x32_bf16 v[116:119], v[132:135], v[188:191], v[116:119]
	v_mfma_f32_16x16x32_bf16 v[112:115], v[140:143], v[188:191], v[112:115]
	v_mfma_f32_16x16x32_bf16 v[108:111], v[132:135], v[198:201], v[108:111]
	v_mfma_f32_16x16x32_bf16 v[104:107], v[140:143], v[198:201], v[104:107]
	v_mfma_f32_16x16x32_bf16 v[100:103], v[132:135], v[206:209], v[100:103]
	v_mfma_f32_16x16x32_bf16 v[96:99], v[140:143], v[206:209], v[96:99]
	v_mfma_f32_16x16x32_bf16 v[60:63], v[144:147], v[176:179], v[60:63]
	v_mfma_f32_16x16x32_bf16 v[56:59], v[152:155], v[176:179], v[56:59]
	v_mfma_f32_16x16x32_bf16 v[52:55], v[144:147], v[184:187], v[52:55]
	v_mfma_f32_16x16x32_bf16 v[48:51], v[152:155], v[184:187], v[48:51]
	v_mfma_f32_16x16x32_bf16 v[44:47], v[144:147], v[194:197], v[44:47]
	v_mfma_f32_16x16x32_bf16 v[40:43], v[152:155], v[194:197], v[40:43]
	v_mfma_f32_16x16x32_bf16 v[36:39], v[144:147], v[202:205], v[36:39]
	v_mfma_f32_16x16x32_bf16 v[32:35], v[152:155], v[202:205], v[32:35]
	v_mfma_f32_16x16x32_bf16 v[60:63], v[148:151], v[180:183], v[60:63]
	v_mfma_f32_16x16x32_bf16 v[56:59], v[156:159], v[180:183], v[56:59]
	v_mfma_f32_16x16x32_bf16 v[52:55], v[148:151], v[188:191], v[52:55]
	v_mfma_f32_16x16x32_bf16 v[48:51], v[156:159], v[188:191], v[48:51]
	v_mfma_f32_16x16x32_bf16 v[44:47], v[148:151], v[198:201], v[44:47]
	v_mfma_f32_16x16x32_bf16 v[40:43], v[156:159], v[198:201], v[40:43]
	v_mfma_f32_16x16x32_bf16 v[36:39], v[148:151], v[206:209], v[36:39]
	v_mfma_f32_16x16x32_bf16 v[32:35], v[156:159], v[206:209], v[32:35]
	s_barrier
; #define PG8_STAGE(bufoff, gbase, voff) do { _Pragma("unroll") for (int _i = 0; _i < 2; ++_i) \
;         __builtin_amdgcn_global_load_lds((const unsigned*)((const char*)(gbase) + (voff)[_i]), (LAS unsigned*)(lds + (bufoff) + ldsw + _i * 8192), 16, 0, 0); } while (0)
; #define PG8_LDA(dst, b, h) do { _Pragma("unroll") for (int m = 0; m < 4; ++m) _Pragma("unroll") for (int k = 0; k < 2; ++k) dst[m][k] = *(const LAS bf16x8*)(lds + PG8_SA(b, h) + aoff + m * 2048 + k * 1024); } while (0)
; #define PG8_MMA(ai, bj, At, Bt) do { __builtin_amdgcn_s_setprio(1); _Pragma("unroll") for (int m = 0; m < 4; ++m) _Pragma("unroll") for (int n = 0; n < 2; ++n) _Pragma("unroll") for (int k = 0; k < 2; ++k) \
;         acc[ai][bj][m][n] = __builtin_amdgcn_mfma_f32_16x16x32_bf16(Bt[n][k], At[m][k], acc[ai][bj][m][n], 0, 0, 0); __builtin_amdgcn_s_setprio(0); } while (0)
; #define PG8_WAIT_V(n) asm volatile("s_waitcnt vmcnt(" #n ")" ::: "memory")
; #define PG8_WAIT_L(n) asm volatile("s_waitcnt lgkmcnt(" #n ")" ::: "memory")
; #define PG8_BAR __builtin_amdgcn_s_barrier()
; #define PG8_SCHED __builtin_amdgcn_sched_barrier(0)
; template <class Epi, class Sched, bool ALIGN_EPI = false, bool SP2 = false>
; __device__ __forceinline__ void gemm_phase(LAS unsigned char* lds, const Gemm g, const Sched S, const Epi E) {
;     ...
;             PG8_LDA(At, 1, 1); PG8_STAGE(PG8_SB(1, 0), b3, voffB); PG8_STAGE(PG8_SB(1, 1), b3 + hstep, voffB); PG8_STAGE(PG8_SA(1, 0), a3, voffA);
;             PG8_WAIT_V(8); PG8_WAIT_L(0); PG8_BAR; PG8_MMA(1, 0, At, B0); PG8_MMA(1, 1, At, B1); PG8_BAR; PG8_SCHED;
;     ...
;         if constexpr (ALIGN_EPI) { if (wr == 0) PG8_BAR; }
	s_add_i32 s44, s53, s9
	v_lshl_add_u64 v[210:211], v[210:211], 0, s[20:21]
	s_mov_b32 m0, s44
	ds_read_b128 v[176:179], v217 offset:49152
	ds_read_b128 v[180:183], v217 offset:50176
	ds_read_b128 v[184:187], v217 offset:51200
	ds_read_b128 v[188:191], v217 offset:52224
	ds_read_b128 v[194:197], v217 offset:53248
	ds_read_b128 v[198:201], v217 offset:54272
	ds_read_b128 v[202:205], v217 offset:55296
	ds_read_b128 v[206:209], v217 offset:56320
	global_load_lds_dwordx4 v[210:211], off
	s_add_i32 m0, s44, 0x2000
	s_add_u32 s42, s42, 0x40080
	v_lshl_add_u64 v[210:211], v[218:219], 0, s[20:21]
	s_addc_u32 s43, s43, 0
	s_add_i32 s44, s54, s9
	global_load_lds_dwordx4 v[210:211], off
	v_lshl_add_u64 v[210:211], s[42:43], 0, v[162:163]
	s_mov_b32 m0, s44
	s_nop 0
	global_load_lds_dwordx4 v[210:211], off
	v_lshl_add_u64 v[210:211], s[42:43], 0, v[166:167]
	s_add_i32 m0, s44, 0x2000
	s_nop 0
	global_load_lds_dwordx4 v[210:211], off
	v_lshl_add_u64 v[210:211], v[220:221], 0, s[20:21]
	s_mov_b32 m0, s30
	s_nop 0
	global_load_lds_dwordx4 v[210:211], off
	v_lshl_add_u64 v[210:211], v[222:223], 0, s[20:21]
	s_mov_b32 m0, s31
	s_nop 0
	global_load_lds_dwordx4 v[210:211], off
	s_waitcnt vmcnt(8)
	s_waitcnt lgkmcnt(0)
	s_barrier
	s_waitcnt lgkmcnt(0)
	v_mfma_f32_16x16x32_bf16 v[92:95], v[128:131], v[176:179], v[92:95]
	v_mfma_f32_16x16x32_bf16 v[88:91], v[136:139], v[176:179], v[88:91]
	v_mfma_f32_16x16x32_bf16 v[84:87], v[128:131], v[184:187], v[84:87]
	v_mfma_f32_16x16x32_bf16 v[80:83], v[136:139], v[184:187], v[80:83]
	v_mfma_f32_16x16x32_bf16 v[76:79], v[128:131], v[194:197], v[76:79]
	v_mfma_f32_16x16x32_bf16 v[72:75], v[136:139], v[194:197], v[72:75]
	v_mfma_f32_16x16x32_bf16 v[68:71], v[128:131], v[202:205], v[68:71]
	v_mfma_f32_16x16x32_bf16 v[64:67], v[136:139], v[202:205], v[64:67]
	v_mfma_f32_16x16x32_bf16 v[92:95], v[132:135], v[180:183], v[92:95]
	v_mfma_f32_16x16x32_bf16 v[88:91], v[140:143], v[180:183], v[88:91]
	v_mfma_f32_16x16x32_bf16 v[84:87], v[132:135], v[188:191], v[84:87]
	v_mfma_f32_16x16x32_bf16 v[80:83], v[140:143], v[188:191], v[80:83]
	v_mfma_f32_16x16x32_bf16 v[76:79], v[132:135], v[198:201], v[76:79]
	v_mfma_f32_16x16x32_bf16 v[72:75], v[140:143], v[198:201], v[72:75]
	v_mfma_f32_16x16x32_bf16 v[68:71], v[132:135], v[206:209], v[68:71]
	v_mfma_f32_16x16x32_bf16 v[64:67], v[140:143], v[206:209], v[64:67]
	v_mfma_f32_16x16x32_bf16 v[28:31], v[144:147], v[176:179], v[28:31]
	v_mfma_f32_16x16x32_bf16 v[24:27], v[152:155], v[176:179], v[24:27]
	v_mfma_f32_16x16x32_bf16 v[20:23], v[144:147], v[184:187], v[20:23]
	v_mfma_f32_16x16x32_bf16 v[16:19], v[152:155], v[184:187], v[16:19]
	v_mfma_f32_16x16x32_bf16 v[12:15], v[144:147], v[194:197], v[12:15]
	v_mfma_f32_16x16x32_bf16 v[8:11], v[152:155], v[194:197], v[8:11]
	v_mfma_f32_16x16x32_bf16 v[4:7], v[144:147], v[202:205], v[4:7]
	v_mfma_f32_16x16x32_bf16 v[0:3], v[152:155], v[202:205], v[0:3]
	v_mfma_f32_16x16x32_bf16 v[28:31], v[148:151], v[180:183], v[28:31]
	v_mfma_f32_16x16x32_bf16 v[24:27], v[156:159], v[180:183], v[24:27]
	v_mfma_f32_16x16x32_bf16 v[20:23], v[148:151], v[188:191], v[20:23]
	v_mfma_f32_16x16x32_bf16 v[16:19], v[156:159], v[188:191], v[16:19]
	v_mfma_f32_16x16x32_bf16 v[12:15], v[148:151], v[198:201], v[12:15]
	v_mfma_f32_16x16x32_bf16 v[8:11], v[156:159], v[198:201], v[8:11]
	v_mfma_f32_16x16x32_bf16 v[4:7], v[148:151], v[206:209], v[4:7]
	v_mfma_f32_16x16x32_bf16 v[0:3], v[156:159], v[206:209], v[0:3]
	s_barrier
	s_add_i32 s52, s52, 2
	s_add_u32 s40, s40, 0x100
	s_addc_u32 s41, s41, 0
	s_add_u32 s50, s50, 0x100
	s_addc_u32 s51, s51, 0
	s_cmp_gt_u32 s52, 13
	s_cbranch_scc0 .LBB0_478
	s_and_b64 vcc, exec, s[22:23]
	s_cbranch_vccz .LBB0_481
	s_barrier

; #define PG8_STAGE(bufoff, gbase, voff) do { _Pragma("unroll") for (int _i = 0; _i < 2; ++_i) \
;         __builtin_amdgcn_global_load_lds((const unsigned*)((const char*)(gbase) + (voff)[_i]), (LAS unsigned*)(lds + (bufoff) + ldsw + _i * 8192), 16, 0, 0); } while (0)
; #define PG8_LDA(dst, b, h) do { _Pragma("unroll") for (int m = 0; m < 4; ++m) _Pragma("unroll") for (int k = 0; k < 2; ++k) dst[m][k] = *(const LAS bf16x8*)(lds + PG8_SA(b, h) + aoff + m * 2048 + k * 1024); } while (0)
; #define PG8_LDB(dst, b, h) do { _Pragma("unroll") for (int n = 0; n < 2; ++n) _Pragma("unroll") for (int k = 0; k < 2; ++k) dst[n][k] = *(const LAS bf16x8*)(lds + PG8_SB(b, h) + boff + n * 2048 + k * 1024); } while (0)
; #define PG8_WAIT_V(n) asm volatile("s_waitcnt vmcnt(" #n ")" ::: "memory")
; #define PG8_WAIT_L(n) asm volatile("s_waitcnt lgkmcnt(" #n ")" ::: "memory")
; #define PG8_BAR __builtin_amdgcn_s_barrier()
; #define PG8_SCHED __builtin_amdgcn_sched_barrier(0)
; template <class Epi, class Sched, bool ALIGN_EPI = false, bool SP2 = false>
; __device__ __forceinline__ void gemm_phase(LAS unsigned char* lds, const Gemm g, const Sched S, const Epi E) {
;     ...
;         const char* nA = has_next ? (const char*)g.A + (size_t)nxt.pm * tstep : cA; const char* nB = has_next ? (const char*)g.Bt + (size_t)nxt.pn * tstep : cB;
;         for (int t = 0; t < nt; t += 2) {
;             const bool last = (t == nt - 2);
;             const char* a1 = cA + (size_t)(t + 1) * kstep;
;             const char* a2 = last ? nA : cA + (size_t)(t + 2) * kstep; const char* b2 = last ? nB : cB + (size_t)(t + 2) * kstep;
;             const char* a3 = a2 + kstep; const char* b3 = b2 + kstep;
;             if (last && has_next) S.a_ready(nxt);
;             if (last) E.prefetch(cur, wr, fr, pre);
;             if constexpr (SP2) {
;             PG8_LDB(B0, 0, 0); PG8_LDB(B1, 0, 1); PG8_SCHED; PG8_LDA(At, 0, 0); PG8_STAGE(PG8_SA(1, 1), a1 + hstep, voffA);
;             PG8_WAIT_V(8); PG8_WAIT_L(0); PG8_BAR; PG8_MMA(0, 0, At, B0); PG8_MMA(0, 1, At, B1); PG8_BAR; PG8_SCHED;
;             PG8_LDA(At, 0, 1); PG8_STAGE(PG8_SB(0, 0), b2, voffB); PG8_STAGE(PG8_SB(0, 1), b2 + hstep, voffB); PG8_STAGE(PG8_SA(0, 0), a2, voffA);
;             PG8_WAIT_V(8); PG8_WAIT_L(0); PG8_BAR; PG8_MMA(1, 0, At, B0); PG8_MMA(1, 1, At, B1); PG8_BAR; PG8_SCHED;
.LBB0_559:
	ds_read_b128 v[140:143], v183
	ds_read_b128 v[144:147], v183 offset:1024
	ds_read_b128 v[148:151], v183 offset:2048
	ds_read_b128 v[152:155], v183 offset:3072
	ds_read_b128 v[156:159], v184
	ds_read_b128 v[160:163], v184 offset:1024
	ds_read_b128 v[164:167], v184 offset:2048
	ds_read_b128 v[168:171], v184 offset:3072
	s_add_u32 s44, s42, 0xfff80080
	s_addc_u32 s45, s43, -1
	s_cmp_eq_u32 s54, 28
	s_cselect_b32 s47, s27, s45
	s_cselect_b32 s46, s39, s44
	s_cselect_b32 s45, s25, s53
	s_cselect_b32 s44, s51, s52
	v_lshl_add_u64 v[214:215], s[42:43], 0, v[132:133]
	s_add_i32 m0, s9, 0xc000
	ds_read_b128 v[172:175], v185
	ds_read_b128 v[176:179], v185 offset:1024
	ds_read_b128 v[188:191], v185 offset:2048
	ds_read_b128 v[194:197], v185 offset:3072
	ds_read_b128 v[198:201], v185 offset:4096
	ds_read_b128 v[202:205], v185 offset:5120
	ds_read_b128 v[206:209], v185 offset:6144
	ds_read_b128 v[210:213], v185 offset:7168
	global_load_lds_dwordx4 v[214:215], off
	v_lshl_add_u64 v[214:215], s[42:43], 0, v[134:135]
	s_add_i32 m0, s9, 0xe000
	s_nop 0
	global_load_lds_dwordx4 v[214:215], off
	s_waitcnt vmcnt(8)
	s_waitcnt lgkmcnt(0)
	s_barrier
	s_waitcnt lgkmcnt(0)
	v_mfma_f32_16x16x32_bf16 v[124:127], v[140:143], v[172:175], v[124:127]
	v_mfma_f32_16x16x32_bf16 v[120:123], v[148:151], v[172:175], v[120:123]
	v_mfma_f32_16x16x32_bf16 v[108:111], v[140:143], v[188:191], v[108:111]
	v_mfma_f32_16x16x32_bf16 v[104:107], v[148:151], v[188:191], v[104:107]
	v_mfma_f32_16x16x32_bf16 v[92:95], v[140:143], v[198:201], v[92:95]
	v_mfma_f32_16x16x32_bf16 v[88:91], v[148:151], v[198:201], v[88:91]
	v_mfma_f32_16x16x32_bf16 v[76:79], v[140:143], v[206:209], v[76:79]
	v_mfma_f32_16x16x32_bf16 v[72:75], v[148:151], v[206:209], v[72:75]
	v_mfma_f32_16x16x32_bf16 v[124:127], v[144:147], v[176:179], v[124:127]
	v_mfma_f32_16x16x32_bf16 v[120:123], v[152:155], v[176:179], v[120:123]
	v_mfma_f32_16x16x32_bf16 v[108:111], v[144:147], v[194:197], v[108:111]
	v_mfma_f32_16x16x32_bf16 v[104:107], v[152:155], v[194:197], v[104:107]
	v_mfma_f32_16x16x32_bf16 v[92:95], v[144:147], v[202:205], v[92:95]
	v_mfma_f32_16x16x32_bf16 v[88:91], v[152:155], v[202:205], v[88:91]
	v_mfma_f32_16x16x32_bf16 v[76:79], v[144:147], v[210:213], v[76:79]
	v_mfma_f32_16x16x32_bf16 v[72:75], v[152:155], v[210:213], v[72:75]
	v_mfma_f32_16x16x32_bf16 v[116:119], v[156:159], v[172:175], v[116:119]
	v_mfma_f32_16x16x32_bf16 v[112:115], v[164:167], v[172:175], v[112:115]
	v_mfma_f32_16x16x32_bf16 v[100:103], v[156:159], v[188:191], v[100:103]
	v_mfma_f32_16x16x32_bf16 v[96:99], v[164:167], v[188:191], v[96:99]
	v_mfma_f32_16x16x32_bf16 v[84:87], v[156:159], v[198:201], v[84:87]
	v_mfma_f32_16x16x32_bf16 v[80:83], v[164:167], v[198:201], v[80:83]
	v_mfma_f32_16x16x32_bf16 v[68:71], v[156:159], v[206:209], v[68:71]
	v_mfma_f32_16x16x32_bf16 v[64:67], v[164:167], v[206:209], v[64:67]
	v_mfma_f32_16x16x32_bf16 v[116:119], v[160:163], v[176:179], v[116:119]
	v_mfma_f32_16x16x32_bf16 v[112:115], v[168:171], v[176:179], v[112:115]
	v_mfma_f32_16x16x32_bf16 v[100:103], v[160:163], v[194:197], v[100:103]
	v_mfma_f32_16x16x32_bf16 v[96:99], v[168:171], v[194:197], v[96:99]
	v_mfma_f32_16x16x32_bf16 v[84:87], v[160:163], v[202:205], v[84:87]
	v_mfma_f32_16x16x32_bf16 v[80:83], v[168:171], v[202:205], v[80:83]
	v_mfma_f32_16x16x32_bf16 v[68:71], v[160:163], v[210:213], v[68:71]
	v_mfma_f32_16x16x32_bf16 v[64:67], v[168:171], v[210:213], v[64:67]
	s_barrier
	s_add_i32 s55, s49, s8
	v_lshl_add_u64 v[214:215], s[44:45], 0, v[128:129]
	s_mov_b32 m0, s55
	ds_read_b128 v[172:175], v185 offset:16384
	ds_read_b128 v[176:179], v185 offset:17408
	ds_read_b128 v[188:191], v185 offset:18432
	ds_read_b128 v[194:197], v185 offset:19456
	ds_read_b128 v[198:201], v185 offset:20480
	ds_read_b128 v[202:205], v185 offset:21504
	ds_read_b128 v[206:209], v185 offset:22528
	ds_read_b128 v[210:213], v185 offset:23552
	global_load_lds_dwordx4 v[214:215], off
	s_add_i32 m0, s55, 0x2000
	s_add_u32 s56, s44, 0x80000
	v_lshl_add_u64 v[216:217], s[44:45], 0, v[130:131]
	s_addc_u32 s57, s45, 0
	s_add_i32 s55, s50, s8
	global_load_lds_dwordx4 v[216:217], off
	v_lshl_add_u64 v[218:219], s[56:57], 0, v[128:129]
	s_mov_b32 m0, s55
	v_lshl_add_u64 v[220:221], s[46:47], 0, v[130:131]
	global_load_lds_dwordx4 v[218:219], off
	v_lshl_add_u64 v[218:219], s[56:57], 0, v[130:131]
	s_add_i32 m0, s55, 0x2000
	s_nop 0
	global_load_lds_dwordx4 v[218:219], off
	v_lshl_add_u64 v[218:219], s[46:47], 0, v[128:129]
	s_mov_b32 m0, s9
	s_nop 0
	global_load_lds_dwordx4 v[218:219], off
	s_mov_b32 m0, s11
	s_nop 0
	global_load_lds_dwordx4 v[220:221], off
	s_waitcnt vmcnt(8)
	s_waitcnt lgkmcnt(0)
	s_barrier
; #define PG8_STAGE(bufoff, gbase, voff) do { _Pragma("unroll") for (int _i = 0; _i < 2; ++_i) \
;         __builtin_amdgcn_global_load_lds((const unsigned*)((const char*)(gbase) + (voff)[_i]), (LAS unsigned*)(lds + (bufoff) + ldsw + _i * 8192), 16, 0, 0); } while (0)
; #define PG8_LDA(dst, b, h) do { _Pragma("unroll") for (int m = 0; m < 4; ++m) _Pragma("unroll") for (int k = 0; k < 2; ++k) dst[m][k] = *(const LAS bf16x8*)(lds + PG8_SA(b, h) + aoff + m * 2048 + k * 1024); } while (0)
; #define PG8_LDB(dst, b, h) do { _Pragma("unroll") for (int n = 0; n < 2; ++n) _Pragma("unroll") for (int k = 0; k < 2; ++k) dst[n][k] = *(const LAS bf16x8*)(lds + PG8_SB(b, h) + boff + n * 2048 + k * 1024); } while (0)
; #define PG8_MMA(ai, bj, At, Bt) do { __builtin_amdgcn_s_setprio(1); _Pragma("unroll") for (int m = 0; m < 4; ++m) _Pragma("unroll") for (int n = 0; n < 2; ++n) _Pragma("unroll") for (int k = 0; k < 2; ++k) \
;         acc[ai][bj][m][n] = __builtin_amdgcn_mfma_f32_16x16x32_bf16(Bt[n][k], At[m][k], acc[ai][bj][m][n], 0, 0, 0); __builtin_amdgcn_s_setprio(0); } while (0)
; #define PG8_WAIT_V(n) asm volatile("s_waitcnt vmcnt(" #n ")" ::: "memory")
; #define PG8_WAIT_L(n) asm volatile("s_waitcnt lgkmcnt(" #n ")" ::: "memory")
; #define PG8_BAR __builtin_amdgcn_s_barrier()
; #define PG8_SCHED __builtin_amdgcn_sched_barrier(0)
; template <class Epi, class Sched, bool ALIGN_EPI = false, bool SP2 = false>
; __device__ __forceinline__ void gemm_phase(LAS unsigned char* lds, const Gemm g, const Sched S, const Epi E) {
;     ...
;             PG8_WAIT_V(8); PG8_WAIT_L(0); PG8_BAR; PG8_MMA(1, 0, At, B0); PG8_MMA(1, 1, At, B1); PG8_BAR; PG8_SCHED;
;             PG8_LDB(B0, 1, 0); PG8_LDB(B1, 1, 1); PG8_SCHED; PG8_LDA(At, 1, 0); PG8_STAGE(PG8_SA(0, 1), a2 + hstep, voffA);
;             PG8_WAIT_V(8); PG8_WAIT_L(0); PG8_BAR; PG8_MMA(0, 0, At, B0); PG8_MMA(0, 1, At, B1); PG8_BAR; PG8_SCHED;
	s_waitcnt lgkmcnt(0)
	v_mfma_f32_16x16x32_bf16 v[60:63], v[140:143], v[172:175], v[60:63]
	v_mfma_f32_16x16x32_bf16 v[56:59], v[148:151], v[172:175], v[56:59]
	v_mfma_f32_16x16x32_bf16 v[44:47], v[140:143], v[188:191], v[44:47]
	v_mfma_f32_16x16x32_bf16 v[40:43], v[148:151], v[188:191], v[40:43]
	v_mfma_f32_16x16x32_bf16 v[28:31], v[140:143], v[198:201], v[28:31]
	v_mfma_f32_16x16x32_bf16 v[24:27], v[148:151], v[198:201], v[24:27]
	v_mfma_f32_16x16x32_bf16 v[12:15], v[140:143], v[206:209], v[12:15]
	v_mfma_f32_16x16x32_bf16 v[8:11], v[148:151], v[206:209], v[8:11]
	v_mfma_f32_16x16x32_bf16 v[60:63], v[144:147], v[176:179], v[60:63]
	v_mfma_f32_16x16x32_bf16 v[56:59], v[152:155], v[176:179], v[56:59]
	v_mfma_f32_16x16x32_bf16 v[44:47], v[144:147], v[194:197], v[44:47]
	v_mfma_f32_16x16x32_bf16 v[40:43], v[152:155], v[194:197], v[40:43]
	v_mfma_f32_16x16x32_bf16 v[28:31], v[144:147], v[202:205], v[28:31]
	v_mfma_f32_16x16x32_bf16 v[24:27], v[152:155], v[202:205], v[24:27]
	v_mfma_f32_16x16x32_bf16 v[12:15], v[144:147], v[210:213], v[12:15]
	v_mfma_f32_16x16x32_bf16 v[8:11], v[152:155], v[210:213], v[8:11]
	v_mfma_f32_16x16x32_bf16 v[52:55], v[156:159], v[172:175], v[52:55]
	v_mfma_f32_16x16x32_bf16 v[48:51], v[164:167], v[172:175], v[48:51]
	v_mfma_f32_16x16x32_bf16 v[36:39], v[156:159], v[188:191], v[36:39]
	v_mfma_f32_16x16x32_bf16 v[32:35], v[164:167], v[188:191], v[32:35]
	v_mfma_f32_16x16x32_bf16 v[20:23], v[156:159], v[198:201], v[20:23]
	v_mfma_f32_16x16x32_bf16 v[16:19], v[164:167], v[198:201], v[16:19]
	v_mfma_f32_16x16x32_bf16 v[4:7], v[156:159], v[206:209], v[4:7]
	v_mfma_f32_16x16x32_bf16 v[0:3], v[164:167], v[206:209], v[0:3]
	v_mfma_f32_16x16x32_bf16 v[52:55], v[160:163], v[176:179], v[52:55]
	v_mfma_f32_16x16x32_bf16 v[48:51], v[168:171], v[176:179], v[48:51]
	v_mfma_f32_16x16x32_bf16 v[36:39], v[160:163], v[194:197], v[36:39]
	v_mfma_f32_16x16x32_bf16 v[32:35], v[168:171], v[194:197], v[32:35]
	v_mfma_f32_16x16x32_bf16 v[20:23], v[160:163], v[202:205], v[20:23]
	v_mfma_f32_16x16x32_bf16 v[16:19], v[168:171], v[202:205], v[16:19]
	v_mfma_f32_16x16x32_bf16 v[4:7], v[160:163], v[210:213], v[4:7]
	v_mfma_f32_16x16x32_bf16 v[0:3], v[168:171], v[210:213], v[0:3]
	s_barrier
	s_add_i32 s55, 0, 0x18000
	s_add_i32 s56, 0, 0x1c000
	v_add_u32_e32 v152, s55, v181
	v_add_u32_e32 v168, s56, v181
	ds_read_b128 v[140:143], v152
	ds_read_b128 v[144:147], v152 offset:1024
	ds_read_b128 v[148:151], v152 offset:2048
	ds_read_b128 v[152:155], v152 offset:3072
	ds_read_b128 v[156:159], v168
	ds_read_b128 v[160:163], v168 offset:1024
	ds_read_b128 v[164:167], v168 offset:2048
	ds_read_b128 v[168:171], v168 offset:3072
	s_add_u32 s46, s46, 0x80000
	s_addc_u32 s47, s47, 0
	s_mov_b32 m0, s28
	v_lshl_add_u64 v[222:223], s[46:47], 0, v[128:129]
	ds_read_b128 v[172:175], v185 offset:32768
	ds_read_b128 v[176:179], v185 offset:33792
	ds_read_b128 v[188:191], v185 offset:34816
	ds_read_b128 v[194:197], v185 offset:35840
	ds_read_b128 v[198:201], v185 offset:36864
	ds_read_b128 v[202:205], v185 offset:37888
	ds_read_b128 v[206:209], v185 offset:38912
	ds_read_b128 v[210:213], v185 offset:39936
	global_load_lds_dwordx4 v[222:223], off
	v_lshl_add_u64 v[222:223], s[46:47], 0, v[130:131]
	s_mov_b32 m0, s29
	s_nop 0
	global_load_lds_dwordx4 v[222:223], off
	s_waitcnt vmcnt(8)
	s_waitcnt lgkmcnt(0)
	s_barrier
	s_waitcnt lgkmcnt(0)
	v_mfma_f32_16x16x32_bf16 v[124:127], v[140:143], v[172:175], v[124:127]
	v_mfma_f32_16x16x32_bf16 v[120:123], v[148:151], v[172:175], v[120:123]
	v_mfma_f32_16x16x32_bf16 v[108:111], v[140:143], v[188:191], v[108:111]
	v_mfma_f32_16x16x32_bf16 v[104:107], v[148:151], v[188:191], v[104:107]
	v_mfma_f32_16x16x32_bf16 v[92:95], v[140:143], v[198:201], v[92:95]
	v_mfma_f32_16x16x32_bf16 v[88:91], v[148:151], v[198:201], v[88:91]
	v_mfma_f32_16x16x32_bf16 v[76:79], v[140:143], v[206:209], v[76:79]
	v_mfma_f32_16x16x32_bf16 v[72:75], v[148:151], v[206:209], v[72:75]
	v_mfma_f32_16x16x32_bf16 v[124:127], v[144:147], v[176:179], v[124:127]
	v_mfma_f32_16x16x32_bf16 v[120:123], v[152:155], v[176:179], v[120:123]
	v_mfma_f32_16x16x32_bf16 v[108:111], v[144:147], v[194:197], v[108:111]
	v_mfma_f32_16x16x32_bf16 v[104:107], v[152:155], v[194:197], v[104:107]
	v_mfma_f32_16x16x32_bf16 v[92:95], v[144:147], v[202:205], v[92:95]
	v_mfma_f32_16x16x32_bf16 v[88:91], v[152:155], v[202:205], v[88:91]
	v_mfma_f32_16x16x32_bf16 v[76:79], v[144:147], v[210:213], v[76:79]
	v_mfma_f32_16x16x32_bf16 v[72:75], v[152:155], v[210:213], v[72:75]
	v_mfma_f32_16x16x32_bf16 v[116:119], v[156:159], v[172:175], v[116:119]
	v_mfma_f32_16x16x32_bf16 v[112:115], v[164:167], v[172:175], v[112:115]
	v_mfma_f32_16x16x32_bf16 v[100:103], v[156:159], v[188:191], v[100:103]
	v_mfma_f32_16x16x32_bf16 v[96:99], v[164:167], v[188:191], v[96:99]
	v_mfma_f32_16x16x32_bf16 v[84:87], v[156:159], v[198:201], v[84:87]
	v_mfma_f32_16x16x32_bf16 v[80:83], v[164:167], v[198:201], v[80:83]
	v_mfma_f32_16x16x32_bf16 v[68:71], v[156:159], v[206:209], v[68:71]
	v_mfma_f32_16x16x32_bf16 v[64:67], v[164:167], v[206:209], v[64:67]
	v_mfma_f32_16x16x32_bf16 v[116:119], v[160:163], v[176:179], v[116:119]
	v_mfma_f32_16x16x32_bf16 v[112:115], v[168:171], v[176:179], v[112:115]
	v_mfma_f32_16x16x32_bf16 v[100:103], v[160:163], v[194:197], v[100:103]
	v_mfma_f32_16x16x32_bf16 v[96:99], v[168:171], v[194:197], v[96:99]
	v_mfma_f32_16x16x32_bf16 v[84:87], v[160:163], v[202:205], v[84:87]
	v_mfma_f32_16x16x32_bf16 v[80:83], v[168:171], v[202:205], v[80:83]
	v_mfma_f32_16x16x32_bf16 v[68:71], v[160:163], v[210:213], v[68:71]
	v_mfma_f32_16x16x32_bf16 v[64:67], v[168:171], v[210:213], v[64:67]
	s_barrier
; #define PG8_STAGE(bufoff, gbase, voff) do { _Pragma("unroll") for (int _i = 0; _i < 2; ++_i) \
;         __builtin_amdgcn_global_load_lds((const unsigned*)((const char*)(gbase) + (voff)[_i]), (LAS unsigned*)(lds + (bufoff) + ldsw + _i * 8192), 16, 0, 0); } while (0)
; #define PG8_LDA(dst, b, h) do { _Pragma("unroll") for (int m = 0; m < 4; ++m) _Pragma("unroll") for (int k = 0; k < 2; ++k) dst[m][k] = *(const LAS bf16x8*)(lds + PG8_SA(b, h) + aoff + m * 2048 + k * 1024); } while (0)
; #define PG8_MMA(ai, bj, At, Bt) do { __builtin_amdgcn_s_setprio(1); _Pragma("unroll") for (int m = 0; m < 4; ++m) _Pragma("unroll") for (int n = 0; n < 2; ++n) _Pragma("unroll") for (int k = 0; k < 2; ++k) \
;         acc[ai][bj][m][n] = __builtin_amdgcn_mfma_f32_16x16x32_bf16(Bt[n][k], At[m][k], acc[ai][bj][m][n], 0, 0, 0); __builtin_amdgcn_s_setprio(0); } while (0)
; #define PG8_WAIT_V(n) asm volatile("s_waitcnt vmcnt(" #n ")" ::: "memory")
; #define PG8_WAIT_L(n) asm volatile("s_waitcnt lgkmcnt(" #n ")" ::: "memory")
; #define PG8_BAR __builtin_amdgcn_s_barrier()
; #define PG8_SCHED __builtin_amdgcn_sched_barrier(0)
; template <class Epi, class Sched, bool ALIGN_EPI = false, bool SP2 = false>
; __device__ __forceinline__ void gemm_phase(LAS unsigned char* lds, const Gemm g, const Sched S, const Epi E) {
;     ...
;             PG8_LDA(At, 1, 1); PG8_STAGE(PG8_SB(1, 0), b3, voffB); PG8_STAGE(PG8_SB(1, 1), b3 + hstep, voffB); PG8_STAGE(PG8_SA(1, 0), a3, voffA);
;             PG8_WAIT_V(8); PG8_WAIT_L(0); PG8_BAR; PG8_MMA(1, 0, At, B0); PG8_MMA(1, 1, At, B1); PG8_BAR; PG8_SCHED;
;     ...
;         if constexpr (ALIGN_EPI) { if (wr == 0) PG8_BAR; }
	s_add_i32 s46, s55, s8
	v_lshl_add_u64 v[214:215], v[214:215], 0, s[20:21]
	s_mov_b32 m0, s46
	ds_read_b128 v[172:175], v185 offset:49152
	ds_read_b128 v[176:179], v185 offset:50176
	ds_read_b128 v[188:191], v185 offset:51200
	ds_read_b128 v[194:197], v185 offset:52224
	ds_read_b128 v[198:201], v185 offset:53248
	ds_read_b128 v[202:205], v185 offset:54272
	ds_read_b128 v[206:209], v185 offset:55296
	ds_read_b128 v[210:213], v185 offset:56320
	global_load_lds_dwordx4 v[214:215], off
	s_add_i32 m0, s46, 0x2000
	s_add_u32 s44, s44, 0x80080
	v_lshl_add_u64 v[214:215], v[216:217], 0, s[20:21]
	s_addc_u32 s45, s45, 0
	s_add_i32 s46, s56, s8
	global_load_lds_dwordx4 v[214:215], off
	v_lshl_add_u64 v[214:215], s[44:45], 0, v[128:129]
	s_mov_b32 m0, s46
	s_nop 0
	global_load_lds_dwordx4 v[214:215], off
	v_lshl_add_u64 v[214:215], s[44:45], 0, v[130:131]
	s_add_i32 m0, s46, 0x2000
	s_nop 0
	global_load_lds_dwordx4 v[214:215], off
	v_lshl_add_u64 v[214:215], v[218:219], 0, s[20:21]
	s_mov_b32 m0, s33
	s_nop 0
	global_load_lds_dwordx4 v[214:215], off
	v_lshl_add_u64 v[214:215], v[220:221], 0, s[20:21]
	s_mov_b32 m0, s41
	s_nop 0
	global_load_lds_dwordx4 v[214:215], off
	s_waitcnt vmcnt(8)
	s_waitcnt lgkmcnt(0)
	s_barrier
	s_waitcnt lgkmcnt(0)
	v_mfma_f32_16x16x32_bf16 v[60:63], v[140:143], v[172:175], v[60:63]
	v_mfma_f32_16x16x32_bf16 v[56:59], v[148:151], v[172:175], v[56:59]
	v_mfma_f32_16x16x32_bf16 v[44:47], v[140:143], v[188:191], v[44:47]
	v_mfma_f32_16x16x32_bf16 v[40:43], v[148:151], v[188:191], v[40:43]
	v_mfma_f32_16x16x32_bf16 v[28:31], v[140:143], v[198:201], v[28:31]
	v_mfma_f32_16x16x32_bf16 v[24:27], v[148:151], v[198:201], v[24:27]
	v_mfma_f32_16x16x32_bf16 v[12:15], v[140:143], v[206:209], v[12:15]
	v_mfma_f32_16x16x32_bf16 v[8:11], v[148:151], v[206:209], v[8:11]
	v_mfma_f32_16x16x32_bf16 v[60:63], v[144:147], v[176:179], v[60:63]
	v_mfma_f32_16x16x32_bf16 v[56:59], v[152:155], v[176:179], v[56:59]
	v_mfma_f32_16x16x32_bf16 v[44:47], v[144:147], v[194:197], v[44:47]
	v_mfma_f32_16x16x32_bf16 v[40:43], v[152:155], v[194:197], v[40:43]
	v_mfma_f32_16x16x32_bf16 v[28:31], v[144:147], v[202:205], v[28:31]
	v_mfma_f32_16x16x32_bf16 v[24:27], v[152:155], v[202:205], v[24:27]
	v_mfma_f32_16x16x32_bf16 v[12:15], v[144:147], v[210:213], v[12:15]
	v_mfma_f32_16x16x32_bf16 v[8:11], v[152:155], v[210:213], v[8:11]
	v_mfma_f32_16x16x32_bf16 v[52:55], v[156:159], v[172:175], v[52:55]
	v_mfma_f32_16x16x32_bf16 v[48:51], v[164:167], v[172:175], v[48:51]
	v_mfma_f32_16x16x32_bf16 v[36:39], v[156:159], v[188:191], v[36:39]
	v_mfma_f32_16x16x32_bf16 v[32:35], v[164:167], v[188:191], v[32:35]
	v_mfma_f32_16x16x32_bf16 v[20:23], v[156:159], v[198:201], v[20:23]
	v_mfma_f32_16x16x32_bf16 v[16:19], v[164:167], v[198:201], v[16:19]
	v_mfma_f32_16x16x32_bf16 v[4:7], v[156:159], v[206:209], v[4:7]
	v_mfma_f32_16x16x32_bf16 v[0:3], v[164:167], v[206:209], v[0:3]
	v_mfma_f32_16x16x32_bf16 v[52:55], v[160:163], v[176:179], v[52:55]
	v_mfma_f32_16x16x32_bf16 v[48:51], v[168:171], v[176:179], v[48:51]
	v_mfma_f32_16x16x32_bf16 v[36:39], v[160:163], v[194:197], v[36:39]
	v_mfma_f32_16x16x32_bf16 v[32:35], v[168:171], v[194:197], v[32:35]
	v_mfma_f32_16x16x32_bf16 v[20:23], v[160:163], v[202:205], v[20:23]
	v_mfma_f32_16x16x32_bf16 v[16:19], v[168:171], v[202:205], v[16:19]
	v_mfma_f32_16x16x32_bf16 v[4:7], v[160:163], v[210:213], v[4:7]
	v_mfma_f32_16x16x32_bf16 v[0:3], v[168:171], v[210:213], v[0:3]
	s_barrier
	s_add_i32 s54, s54, 2
	s_add_u32 s42, s42, 0x100
	s_addc_u32 s43, s43, 0
	s_add_u32 s52, s52, 0x100
	s_addc_u32 s53, s53, 0
	s_cmp_gt_u32 s54, 29
	s_cbranch_scc0 .LBB0_559
	s_and_b64 vcc, exec, s[22:23]
	s_cbranch_vccz .LBB0_562
	s_barrier

; #define PG8_STAGE(bufoff, gbase, voff) do { _Pragma("unroll") for (int _i = 0; _i < 2; ++_i) \
;         __builtin_amdgcn_global_load_lds((const unsigned*)((const char*)(gbase) + (voff)[_i]), (LAS unsigned*)(lds + (bufoff) + ldsw + _i * 8192), 16, 0, 0); } while (0)
; #define PG8_LDA(dst, b, h) do { _Pragma("unroll") for (int m = 0; m < 4; ++m) _Pragma("unroll") for (int k = 0; k < 2; ++k) dst[m][k] = *(const LAS bf16x8*)(lds + PG8_SA(b, h) + aoff + m * 2048 + k * 1024); } while (0)
; #define PG8_LDB(dst, b, h) do { _Pragma("unroll") for (int n = 0; n < 2; ++n) _Pragma("unroll") for (int k = 0; k < 2; ++k) dst[n][k] = *(const LAS bf16x8*)(lds + PG8_SB(b, h) + boff + n * 2048 + k * 1024); } while (0)
; #define PG8_WAIT_V(n) asm volatile("s_waitcnt vmcnt(" #n ")" ::: "memory")
; #define PG8_WAIT_L(n) asm volatile("s_waitcnt lgkmcnt(" #n ")" ::: "memory")
; #define PG8_BAR __builtin_amdgcn_s_barrier()
; #define PG8_SCHED __builtin_amdgcn_sched_barrier(0)
; template <class Epi, class Sched, bool ALIGN_EPI = false, bool SP2 = false>
; __device__ __forceinline__ void gemm_phase(LAS unsigned char* lds, const Gemm g, const Sched S, const Epi E) {
;     ...
;         const char* nA = has_next ? (const char*)g.A + (size_t)nxt.pm * tstep : cA; const char* nB = has_next ? (const char*)g.Bt + (size_t)nxt.pn * tstep : cB;
;         for (int t = 0; t < nt; t += 2) {
;             const bool last = (t == nt - 2);
;             const char* a1 = cA + (size_t)(t + 1) * kstep;
;             const char* a2 = last ? nA : cA + (size_t)(t + 2) * kstep; const char* b2 = last ? nB : cB + (size_t)(t + 2) * kstep;
;             const char* a3 = a2 + kstep; const char* b3 = b2 + kstep;
;             if (last && has_next) S.a_ready(nxt);
;             if (last) E.prefetch(cur, wr, fr, pre);
;             if constexpr (SP2) {
;             PG8_LDB(B0, 0, 0); PG8_LDB(B1, 0, 1); PG8_SCHED; PG8_LDA(At, 0, 0); PG8_STAGE(PG8_SA(1, 1), a1 + hstep, voffA);
;             PG8_WAIT_V(8); PG8_WAIT_L(0); PG8_BAR; PG8_MMA(0, 0, At, B0); PG8_MMA(0, 1, At, B1); PG8_BAR; PG8_SCHED;
;             PG8_LDA(At, 0, 1); PG8_STAGE(PG8_SB(0, 0), b2, voffB); PG8_STAGE(PG8_SB(0, 1), b2 + hstep, voffB); PG8_STAGE(PG8_SA(0, 0), a2, voffA);
;             PG8_WAIT_V(8); PG8_WAIT_L(0); PG8_BAR; PG8_MMA(1, 0, At, B0); PG8_MMA(1, 1, At, B1); PG8_BAR; PG8_SCHED;
.LBB0_646:
	v_add_u32_e32 v145, s47, v149
	ds_read_b128 v[162:165], v145
	ds_read_b128 v[166:169], v145 offset:1024
	ds_read_b128 v[170:173], v145 offset:2048
	ds_read_b128 v[174:177], v145 offset:3072
	v_add_u32_e32 v145, s48, v149
	ds_read_b128 v[178:181], v145
	ds_read_b128 v[182:185], v145 offset:1024
	ds_read_b128 v[186:189], v145 offset:2048
	ds_read_b128 v[194:197], v145 offset:3072
	s_add_u32 s40, s36, 0xfff80080
	s_addc_u32 s41, s37, -1
	s_and_b64 s[38:39], s[38:39], exec
	s_cselect_b32 s41, s25, s41
	s_cselect_b32 s40, s51, s40
	s_cselect_b32 s39, s23, s54
	s_cselect_b32 s38, s52, s53
	v_lshl_add_u64 v[190:191], s[36:37], 0, v[136:137]
	s_add_i32 m0, s30, 0xc000
	ds_read_b128 v[198:201], v151
	ds_read_b128 v[202:205], v151 offset:1024
	ds_read_b128 v[206:209], v151 offset:2048
	ds_read_b128 v[210:213], v151 offset:3072
	ds_read_b128 v[214:217], v151 offset:4096
	ds_read_b128 v[218:221], v151 offset:5120
	ds_read_b128 v[222:225], v151 offset:6144
	ds_read_b128 v[226:229], v151 offset:7168
	global_load_lds_dwordx4 v[190:191], off
	v_lshl_add_u64 v[190:191], s[36:37], 0, v[138:139]
	s_add_i32 m0, s30, 0xe000
	s_nop 0
	global_load_lds_dwordx4 v[190:191], off
	s_waitcnt vmcnt(8)
	s_waitcnt lgkmcnt(0)
	s_barrier
	s_waitcnt lgkmcnt(0)
	v_mfma_f32_16x16x32_bf16 v[124:127], v[162:165], v[198:201], v[124:127]
	v_mfma_f32_16x16x32_bf16 v[120:123], v[170:173], v[198:201], v[120:123]
	v_mfma_f32_16x16x32_bf16 v[108:111], v[162:165], v[206:209], v[108:111]
	v_mfma_f32_16x16x32_bf16 v[104:107], v[170:173], v[206:209], v[104:107]
	v_mfma_f32_16x16x32_bf16 v[92:95], v[162:165], v[214:217], v[92:95]
	v_mfma_f32_16x16x32_bf16 v[88:91], v[170:173], v[214:217], v[88:91]
	v_mfma_f32_16x16x32_bf16 v[76:79], v[162:165], v[222:225], v[76:79]
	v_mfma_f32_16x16x32_bf16 v[72:75], v[170:173], v[222:225], v[72:75]
	v_mfma_f32_16x16x32_bf16 v[124:127], v[166:169], v[202:205], v[124:127]
	v_mfma_f32_16x16x32_bf16 v[120:123], v[174:177], v[202:205], v[120:123]
	v_mfma_f32_16x16x32_bf16 v[108:111], v[166:169], v[210:213], v[108:111]
	v_mfma_f32_16x16x32_bf16 v[104:107], v[174:177], v[210:213], v[104:107]
	v_mfma_f32_16x16x32_bf16 v[92:95], v[166:169], v[218:221], v[92:95]
	v_mfma_f32_16x16x32_bf16 v[88:91], v[174:177], v[218:221], v[88:91]
	v_mfma_f32_16x16x32_bf16 v[76:79], v[166:169], v[226:229], v[76:79]
	v_mfma_f32_16x16x32_bf16 v[72:75], v[174:177], v[226:229], v[72:75]
	v_mfma_f32_16x16x32_bf16 v[116:119], v[178:181], v[198:201], v[116:119]
	v_mfma_f32_16x16x32_bf16 v[112:115], v[186:189], v[198:201], v[112:115]
	v_mfma_f32_16x16x32_bf16 v[100:103], v[178:181], v[206:209], v[100:103]
	v_mfma_f32_16x16x32_bf16 v[96:99], v[186:189], v[206:209], v[96:99]
	v_mfma_f32_16x16x32_bf16 v[84:87], v[178:181], v[214:217], v[84:87]
	v_mfma_f32_16x16x32_bf16 v[80:83], v[186:189], v[214:217], v[80:83]
	v_mfma_f32_16x16x32_bf16 v[68:71], v[178:181], v[222:225], v[68:71]
	v_mfma_f32_16x16x32_bf16 v[64:67], v[186:189], v[222:225], v[64:67]
	v_mfma_f32_16x16x32_bf16 v[116:119], v[182:185], v[202:205], v[116:119]
	v_mfma_f32_16x16x32_bf16 v[112:115], v[194:197], v[202:205], v[112:115]
	v_mfma_f32_16x16x32_bf16 v[100:103], v[182:185], v[210:213], v[100:103]
	v_mfma_f32_16x16x32_bf16 v[96:99], v[194:197], v[210:213], v[96:99]
	v_mfma_f32_16x16x32_bf16 v[84:87], v[182:185], v[218:221], v[84:87]
	v_mfma_f32_16x16x32_bf16 v[80:83], v[194:197], v[218:221], v[80:83]
	v_mfma_f32_16x16x32_bf16 v[68:71], v[182:185], v[226:229], v[68:71]
	v_mfma_f32_16x16x32_bf16 v[64:67], v[194:197], v[226:229], v[64:67]
	s_barrier
	s_add_i32 s56, s47, s11
	v_lshl_add_u64 v[190:191], s[38:39], 0, v[132:133]
	s_mov_b32 m0, s56
	ds_read_b128 v[198:201], v151 offset:16384
	ds_read_b128 v[202:205], v151 offset:17408
	ds_read_b128 v[206:209], v151 offset:18432
	ds_read_b128 v[210:213], v151 offset:19456
	ds_read_b128 v[214:217], v151 offset:20480
	ds_read_b128 v[218:221], v151 offset:21504
	ds_read_b128 v[222:225], v151 offset:22528
	ds_read_b128 v[226:229], v151 offset:23552
	global_load_lds_dwordx4 v[190:191], off
	s_add_i32 m0, s56, 0x2000
	s_add_u32 s56, s38, 0x80000
	v_lshl_add_u64 v[230:231], s[38:39], 0, v[128:129]
	s_addc_u32 s57, s39, 0
	s_add_i32 s58, s48, s11
	global_load_lds_dwordx4 v[230:231], off
	v_lshl_add_u64 v[232:233], s[56:57], 0, v[132:133]
	s_mov_b32 m0, s58
	v_lshl_add_u64 v[234:235], s[40:41], 0, v[130:131]
	global_load_lds_dwordx4 v[232:233], off
	v_lshl_add_u64 v[232:233], s[56:57], 0, v[128:129]
	s_add_i32 m0, s58, 0x2000
	s_nop 0
	global_load_lds_dwordx4 v[232:233], off
	v_lshl_add_u64 v[232:233], s[40:41], 0, v[134:135]
	s_mov_b32 m0, s30
	s_nop 0
	global_load_lds_dwordx4 v[232:233], off
	s_mov_b32 m0, s31
	s_nop 0
	global_load_lds_dwordx4 v[234:235], off
	s_waitcnt vmcnt(8)
	s_waitcnt lgkmcnt(0)
	s_barrier
; #define PG8_STAGE(bufoff, gbase, voff) do { _Pragma("unroll") for (int _i = 0; _i < 2; ++_i) \
;         __builtin_amdgcn_global_load_lds((const unsigned*)((const char*)(gbase) + (voff)[_i]), (LAS unsigned*)(lds + (bufoff) + ldsw + _i * 8192), 16, 0, 0); } while (0)
; #define PG8_LDA(dst, b, h) do { _Pragma("unroll") for (int m = 0; m < 4; ++m) _Pragma("unroll") for (int k = 0; k < 2; ++k) dst[m][k] = *(const LAS bf16x8*)(lds + PG8_SA(b, h) + aoff + m * 2048 + k * 1024); } while (0)
; #define PG8_LDB(dst, b, h) do { _Pragma("unroll") for (int n = 0; n < 2; ++n) _Pragma("unroll") for (int k = 0; k < 2; ++k) dst[n][k] = *(const LAS bf16x8*)(lds + PG8_SB(b, h) + boff + n * 2048 + k * 1024); } while (0)
; #define PG8_MMA(ai, bj, At, Bt) do { __builtin_amdgcn_s_setprio(1); _Pragma("unroll") for (int m = 0; m < 4; ++m) _Pragma("unroll") for (int n = 0; n < 2; ++n) _Pragma("unroll") for (int k = 0; k < 2; ++k) \
;         acc[ai][bj][m][n] = __builtin_amdgcn_mfma_f32_16x16x32_bf16(Bt[n][k], At[m][k], acc[ai][bj][m][n], 0, 0, 0); __builtin_amdgcn_s_setprio(0); } while (0)
; #define PG8_WAIT_V(n) asm volatile("s_waitcnt vmcnt(" #n ")" ::: "memory")
; #define PG8_WAIT_L(n) asm volatile("s_waitcnt lgkmcnt(" #n ")" ::: "memory")
; #define PG8_BAR __builtin_amdgcn_s_barrier()
; #define PG8_SCHED __builtin_amdgcn_sched_barrier(0)
; template <class Epi, class Sched, bool ALIGN_EPI = false, bool SP2 = false>
; __device__ __forceinline__ void gemm_phase(LAS unsigned char* lds, const Gemm g, const Sched S, const Epi E) {
;     ...
;             PG8_WAIT_V(8); PG8_WAIT_L(0); PG8_BAR; PG8_MMA(1, 0, At, B0); PG8_MMA(1, 1, At, B1); PG8_BAR; PG8_SCHED;
;             PG8_LDB(B0, 1, 0); PG8_LDB(B1, 1, 1); PG8_SCHED; PG8_LDA(At, 1, 0); PG8_STAGE(PG8_SA(0, 1), a2 + hstep, voffA);
;             PG8_WAIT_V(8); PG8_WAIT_L(0); PG8_BAR; PG8_MMA(0, 0, At, B0); PG8_MMA(0, 1, At, B1); PG8_BAR; PG8_SCHED;
	s_waitcnt lgkmcnt(0)
	v_mfma_f32_16x16x32_bf16 v[60:63], v[162:165], v[198:201], v[60:63]
	v_mfma_f32_16x16x32_bf16 v[56:59], v[170:173], v[198:201], v[56:59]
	v_mfma_f32_16x16x32_bf16 v[44:47], v[162:165], v[206:209], v[44:47]
	v_mfma_f32_16x16x32_bf16 v[40:43], v[170:173], v[206:209], v[40:43]
	v_mfma_f32_16x16x32_bf16 v[28:31], v[162:165], v[214:217], v[28:31]
	v_mfma_f32_16x16x32_bf16 v[24:27], v[170:173], v[214:217], v[24:27]
	v_mfma_f32_16x16x32_bf16 v[12:15], v[162:165], v[222:225], v[12:15]
	v_mfma_f32_16x16x32_bf16 v[8:11], v[170:173], v[222:225], v[8:11]
	v_mfma_f32_16x16x32_bf16 v[60:63], v[166:169], v[202:205], v[60:63]
	v_mfma_f32_16x16x32_bf16 v[56:59], v[174:177], v[202:205], v[56:59]
	v_mfma_f32_16x16x32_bf16 v[44:47], v[166:169], v[210:213], v[44:47]
	v_mfma_f32_16x16x32_bf16 v[40:43], v[174:177], v[210:213], v[40:43]
	v_mfma_f32_16x16x32_bf16 v[28:31], v[166:169], v[218:221], v[28:31]
	v_mfma_f32_16x16x32_bf16 v[24:27], v[174:177], v[218:221], v[24:27]
	v_mfma_f32_16x16x32_bf16 v[12:15], v[166:169], v[226:229], v[12:15]
	v_mfma_f32_16x16x32_bf16 v[8:11], v[174:177], v[226:229], v[8:11]
	v_mfma_f32_16x16x32_bf16 v[52:55], v[178:181], v[198:201], v[52:55]
	v_mfma_f32_16x16x32_bf16 v[48:51], v[186:189], v[198:201], v[48:51]
	v_mfma_f32_16x16x32_bf16 v[36:39], v[178:181], v[206:209], v[36:39]
	v_mfma_f32_16x16x32_bf16 v[32:35], v[186:189], v[206:209], v[32:35]
	v_mfma_f32_16x16x32_bf16 v[20:23], v[178:181], v[214:217], v[20:23]
	v_mfma_f32_16x16x32_bf16 v[16:19], v[186:189], v[214:217], v[16:19]
	v_mfma_f32_16x16x32_bf16 v[4:7], v[178:181], v[222:225], v[4:7]
	v_mfma_f32_16x16x32_bf16 v[0:3], v[186:189], v[222:225], v[0:3]
	v_mfma_f32_16x16x32_bf16 v[52:55], v[182:185], v[202:205], v[52:55]
	v_mfma_f32_16x16x32_bf16 v[48:51], v[194:197], v[202:205], v[48:51]
	v_mfma_f32_16x16x32_bf16 v[36:39], v[182:185], v[210:213], v[36:39]
	v_mfma_f32_16x16x32_bf16 v[32:35], v[194:197], v[210:213], v[32:35]
	v_mfma_f32_16x16x32_bf16 v[20:23], v[182:185], v[218:221], v[20:23]
	v_mfma_f32_16x16x32_bf16 v[16:19], v[194:197], v[218:221], v[16:19]
	v_mfma_f32_16x16x32_bf16 v[4:7], v[182:185], v[226:229], v[4:7]
	v_mfma_f32_16x16x32_bf16 v[0:3], v[194:197], v[226:229], v[0:3]
	s_barrier
	s_add_i32 s56, 0, 0x18000
	v_add_u32_e32 v145, s56, v149
	s_add_i32 s57, 0, 0x1c000
	ds_read_b128 v[162:165], v145
	ds_read_b128 v[166:169], v145 offset:1024
	ds_read_b128 v[170:173], v145 offset:2048
	ds_read_b128 v[174:177], v145 offset:3072
	v_add_u32_e32 v145, s57, v149
	ds_read_b128 v[178:181], v145
	ds_read_b128 v[182:185], v145 offset:1024
	ds_read_b128 v[186:189], v145 offset:2048
	ds_read_b128 v[194:197], v145 offset:3072
	s_add_u32 s40, s40, 0x80000
	s_addc_u32 s41, s41, 0
	s_mov_b32 m0, s33
	v_lshl_add_u64 v[236:237], s[40:41], 0, v[134:135]
	ds_read_b128 v[198:201], v151 offset:32768
	ds_read_b128 v[202:205], v151 offset:33792
	ds_read_b128 v[206:209], v151 offset:34816
	ds_read_b128 v[210:213], v151 offset:35840
	ds_read_b128 v[214:217], v151 offset:36864
	ds_read_b128 v[218:221], v151 offset:37888
	ds_read_b128 v[222:225], v151 offset:38912
	ds_read_b128 v[226:229], v151 offset:39936
	global_load_lds_dwordx4 v[236:237], off
	v_lshl_add_u64 v[236:237], s[40:41], 0, v[130:131]
	s_mov_b32 m0, s42
	s_nop 0
	global_load_lds_dwordx4 v[236:237], off
	s_waitcnt vmcnt(8)
	s_waitcnt lgkmcnt(0)
	s_barrier
	s_waitcnt lgkmcnt(0)
	v_mfma_f32_16x16x32_bf16 v[124:127], v[162:165], v[198:201], v[124:127]
	v_mfma_f32_16x16x32_bf16 v[120:123], v[170:173], v[198:201], v[120:123]
	v_mfma_f32_16x16x32_bf16 v[108:111], v[162:165], v[206:209], v[108:111]
	v_mfma_f32_16x16x32_bf16 v[104:107], v[170:173], v[206:209], v[104:107]
	v_mfma_f32_16x16x32_bf16 v[92:95], v[162:165], v[214:217], v[92:95]
	v_mfma_f32_16x16x32_bf16 v[88:91], v[170:173], v[214:217], v[88:91]
	v_mfma_f32_16x16x32_bf16 v[76:79], v[162:165], v[222:225], v[76:79]
	v_mfma_f32_16x16x32_bf16 v[72:75], v[170:173], v[222:225], v[72:75]
	v_mfma_f32_16x16x32_bf16 v[124:127], v[166:169], v[202:205], v[124:127]
	v_mfma_f32_16x16x32_bf16 v[120:123], v[174:177], v[202:205], v[120:123]
	v_mfma_f32_16x16x32_bf16 v[108:111], v[166:169], v[210:213], v[108:111]
	v_mfma_f32_16x16x32_bf16 v[104:107], v[174:177], v[210:213], v[104:107]
	v_mfma_f32_16x16x32_bf16 v[92:95], v[166:169], v[218:221], v[92:95]
	v_mfma_f32_16x16x32_bf16 v[88:91], v[174:177], v[218:221], v[88:91]
	v_mfma_f32_16x16x32_bf16 v[76:79], v[166:169], v[226:229], v[76:79]
	v_mfma_f32_16x16x32_bf16 v[72:75], v[174:177], v[226:229], v[72:75]
	v_mfma_f32_16x16x32_bf16 v[116:119], v[178:181], v[198:201], v[116:119]
	v_mfma_f32_16x16x32_bf16 v[112:115], v[186:189], v[198:201], v[112:115]
	v_mfma_f32_16x16x32_bf16 v[100:103], v[178:181], v[206:209], v[100:103]
	v_mfma_f32_16x16x32_bf16 v[96:99], v[186:189], v[206:209], v[96:99]
	v_mfma_f32_16x16x32_bf16 v[84:87], v[178:181], v[214:217], v[84:87]
	v_mfma_f32_16x16x32_bf16 v[80:83], v[186:189], v[214:217], v[80:83]
	v_mfma_f32_16x16x32_bf16 v[68:71], v[178:181], v[222:225], v[68:71]
	v_mfma_f32_16x16x32_bf16 v[64:67], v[186:189], v[222:225], v[64:67]
	v_mfma_f32_16x16x32_bf16 v[116:119], v[182:185], v[202:205], v[116:119]
	v_mfma_f32_16x16x32_bf16 v[112:115], v[194:197], v[202:205], v[112:115]
	v_mfma_f32_16x16x32_bf16 v[100:103], v[182:185], v[210:213], v[100:103]
	v_mfma_f32_16x16x32_bf16 v[96:99], v[194:197], v[210:213], v[96:99]
	v_mfma_f32_16x16x32_bf16 v[84:87], v[182:185], v[218:221], v[84:87]
	v_mfma_f32_16x16x32_bf16 v[80:83], v[194:197], v[218:221], v[80:83]
	v_mfma_f32_16x16x32_bf16 v[68:71], v[182:185], v[226:229], v[68:71]
	v_mfma_f32_16x16x32_bf16 v[64:67], v[194:197], v[226:229], v[64:67]
	s_barrier
; #define PG8_STAGE(bufoff, gbase, voff) do { _Pragma("unroll") for (int _i = 0; _i < 2; ++_i) \
;         __builtin_amdgcn_global_load_lds((const unsigned*)((const char*)(gbase) + (voff)[_i]), (LAS unsigned*)(lds + (bufoff) + ldsw + _i * 8192), 16, 0, 0); } while (0)
; #define PG8_LDA(dst, b, h) do { _Pragma("unroll") for (int m = 0; m < 4; ++m) _Pragma("unroll") for (int k = 0; k < 2; ++k) dst[m][k] = *(const LAS bf16x8*)(lds + PG8_SA(b, h) + aoff + m * 2048 + k * 1024); } while (0)
; #define PG8_MMA(ai, bj, At, Bt) do { __builtin_amdgcn_s_setprio(1); _Pragma("unroll") for (int m = 0; m < 4; ++m) _Pragma("unroll") for (int n = 0; n < 2; ++n) _Pragma("unroll") for (int k = 0; k < 2; ++k) \
;         acc[ai][bj][m][n] = __builtin_amdgcn_mfma_f32_16x16x32_bf16(Bt[n][k], At[m][k], acc[ai][bj][m][n], 0, 0, 0); __builtin_amdgcn_s_setprio(0); } while (0)
; #define PG8_WAIT_V(n) asm volatile("s_waitcnt vmcnt(" #n ")" ::: "memory")
; #define PG8_WAIT_L(n) asm volatile("s_waitcnt lgkmcnt(" #n ")" ::: "memory")
; #define PG8_BAR __builtin_amdgcn_s_barrier()
; #define PG8_SCHED __builtin_amdgcn_sched_barrier(0)
; template <class Epi, class Sched, bool ALIGN_EPI = false, bool SP2 = false>
; __device__ __forceinline__ void gemm_phase(LAS unsigned char* lds, const Gemm g, const Sched S, const Epi E) {
;     ...
;         for (int t = 0; t < nt; t += 2) {
;             const bool last = (t == nt - 2);
;             const char* a1 = cA + (size_t)(t + 1) * kstep;
;             const char* a2 = last ? nA : cA + (size_t)(t + 2) * kstep; const char* b2 = last ? nB : cB + (size_t)(t + 2) * kstep;
;             const char* a3 = a2 + kstep; const char* b3 = b2 + kstep;
;     ...
;             PG8_LDA(At, 1, 1); PG8_STAGE(PG8_SB(1, 0), b3, voffB); PG8_STAGE(PG8_SB(1, 1), b3 + hstep, voffB); PG8_STAGE(PG8_SA(1, 0), a3, voffA);
;             PG8_WAIT_V(8); PG8_WAIT_L(0); PG8_BAR; PG8_MMA(1, 0, At, B0); PG8_MMA(1, 1, At, B1); PG8_BAR; PG8_SCHED;
	s_add_i32 s40, s56, s11
	v_lshl_add_u64 v[190:191], v[190:191], 0, s[14:15]
	s_mov_b32 m0, s40
	ds_read_b128 v[198:201], v151 offset:49152
	ds_read_b128 v[202:205], v151 offset:50176
	ds_read_b128 v[206:209], v151 offset:51200
	ds_read_b128 v[210:213], v151 offset:52224
	ds_read_b128 v[214:217], v151 offset:53248
	ds_read_b128 v[218:221], v151 offset:54272
	ds_read_b128 v[222:225], v151 offset:55296
	ds_read_b128 v[226:229], v151 offset:56320
	global_load_lds_dwordx4 v[190:191], off
	s_add_i32 m0, s40, 0x2000
	s_add_u32 s38, s38, 0x80080
	v_lshl_add_u64 v[190:191], v[230:231], 0, s[14:15]
	s_addc_u32 s39, s39, 0
	s_add_i32 s40, s57, s11
	global_load_lds_dwordx4 v[190:191], off
	v_lshl_add_u64 v[190:191], s[38:39], 0, v[132:133]
	s_mov_b32 m0, s40
	s_nop 0
	global_load_lds_dwordx4 v[190:191], off
	v_lshl_add_u64 v[190:191], s[38:39], 0, v[128:129]
	s_add_i32 m0, s40, 0x2000
	s_nop 0
	global_load_lds_dwordx4 v[190:191], off
	v_lshl_add_u64 v[190:191], v[232:233], 0, s[14:15]
	s_mov_b32 m0, s44
	s_nop 0
	global_load_lds_dwordx4 v[190:191], off
	v_lshl_add_u64 v[190:191], v[234:235], 0, s[14:15]
	s_mov_b32 m0, s45
	s_nop 0
	global_load_lds_dwordx4 v[190:191], off
	s_waitcnt vmcnt(8)
	s_waitcnt lgkmcnt(0)
	s_barrier
	s_waitcnt lgkmcnt(0)
	v_mfma_f32_16x16x32_bf16 v[60:63], v[162:165], v[198:201], v[60:63]
	v_mfma_f32_16x16x32_bf16 v[56:59], v[170:173], v[198:201], v[56:59]
	v_mfma_f32_16x16x32_bf16 v[44:47], v[162:165], v[206:209], v[44:47]
	v_mfma_f32_16x16x32_bf16 v[40:43], v[170:173], v[206:209], v[40:43]
	v_mfma_f32_16x16x32_bf16 v[28:31], v[162:165], v[214:217], v[28:31]
	v_mfma_f32_16x16x32_bf16 v[24:27], v[170:173], v[214:217], v[24:27]
	v_mfma_f32_16x16x32_bf16 v[12:15], v[162:165], v[222:225], v[12:15]
	v_mfma_f32_16x16x32_bf16 v[8:11], v[170:173], v[222:225], v[8:11]
	v_mfma_f32_16x16x32_bf16 v[60:63], v[166:169], v[202:205], v[60:63]
	v_mfma_f32_16x16x32_bf16 v[56:59], v[174:177], v[202:205], v[56:59]
	v_mfma_f32_16x16x32_bf16 v[44:47], v[166:169], v[210:213], v[44:47]
	v_mfma_f32_16x16x32_bf16 v[40:43], v[174:177], v[210:213], v[40:43]
	v_mfma_f32_16x16x32_bf16 v[28:31], v[166:169], v[218:221], v[28:31]
	v_mfma_f32_16x16x32_bf16 v[24:27], v[174:177], v[218:221], v[24:27]
	v_mfma_f32_16x16x32_bf16 v[12:15], v[166:169], v[226:229], v[12:15]
	v_mfma_f32_16x16x32_bf16 v[8:11], v[174:177], v[226:229], v[8:11]
	v_mfma_f32_16x16x32_bf16 v[52:55], v[178:181], v[198:201], v[52:55]
	v_mfma_f32_16x16x32_bf16 v[48:51], v[186:189], v[198:201], v[48:51]
	v_mfma_f32_16x16x32_bf16 v[36:39], v[178:181], v[206:209], v[36:39]
	v_mfma_f32_16x16x32_bf16 v[32:35], v[186:189], v[206:209], v[32:35]
	v_mfma_f32_16x16x32_bf16 v[20:23], v[178:181], v[214:217], v[20:23]
	v_mfma_f32_16x16x32_bf16 v[16:19], v[186:189], v[214:217], v[16:19]
	v_mfma_f32_16x16x32_bf16 v[4:7], v[178:181], v[222:225], v[4:7]
	v_mfma_f32_16x16x32_bf16 v[0:3], v[186:189], v[222:225], v[0:3]
	v_mfma_f32_16x16x32_bf16 v[52:55], v[182:185], v[202:205], v[52:55]
	v_mfma_f32_16x16x32_bf16 v[48:51], v[194:197], v[202:205], v[48:51]
	v_mfma_f32_16x16x32_bf16 v[36:39], v[182:185], v[210:213], v[36:39]
	v_mfma_f32_16x16x32_bf16 v[32:35], v[194:197], v[210:213], v[32:35]
	v_mfma_f32_16x16x32_bf16 v[20:23], v[182:185], v[218:221], v[20:23]
	v_mfma_f32_16x16x32_bf16 v[16:19], v[194:197], v[218:221], v[16:19]
	v_mfma_f32_16x16x32_bf16 v[4:7], v[182:185], v[226:229], v[4:7]
	v_mfma_f32_16x16x32_bf16 v[0:3], v[194:197], v[226:229], v[0:3]
	s_barrier
	s_add_i32 s55, s55, 2
	s_add_u32 s36, s36, 0x100
	s_addc_u32 s37, s37, 0
	s_add_u32 s53, s53, 0x100
	s_addc_u32 s54, s54, 0
	s_cmp_gt_u32 s55, 29
	s_cbranch_scc1 .LBB0_649

; #define PG8_STAGE(bufoff, gbase, voff) do { _Pragma("unroll") for (int _i = 0; _i < 2; ++_i) \
;         __builtin_amdgcn_global_load_lds((const unsigned*)((const char*)(gbase) + (voff)[_i]), (LAS unsigned*)(lds + (bufoff) + ldsw + _i * 8192), 16, 0, 0); } while (0)
; #define PG8_LDA(dst, b, h) do { _Pragma("unroll") for (int m = 0; m < 4; ++m) _Pragma("unroll") for (int k = 0; k < 2; ++k) dst[m][k] = *(const LAS bf16x8*)(lds + PG8_SA(b, h) + aoff + m * 2048 + k * 1024); } while (0)
; #define PG8_LDB(dst, b, h) do { _Pragma("unroll") for (int n = 0; n < 2; ++n) _Pragma("unroll") for (int k = 0; k < 2; ++k) dst[n][k] = *(const LAS bf16x8*)(lds + PG8_SB(b, h) + boff + n * 2048 + k * 1024); } while (0)
; #define PG8_WAIT_V(n) asm volatile("s_waitcnt vmcnt(" #n ")" ::: "memory")
; #define PG8_WAIT_L(n) asm volatile("s_waitcnt lgkmcnt(" #n ")" ::: "memory")
; #define PG8_BAR __builtin_amdgcn_s_barrier()
; #define PG8_SCHED __builtin_amdgcn_sched_barrier(0)
; template <class Epi, class Sched, bool ALIGN_EPI = false, bool SP2 = false>
; __device__ __forceinline__ void gemm_phase(LAS unsigned char* lds, const Gemm g, const Sched S, const Epi E) {
;     ...
;         const char* nA = has_next ? (const char*)g.A + (size_t)nxt.pm * tstep : cA; const char* nB = has_next ? (const char*)g.Bt + (size_t)nxt.pn * tstep : cB;
;         for (int t = 0; t < nt; t += 2) {
;             const bool last = (t == nt - 2);
;             const char* a1 = cA + (size_t)(t + 1) * kstep;
;             const char* a2 = last ? nA : cA + (size_t)(t + 2) * kstep; const char* b2 = last ? nB : cB + (size_t)(t + 2) * kstep;
;             const char* a3 = a2 + kstep; const char* b3 = b2 + kstep;
;             if (last && has_next) S.a_ready(nxt);
;             if (last) E.prefetch(cur, wr, fr, pre);
;             if constexpr (SP2) {
;             PG8_LDB(B0, 0, 0); PG8_LDB(B1, 0, 1); PG8_SCHED; PG8_LDA(At, 0, 0); PG8_STAGE(PG8_SA(1, 1), a1 + hstep, voffA);
;             PG8_WAIT_V(8); PG8_WAIT_L(0); PG8_BAR; PG8_MMA(0, 0, At, B0); PG8_MMA(0, 1, At, B1); PG8_BAR; PG8_SCHED;
;             PG8_LDA(At, 0, 1); PG8_STAGE(PG8_SB(0, 0), b2, voffB); PG8_STAGE(PG8_SB(0, 1), b2 + hstep, voffB); PG8_STAGE(PG8_SA(0, 0), a2, voffA);
;             PG8_WAIT_V(8); PG8_WAIT_L(0); PG8_BAR; PG8_MMA(1, 0, At, B0); PG8_MMA(1, 1, At, B1); PG8_BAR; PG8_SCHED;
.LBB0_733:
	ds_read_b128 v[140:143], v183
	ds_read_b128 v[144:147], v183 offset:1024
	ds_read_b128 v[148:151], v183 offset:2048
	ds_read_b128 v[152:155], v183 offset:3072
	ds_read_b128 v[156:159], v184
	ds_read_b128 v[160:163], v184 offset:1024
	ds_read_b128 v[164:167], v184 offset:2048
	ds_read_b128 v[168:171], v184 offset:3072
	s_add_u32 s36, s34, 0xffea8080
	s_addc_u32 s37, s35, -1
	s_cmpk_eq_i32 s52, 0x52
	s_cselect_b32 s39, s1, s37
	s_cselect_b32 s38, s0, s36
	s_cselect_b32 s37, s27, s51
	s_cselect_b32 s36, s26, s50
	v_lshl_add_u64 v[214:215], s[34:35], 0, v[132:133]
	s_add_i32 m0, s28, 0xc000
	ds_read_b128 v[172:175], v185
	ds_read_b128 v[176:179], v185 offset:1024
	ds_read_b128 v[188:191], v185 offset:2048
	ds_read_b128 v[194:197], v185 offset:3072
	ds_read_b128 v[198:201], v185 offset:4096
	ds_read_b128 v[202:205], v185 offset:5120
	ds_read_b128 v[206:209], v185 offset:6144
	ds_read_b128 v[210:213], v185 offset:7168
	global_load_lds_dwordx4 v[214:215], off
	v_lshl_add_u64 v[214:215], s[34:35], 0, v[134:135]
	s_add_i32 m0, s28, 0xe000
	s_nop 0
	global_load_lds_dwordx4 v[214:215], off
	s_waitcnt vmcnt(8)
	s_waitcnt lgkmcnt(0)
	s_barrier
	s_waitcnt lgkmcnt(0)
	v_mfma_f32_16x16x32_bf16 v[124:127], v[140:143], v[172:175], v[124:127]
	v_mfma_f32_16x16x32_bf16 v[120:123], v[148:151], v[172:175], v[120:123]
	v_mfma_f32_16x16x32_bf16 v[108:111], v[140:143], v[188:191], v[108:111]
	v_mfma_f32_16x16x32_bf16 v[104:107], v[148:151], v[188:191], v[104:107]
	v_mfma_f32_16x16x32_bf16 v[92:95], v[140:143], v[198:201], v[92:95]
	v_mfma_f32_16x16x32_bf16 v[88:91], v[148:151], v[198:201], v[88:91]
	v_mfma_f32_16x16x32_bf16 v[76:79], v[140:143], v[206:209], v[76:79]
	v_mfma_f32_16x16x32_bf16 v[72:75], v[148:151], v[206:209], v[72:75]
	v_mfma_f32_16x16x32_bf16 v[124:127], v[144:147], v[176:179], v[124:127]
	v_mfma_f32_16x16x32_bf16 v[120:123], v[152:155], v[176:179], v[120:123]
	v_mfma_f32_16x16x32_bf16 v[108:111], v[144:147], v[194:197], v[108:111]
	v_mfma_f32_16x16x32_bf16 v[104:107], v[152:155], v[194:197], v[104:107]
	v_mfma_f32_16x16x32_bf16 v[92:95], v[144:147], v[202:205], v[92:95]
	v_mfma_f32_16x16x32_bf16 v[88:91], v[152:155], v[202:205], v[88:91]
	v_mfma_f32_16x16x32_bf16 v[76:79], v[144:147], v[210:213], v[76:79]
	v_mfma_f32_16x16x32_bf16 v[72:75], v[152:155], v[210:213], v[72:75]
	v_mfma_f32_16x16x32_bf16 v[116:119], v[156:159], v[172:175], v[116:119]
	v_mfma_f32_16x16x32_bf16 v[112:115], v[164:167], v[172:175], v[112:115]
	v_mfma_f32_16x16x32_bf16 v[100:103], v[156:159], v[188:191], v[100:103]
	v_mfma_f32_16x16x32_bf16 v[96:99], v[164:167], v[188:191], v[96:99]
	v_mfma_f32_16x16x32_bf16 v[84:87], v[156:159], v[198:201], v[84:87]
	v_mfma_f32_16x16x32_bf16 v[80:83], v[164:167], v[198:201], v[80:83]
	v_mfma_f32_16x16x32_bf16 v[68:71], v[156:159], v[206:209], v[68:71]
	v_mfma_f32_16x16x32_bf16 v[64:67], v[164:167], v[206:209], v[64:67]
	v_mfma_f32_16x16x32_bf16 v[116:119], v[160:163], v[176:179], v[116:119]
	v_mfma_f32_16x16x32_bf16 v[112:115], v[168:171], v[176:179], v[112:115]
	v_mfma_f32_16x16x32_bf16 v[100:103], v[160:163], v[194:197], v[100:103]
	v_mfma_f32_16x16x32_bf16 v[96:99], v[168:171], v[194:197], v[96:99]
	v_mfma_f32_16x16x32_bf16 v[84:87], v[160:163], v[202:205], v[84:87]
	v_mfma_f32_16x16x32_bf16 v[80:83], v[168:171], v[202:205], v[80:83]
	v_mfma_f32_16x16x32_bf16 v[68:71], v[160:163], v[210:213], v[68:71]
	v_mfma_f32_16x16x32_bf16 v[64:67], v[168:171], v[210:213], v[64:67]
	s_barrier
	s_add_i32 s53, s44, s11
	v_lshl_add_u64 v[214:215], s[36:37], 0, v[128:129]
	s_mov_b32 m0, s53
	ds_read_b128 v[172:175], v185 offset:16384
	ds_read_b128 v[176:179], v185 offset:17408
	ds_read_b128 v[188:191], v185 offset:18432
	ds_read_b128 v[194:197], v185 offset:19456
	ds_read_b128 v[198:201], v185 offset:20480
	ds_read_b128 v[202:205], v185 offset:21504
	ds_read_b128 v[206:209], v185 offset:22528
	ds_read_b128 v[210:213], v185 offset:23552
	global_load_lds_dwordx4 v[214:215], off
	s_add_i32 m0, s53, 0x2000
	s_add_u32 s54, s36, 0x158000
	v_lshl_add_u64 v[216:217], s[36:37], 0, v[130:131]
	s_addc_u32 s55, s37, 0
	s_add_i32 s53, s45, s11
	global_load_lds_dwordx4 v[216:217], off
	v_lshl_add_u64 v[218:219], s[54:55], 0, v[128:129]
	s_mov_b32 m0, s53
	v_lshl_add_u64 v[220:221], s[38:39], 0, v[130:131]
	global_load_lds_dwordx4 v[218:219], off
	v_lshl_add_u64 v[218:219], s[54:55], 0, v[130:131]
	s_add_i32 m0, s53, 0x2000
	s_nop 0
	global_load_lds_dwordx4 v[218:219], off
	v_lshl_add_u64 v[218:219], s[38:39], 0, v[128:129]
	s_mov_b32 m0, s28
	s_nop 0
	global_load_lds_dwordx4 v[218:219], off
	s_mov_b32 m0, s29
	s_nop 0
	global_load_lds_dwordx4 v[220:221], off
	s_waitcnt vmcnt(8)
	s_waitcnt lgkmcnt(0)
	s_barrier
; #define PG8_STAGE(bufoff, gbase, voff) do { _Pragma("unroll") for (int _i = 0; _i < 2; ++_i) \
;         __builtin_amdgcn_global_load_lds((const unsigned*)((const char*)(gbase) + (voff)[_i]), (LAS unsigned*)(lds + (bufoff) + ldsw + _i * 8192), 16, 0, 0); } while (0)
; #define PG8_LDA(dst, b, h) do { _Pragma("unroll") for (int m = 0; m < 4; ++m) _Pragma("unroll") for (int k = 0; k < 2; ++k) dst[m][k] = *(const LAS bf16x8*)(lds + PG8_SA(b, h) + aoff + m * 2048 + k * 1024); } while (0)
; #define PG8_LDB(dst, b, h) do { _Pragma("unroll") for (int n = 0; n < 2; ++n) _Pragma("unroll") for (int k = 0; k < 2; ++k) dst[n][k] = *(const LAS bf16x8*)(lds + PG8_SB(b, h) + boff + n * 2048 + k * 1024); } while (0)
; #define PG8_MMA(ai, bj, At, Bt) do { __builtin_amdgcn_s_setprio(1); _Pragma("unroll") for (int m = 0; m < 4; ++m) _Pragma("unroll") for (int n = 0; n < 2; ++n) _Pragma("unroll") for (int k = 0; k < 2; ++k) \
;         acc[ai][bj][m][n] = __builtin_amdgcn_mfma_f32_16x16x32_bf16(Bt[n][k], At[m][k], acc[ai][bj][m][n], 0, 0, 0); __builtin_amdgcn_s_setprio(0); } while (0)
; #define PG8_WAIT_V(n) asm volatile("s_waitcnt vmcnt(" #n ")" ::: "memory")
; #define PG8_WAIT_L(n) asm volatile("s_waitcnt lgkmcnt(" #n ")" ::: "memory")
; #define PG8_BAR __builtin_amdgcn_s_barrier()
; #define PG8_SCHED __builtin_amdgcn_sched_barrier(0)
; template <class Epi, class Sched, bool ALIGN_EPI = false, bool SP2 = false>
; __device__ __forceinline__ void gemm_phase(LAS unsigned char* lds, const Gemm g, const Sched S, const Epi E) {
;     ...
;             PG8_WAIT_V(8); PG8_WAIT_L(0); PG8_BAR; PG8_MMA(1, 0, At, B0); PG8_MMA(1, 1, At, B1); PG8_BAR; PG8_SCHED;
;             PG8_LDB(B0, 1, 0); PG8_LDB(B1, 1, 1); PG8_SCHED; PG8_LDA(At, 1, 0); PG8_STAGE(PG8_SA(0, 1), a2 + hstep, voffA);
;             PG8_WAIT_V(8); PG8_WAIT_L(0); PG8_BAR; PG8_MMA(0, 0, At, B0); PG8_MMA(0, 1, At, B1); PG8_BAR; PG8_SCHED;
	s_waitcnt lgkmcnt(0)
	v_mfma_f32_16x16x32_bf16 v[60:63], v[140:143], v[172:175], v[60:63]
	v_mfma_f32_16x16x32_bf16 v[56:59], v[148:151], v[172:175], v[56:59]
	v_mfma_f32_16x16x32_bf16 v[44:47], v[140:143], v[188:191], v[44:47]
	v_mfma_f32_16x16x32_bf16 v[40:43], v[148:151], v[188:191], v[40:43]
	v_mfma_f32_16x16x32_bf16 v[28:31], v[140:143], v[198:201], v[28:31]
	v_mfma_f32_16x16x32_bf16 v[24:27], v[148:151], v[198:201], v[24:27]
	v_mfma_f32_16x16x32_bf16 v[12:15], v[140:143], v[206:209], v[12:15]
	v_mfma_f32_16x16x32_bf16 v[8:11], v[148:151], v[206:209], v[8:11]
	v_mfma_f32_16x16x32_bf16 v[60:63], v[144:147], v[176:179], v[60:63]
	v_mfma_f32_16x16x32_bf16 v[56:59], v[152:155], v[176:179], v[56:59]
	v_mfma_f32_16x16x32_bf16 v[44:47], v[144:147], v[194:197], v[44:47]
	v_mfma_f32_16x16x32_bf16 v[40:43], v[152:155], v[194:197], v[40:43]
	v_mfma_f32_16x16x32_bf16 v[28:31], v[144:147], v[202:205], v[28:31]
	v_mfma_f32_16x16x32_bf16 v[24:27], v[152:155], v[202:205], v[24:27]
	v_mfma_f32_16x16x32_bf16 v[12:15], v[144:147], v[210:213], v[12:15]
	v_mfma_f32_16x16x32_bf16 v[8:11], v[152:155], v[210:213], v[8:11]
	v_mfma_f32_16x16x32_bf16 v[52:55], v[156:159], v[172:175], v[52:55]
	v_mfma_f32_16x16x32_bf16 v[48:51], v[164:167], v[172:175], v[48:51]
	v_mfma_f32_16x16x32_bf16 v[36:39], v[156:159], v[188:191], v[36:39]
	v_mfma_f32_16x16x32_bf16 v[32:35], v[164:167], v[188:191], v[32:35]
	v_mfma_f32_16x16x32_bf16 v[20:23], v[156:159], v[198:201], v[20:23]
	v_mfma_f32_16x16x32_bf16 v[16:19], v[164:167], v[198:201], v[16:19]
	v_mfma_f32_16x16x32_bf16 v[4:7], v[156:159], v[206:209], v[4:7]
	v_mfma_f32_16x16x32_bf16 v[0:3], v[164:167], v[206:209], v[0:3]
	v_mfma_f32_16x16x32_bf16 v[52:55], v[160:163], v[176:179], v[52:55]
	v_mfma_f32_16x16x32_bf16 v[48:51], v[168:171], v[176:179], v[48:51]
	v_mfma_f32_16x16x32_bf16 v[36:39], v[160:163], v[194:197], v[36:39]
	v_mfma_f32_16x16x32_bf16 v[32:35], v[168:171], v[194:197], v[32:35]
	v_mfma_f32_16x16x32_bf16 v[20:23], v[160:163], v[202:205], v[20:23]
	v_mfma_f32_16x16x32_bf16 v[16:19], v[168:171], v[202:205], v[16:19]
	v_mfma_f32_16x16x32_bf16 v[4:7], v[160:163], v[210:213], v[4:7]
	v_mfma_f32_16x16x32_bf16 v[0:3], v[168:171], v[210:213], v[0:3]
	s_barrier
	s_add_i32 s53, 0, 0x18000
	s_add_i32 s54, 0, 0x1c000
	v_add_u32_e32 v152, s53, v181
	v_add_u32_e32 v168, s54, v181
	ds_read_b128 v[140:143], v152
	ds_read_b128 v[144:147], v152 offset:1024
	ds_read_b128 v[148:151], v152 offset:2048
	ds_read_b128 v[152:155], v152 offset:3072
	ds_read_b128 v[156:159], v168
	ds_read_b128 v[160:163], v168 offset:1024
	ds_read_b128 v[164:167], v168 offset:2048
	ds_read_b128 v[168:171], v168 offset:3072
	s_add_u32 s38, s38, 0x158000
	s_addc_u32 s39, s39, 0
	s_mov_b32 m0, s30
	v_lshl_add_u64 v[222:223], s[38:39], 0, v[128:129]
	ds_read_b128 v[172:175], v185 offset:32768
	ds_read_b128 v[176:179], v185 offset:33792
	ds_read_b128 v[188:191], v185 offset:34816
	ds_read_b128 v[194:197], v185 offset:35840
	ds_read_b128 v[198:201], v185 offset:36864
	ds_read_b128 v[202:205], v185 offset:37888
	ds_read_b128 v[206:209], v185 offset:38912
	ds_read_b128 v[210:213], v185 offset:39936
	global_load_lds_dwordx4 v[222:223], off
	v_lshl_add_u64 v[222:223], s[38:39], 0, v[130:131]
	s_mov_b32 m0, s31
	s_nop 0
	global_load_lds_dwordx4 v[222:223], off
	s_waitcnt vmcnt(8)
	s_waitcnt lgkmcnt(0)
	s_barrier
	s_waitcnt lgkmcnt(0)
	v_mfma_f32_16x16x32_bf16 v[124:127], v[140:143], v[172:175], v[124:127]
	v_mfma_f32_16x16x32_bf16 v[120:123], v[148:151], v[172:175], v[120:123]
	v_mfma_f32_16x16x32_bf16 v[108:111], v[140:143], v[188:191], v[108:111]
	v_mfma_f32_16x16x32_bf16 v[104:107], v[148:151], v[188:191], v[104:107]
	v_mfma_f32_16x16x32_bf16 v[92:95], v[140:143], v[198:201], v[92:95]
	v_mfma_f32_16x16x32_bf16 v[88:91], v[148:151], v[198:201], v[88:91]
	v_mfma_f32_16x16x32_bf16 v[76:79], v[140:143], v[206:209], v[76:79]
	v_mfma_f32_16x16x32_bf16 v[72:75], v[148:151], v[206:209], v[72:75]
	v_mfma_f32_16x16x32_bf16 v[124:127], v[144:147], v[176:179], v[124:127]
	v_mfma_f32_16x16x32_bf16 v[120:123], v[152:155], v[176:179], v[120:123]
	v_mfma_f32_16x16x32_bf16 v[108:111], v[144:147], v[194:197], v[108:111]
	v_mfma_f32_16x16x32_bf16 v[104:107], v[152:155], v[194:197], v[104:107]
	v_mfma_f32_16x16x32_bf16 v[92:95], v[144:147], v[202:205], v[92:95]
	v_mfma_f32_16x16x32_bf16 v[88:91], v[152:155], v[202:205], v[88:91]
	v_mfma_f32_16x16x32_bf16 v[76:79], v[144:147], v[210:213], v[76:79]
	v_mfma_f32_16x16x32_bf16 v[72:75], v[152:155], v[210:213], v[72:75]
	v_mfma_f32_16x16x32_bf16 v[116:119], v[156:159], v[172:175], v[116:119]
	v_mfma_f32_16x16x32_bf16 v[112:115], v[164:167], v[172:175], v[112:115]
	v_mfma_f32_16x16x32_bf16 v[100:103], v[156:159], v[188:191], v[100:103]
	v_mfma_f32_16x16x32_bf16 v[96:99], v[164:167], v[188:191], v[96:99]
	v_mfma_f32_16x16x32_bf16 v[84:87], v[156:159], v[198:201], v[84:87]
	v_mfma_f32_16x16x32_bf16 v[80:83], v[164:167], v[198:201], v[80:83]
	v_mfma_f32_16x16x32_bf16 v[68:71], v[156:159], v[206:209], v[68:71]
	v_mfma_f32_16x16x32_bf16 v[64:67], v[164:167], v[206:209], v[64:67]
	v_mfma_f32_16x16x32_bf16 v[116:119], v[160:163], v[176:179], v[116:119]
	v_mfma_f32_16x16x32_bf16 v[112:115], v[168:171], v[176:179], v[112:115]
	v_mfma_f32_16x16x32_bf16 v[100:103], v[160:163], v[194:197], v[100:103]
	v_mfma_f32_16x16x32_bf16 v[96:99], v[168:171], v[194:197], v[96:99]
	v_mfma_f32_16x16x32_bf16 v[84:87], v[160:163], v[202:205], v[84:87]
	v_mfma_f32_16x16x32_bf16 v[80:83], v[168:171], v[202:205], v[80:83]
	v_mfma_f32_16x16x32_bf16 v[68:71], v[160:163], v[210:213], v[68:71]
	v_mfma_f32_16x16x32_bf16 v[64:67], v[168:171], v[210:213], v[64:67]
	s_barrier
; #define PG8_STAGE(bufoff, gbase, voff) do { _Pragma("unroll") for (int _i = 0; _i < 2; ++_i) \
;         __builtin_amdgcn_global_load_lds((const unsigned*)((const char*)(gbase) + (voff)[_i]), (LAS unsigned*)(lds + (bufoff) + ldsw + _i * 8192), 16, 0, 0); } while (0)
; #define PG8_LDA(dst, b, h) do { _Pragma("unroll") for (int m = 0; m < 4; ++m) _Pragma("unroll") for (int k = 0; k < 2; ++k) dst[m][k] = *(const LAS bf16x8*)(lds + PG8_SA(b, h) + aoff + m * 2048 + k * 1024); } while (0)
; #define PG8_MMA(ai, bj, At, Bt) do { __builtin_amdgcn_s_setprio(1); _Pragma("unroll") for (int m = 0; m < 4; ++m) _Pragma("unroll") for (int n = 0; n < 2; ++n) _Pragma("unroll") for (int k = 0; k < 2; ++k) \
;         acc[ai][bj][m][n] = __builtin_amdgcn_mfma_f32_16x16x32_bf16(Bt[n][k], At[m][k], acc[ai][bj][m][n], 0, 0, 0); __builtin_amdgcn_s_setprio(0); } while (0)
; #define PG8_WAIT_V(n) asm volatile("s_waitcnt vmcnt(" #n ")" ::: "memory")
; #define PG8_WAIT_L(n) asm volatile("s_waitcnt lgkmcnt(" #n ")" ::: "memory")
; #define PG8_BAR __builtin_amdgcn_s_barrier()
; #define PG8_SCHED __builtin_amdgcn_sched_barrier(0)
; template <class Epi, class Sched, bool ALIGN_EPI = false, bool SP2 = false>
; __device__ __forceinline__ void gemm_phase(LAS unsigned char* lds, const Gemm g, const Sched S, const Epi E) {
;     ...
;             PG8_LDA(At, 1, 1); PG8_STAGE(PG8_SB(1, 0), b3, voffB); PG8_STAGE(PG8_SB(1, 1), b3 + hstep, voffB); PG8_STAGE(PG8_SA(1, 0), a3, voffA);
;             PG8_WAIT_V(8); PG8_WAIT_L(0); PG8_BAR; PG8_MMA(1, 0, At, B0); PG8_MMA(1, 1, At, B1); PG8_BAR; PG8_SCHED;
;     ...
;         if constexpr (ALIGN_EPI) { if (wr == 0) PG8_BAR; }
	s_add_i32 s38, s53, s11
	v_lshl_add_u64 v[214:215], v[214:215], 0, s[22:23]
	s_mov_b32 m0, s38
	ds_read_b128 v[172:175], v185 offset:49152
	ds_read_b128 v[176:179], v185 offset:50176
	ds_read_b128 v[188:191], v185 offset:51200
	ds_read_b128 v[194:197], v185 offset:52224
	ds_read_b128 v[198:201], v185 offset:53248
	ds_read_b128 v[202:205], v185 offset:54272
	ds_read_b128 v[206:209], v185 offset:55296
	ds_read_b128 v[210:213], v185 offset:56320
	global_load_lds_dwordx4 v[214:215], off
	s_add_i32 m0, s38, 0x2000
	s_add_u32 s36, s36, 0x158080
	v_lshl_add_u64 v[214:215], v[216:217], 0, s[22:23]
	s_addc_u32 s37, s37, 0
	s_add_i32 s38, s54, s11
	global_load_lds_dwordx4 v[214:215], off
	v_lshl_add_u64 v[214:215], s[36:37], 0, v[128:129]
	s_mov_b32 m0, s38
	s_nop 0
	global_load_lds_dwordx4 v[214:215], off
	v_lshl_add_u64 v[214:215], s[36:37], 0, v[130:131]
	s_add_i32 m0, s38, 0x2000
	s_nop 0
	global_load_lds_dwordx4 v[214:215], off
	v_lshl_add_u64 v[214:215], v[218:219], 0, s[22:23]
	s_mov_b32 m0, s41
	s_nop 0
	global_load_lds_dwordx4 v[214:215], off
	v_lshl_add_u64 v[214:215], v[220:221], 0, s[22:23]
	s_mov_b32 m0, s42
	s_nop 0
	global_load_lds_dwordx4 v[214:215], off
	s_waitcnt vmcnt(8)
	s_waitcnt lgkmcnt(0)
	s_barrier
	s_waitcnt lgkmcnt(0)
	v_mfma_f32_16x16x32_bf16 v[60:63], v[140:143], v[172:175], v[60:63]
	v_mfma_f32_16x16x32_bf16 v[56:59], v[148:151], v[172:175], v[56:59]
	v_mfma_f32_16x16x32_bf16 v[44:47], v[140:143], v[188:191], v[44:47]
	v_mfma_f32_16x16x32_bf16 v[40:43], v[148:151], v[188:191], v[40:43]
	v_mfma_f32_16x16x32_bf16 v[28:31], v[140:143], v[198:201], v[28:31]
	v_mfma_f32_16x16x32_bf16 v[24:27], v[148:151], v[198:201], v[24:27]
	v_mfma_f32_16x16x32_bf16 v[12:15], v[140:143], v[206:209], v[12:15]
	v_mfma_f32_16x16x32_bf16 v[8:11], v[148:151], v[206:209], v[8:11]
	v_mfma_f32_16x16x32_bf16 v[60:63], v[144:147], v[176:179], v[60:63]
	v_mfma_f32_16x16x32_bf16 v[56:59], v[152:155], v[176:179], v[56:59]
	v_mfma_f32_16x16x32_bf16 v[44:47], v[144:147], v[194:197], v[44:47]
	v_mfma_f32_16x16x32_bf16 v[40:43], v[152:155], v[194:197], v[40:43]
	v_mfma_f32_16x16x32_bf16 v[28:31], v[144:147], v[202:205], v[28:31]
	v_mfma_f32_16x16x32_bf16 v[24:27], v[152:155], v[202:205], v[24:27]
	v_mfma_f32_16x16x32_bf16 v[12:15], v[144:147], v[210:213], v[12:15]
	v_mfma_f32_16x16x32_bf16 v[8:11], v[152:155], v[210:213], v[8:11]
	v_mfma_f32_16x16x32_bf16 v[52:55], v[156:159], v[172:175], v[52:55]
	v_mfma_f32_16x16x32_bf16 v[48:51], v[164:167], v[172:175], v[48:51]
	v_mfma_f32_16x16x32_bf16 v[36:39], v[156:159], v[188:191], v[36:39]
	v_mfma_f32_16x16x32_bf16 v[32:35], v[164:167], v[188:191], v[32:35]
	v_mfma_f32_16x16x32_bf16 v[20:23], v[156:159], v[198:201], v[20:23]
	v_mfma_f32_16x16x32_bf16 v[16:19], v[164:167], v[198:201], v[16:19]
	v_mfma_f32_16x16x32_bf16 v[4:7], v[156:159], v[206:209], v[4:7]
	v_mfma_f32_16x16x32_bf16 v[0:3], v[164:167], v[206:209], v[0:3]
	v_mfma_f32_16x16x32_bf16 v[52:55], v[160:163], v[176:179], v[52:55]
	v_mfma_f32_16x16x32_bf16 v[48:51], v[168:171], v[176:179], v[48:51]
	v_mfma_f32_16x16x32_bf16 v[36:39], v[160:163], v[194:197], v[36:39]
	v_mfma_f32_16x16x32_bf16 v[32:35], v[168:171], v[194:197], v[32:35]
	v_mfma_f32_16x16x32_bf16 v[20:23], v[160:163], v[202:205], v[20:23]
	v_mfma_f32_16x16x32_bf16 v[16:19], v[168:171], v[202:205], v[16:19]
	v_mfma_f32_16x16x32_bf16 v[4:7], v[160:163], v[210:213], v[4:7]
	v_mfma_f32_16x16x32_bf16 v[0:3], v[168:171], v[210:213], v[0:3]
	s_barrier
	s_add_i32 s52, s52, 2
	s_add_u32 s34, s34, 0x100
	s_addc_u32 s35, s35, 0
	s_add_u32 s50, s50, 0x100
	s_addc_u32 s51, s51, 0
	s_cmpk_gt_u32 s52, 0x53
	s_cbranch_scc0 .LBB0_733
	s_and_b64 vcc, exec, s[24:25]
	s_cbranch_vccz .LBB0_736
	s_barrier

; #define PG8_STAGE(bufoff, gbase, voff) do { _Pragma("unroll") for (int _i = 0; _i < 2; ++_i) \
;         __builtin_amdgcn_global_load_lds((const unsigned*)((const char*)(gbase) + (voff)[_i]), (LAS unsigned*)(lds + (bufoff) + ldsw + _i * 8192), 16, 0, 0); } while (0)
; #define PG8_LDA(dst, b, h) do { _Pragma("unroll") for (int m = 0; m < 4; ++m) _Pragma("unroll") for (int k = 0; k < 2; ++k) dst[m][k] = *(const LAS bf16x8*)(lds + PG8_SA(b, h) + aoff + m * 2048 + k * 1024); } while (0)
; #define PG8_LDB(dst, b, h) do { _Pragma("unroll") for (int n = 0; n < 2; ++n) _Pragma("unroll") for (int k = 0; k < 2; ++k) dst[n][k] = *(const LAS bf16x8*)(lds + PG8_SB(b, h) + boff + n * 2048 + k * 1024); } while (0)
; #define PG8_WAIT_V(n) asm volatile("s_waitcnt vmcnt(" #n ")" ::: "memory")
; #define PG8_WAIT_L(n) asm volatile("s_waitcnt lgkmcnt(" #n ")" ::: "memory")
; #define PG8_BAR __builtin_amdgcn_s_barrier()
; #define PG8_SCHED __builtin_amdgcn_sched_barrier(0)
; template <class Epi, class Sched, bool ALIGN_EPI = false, bool SP2 = false>
; __device__ __forceinline__ void gemm_phase(LAS unsigned char* lds, const Gemm g, const Sched S, const Epi E) {
;     ...
;         const char* nA = has_next ? (const char*)g.A + (size_t)nxt.pm * tstep : cA; const char* nB = has_next ? (const char*)g.Bt + (size_t)nxt.pn * tstep : cB;
;         for (int t = 0; t < nt; t += 2) {
;             const bool last = (t == nt - 2);
;             const char* a1 = cA + (size_t)(t + 1) * kstep;
;             const char* a2 = last ? nA : cA + (size_t)(t + 2) * kstep; const char* b2 = last ? nB : cB + (size_t)(t + 2) * kstep;
;             const char* a3 = a2 + kstep; const char* b3 = b2 + kstep;
;             if (last && has_next) S.a_ready(nxt);
;             if (last) E.prefetch(cur, wr, fr, pre);
;             if constexpr (SP2) {
;             PG8_LDB(B0, 0, 0); PG8_LDB(B1, 0, 1); PG8_SCHED; PG8_LDA(At, 0, 0); PG8_STAGE(PG8_SA(1, 1), a1 + hstep, voffA);
;             PG8_WAIT_V(8); PG8_WAIT_L(0); PG8_BAR; PG8_MMA(0, 0, At, B0); PG8_MMA(0, 1, At, B1); PG8_BAR; PG8_SCHED;
;             PG8_LDA(At, 0, 1); PG8_STAGE(PG8_SB(0, 0), b2, voffB); PG8_STAGE(PG8_SB(0, 1), b2 + hstep, voffB); PG8_STAGE(PG8_SA(0, 0), a2, voffA);
;             PG8_WAIT_V(8); PG8_WAIT_L(0); PG8_BAR; PG8_MMA(1, 0, At, B0); PG8_MMA(1, 1, At, B1); PG8_BAR; PG8_SCHED;
.LBB0_996:
	v_add_u32_e32 v156, s49, v214
	v_add_u32_e32 v172, s50, v214
	ds_read_b128 v[144:147], v156
	ds_read_b128 v[148:151], v156 offset:1024
	ds_read_b128 v[152:155], v156 offset:2048
	ds_read_b128 v[156:159], v156 offset:3072
	ds_read_b128 v[160:163], v172
	ds_read_b128 v[164:167], v172 offset:1024
	ds_read_b128 v[168:171], v172 offset:2048
	ds_read_b128 v[172:175], v172 offset:3072
	s_add_u32 s44, s4, 0xfff80080
	s_addc_u32 s45, s5, -1
	s_and_b64 s[42:43], s[42:43], exec
	s_cselect_b32 s45, s35, s45
	s_cselect_b32 s44, s52, s44
	s_cselect_b32 s43, s53, s56
	s_cselect_b32 s42, s54, s55
	v_lshl_add_u64 v[246:247], s[4:5], 0, v[204:205]
	s_add_i32 m0, s9, 0xc000
	ds_read_b128 v[176:179], v218
	ds_read_b128 v[180:183], v218 offset:1024
	ds_read_b128 v[184:187], v218 offset:2048
	ds_read_b128 v[188:191], v218 offset:3072
	ds_read_b128 v[230:233], v218 offset:4096
	ds_read_b128 v[234:237], v218 offset:5120
	ds_read_b128 v[238:241], v218 offset:6144
	ds_read_b128 v[242:245], v218 offset:7168
	global_load_lds_dwordx4 v[246:247], off
	v_lshl_add_u64 v[246:247], s[4:5], 0, v[206:207]
	s_add_i32 m0, s9, 0xe000
	s_nop 0
	global_load_lds_dwordx4 v[246:247], off
	s_waitcnt vmcnt(8)
	s_waitcnt lgkmcnt(0)
	s_barrier
	s_waitcnt lgkmcnt(0)
	v_mfma_f32_16x16x32_bf16 v[124:127], v[144:147], v[176:179], v[124:127]
	v_mfma_f32_16x16x32_bf16 v[120:123], v[152:155], v[176:179], v[120:123]
	v_mfma_f32_16x16x32_bf16 v[108:111], v[144:147], v[184:187], v[108:111]
	v_mfma_f32_16x16x32_bf16 v[104:107], v[152:155], v[184:187], v[104:107]
	v_mfma_f32_16x16x32_bf16 v[92:95], v[144:147], v[230:233], v[92:95]
	v_mfma_f32_16x16x32_bf16 v[88:91], v[152:155], v[230:233], v[88:91]
	v_mfma_f32_16x16x32_bf16 v[76:79], v[144:147], v[238:241], v[76:79]
	v_mfma_f32_16x16x32_bf16 v[72:75], v[152:155], v[238:241], v[72:75]
	v_mfma_f32_16x16x32_bf16 v[124:127], v[148:151], v[180:183], v[124:127]
	v_mfma_f32_16x16x32_bf16 v[120:123], v[156:159], v[180:183], v[120:123]
	v_mfma_f32_16x16x32_bf16 v[108:111], v[148:151], v[188:191], v[108:111]
	v_mfma_f32_16x16x32_bf16 v[104:107], v[156:159], v[188:191], v[104:107]
	v_mfma_f32_16x16x32_bf16 v[92:95], v[148:151], v[234:237], v[92:95]
	v_mfma_f32_16x16x32_bf16 v[88:91], v[156:159], v[234:237], v[88:91]
	v_mfma_f32_16x16x32_bf16 v[76:79], v[148:151], v[242:245], v[76:79]
	v_mfma_f32_16x16x32_bf16 v[72:75], v[156:159], v[242:245], v[72:75]
	v_mfma_f32_16x16x32_bf16 v[116:119], v[160:163], v[176:179], v[116:119]
	v_mfma_f32_16x16x32_bf16 v[112:115], v[168:171], v[176:179], v[112:115]
	v_mfma_f32_16x16x32_bf16 v[100:103], v[160:163], v[184:187], v[100:103]
	v_mfma_f32_16x16x32_bf16 v[96:99], v[168:171], v[184:187], v[96:99]
	v_mfma_f32_16x16x32_bf16 v[84:87], v[160:163], v[230:233], v[84:87]
	v_mfma_f32_16x16x32_bf16 v[80:83], v[168:171], v[230:233], v[80:83]
	v_mfma_f32_16x16x32_bf16 v[68:71], v[160:163], v[238:241], v[68:71]
	v_mfma_f32_16x16x32_bf16 v[64:67], v[168:171], v[238:241], v[64:67]
	v_mfma_f32_16x16x32_bf16 v[116:119], v[164:167], v[180:183], v[116:119]
	v_mfma_f32_16x16x32_bf16 v[112:115], v[172:175], v[180:183], v[112:115]
	v_mfma_f32_16x16x32_bf16 v[100:103], v[164:167], v[188:191], v[100:103]
	v_mfma_f32_16x16x32_bf16 v[96:99], v[172:175], v[188:191], v[96:99]
	v_mfma_f32_16x16x32_bf16 v[84:87], v[164:167], v[234:237], v[84:87]
	v_mfma_f32_16x16x32_bf16 v[80:83], v[172:175], v[234:237], v[80:83]
	v_mfma_f32_16x16x32_bf16 v[68:71], v[164:167], v[242:245], v[68:71]
	v_mfma_f32_16x16x32_bf16 v[64:67], v[172:175], v[242:245], v[64:67]
	s_barrier
	s_add_i32 s58, s49, s8
	v_lshl_add_u64 v[246:247], s[42:43], 0, v[194:195]
	s_mov_b32 m0, s58
	ds_read_b128 v[176:179], v218 offset:16384
	ds_read_b128 v[180:183], v218 offset:17408
	ds_read_b128 v[184:187], v218 offset:18432
	ds_read_b128 v[188:191], v218 offset:19456
	ds_read_b128 v[230:233], v218 offset:20480
	ds_read_b128 v[234:237], v218 offset:21504
	ds_read_b128 v[238:241], v218 offset:22528
	ds_read_b128 v[242:245], v218 offset:23552
	global_load_lds_dwordx4 v[246:247], off
	s_add_i32 m0, s58, 0x2000
	s_add_u32 s58, s42, 0x80000
	v_lshl_add_u64 v[248:249], s[42:43], 0, v[196:197]
	s_addc_u32 s59, s43, 0
	s_add_i32 s60, s50, s8
	global_load_lds_dwordx4 v[248:249], off
	v_lshl_add_u64 v[250:251], s[58:59], 0, v[194:195]
	s_mov_b32 m0, s60
	v_lshl_add_u64 v[252:253], s[44:45], 0, v[196:197]
	global_load_lds_dwordx4 v[250:251], off
	v_lshl_add_u64 v[250:251], s[58:59], 0, v[196:197]
	s_add_i32 m0, s60, 0x2000
	s_nop 0
	global_load_lds_dwordx4 v[250:251], off
	v_lshl_add_u64 v[250:251], s[44:45], 0, v[194:195]
	s_mov_b32 m0, s9
	s_nop 0
	global_load_lds_dwordx4 v[250:251], off
	s_mov_b32 m0, s11
	s_nop 0
	global_load_lds_dwordx4 v[252:253], off
	s_waitcnt vmcnt(8)
	s_waitcnt lgkmcnt(0)
	s_barrier
; #define PG8_STAGE(bufoff, gbase, voff) do { _Pragma("unroll") for (int _i = 0; _i < 2; ++_i) \
;         __builtin_amdgcn_global_load_lds((const unsigned*)((const char*)(gbase) + (voff)[_i]), (LAS unsigned*)(lds + (bufoff) + ldsw + _i * 8192), 16, 0, 0); } while (0)
; #define PG8_LDA(dst, b, h) do { _Pragma("unroll") for (int m = 0; m < 4; ++m) _Pragma("unroll") for (int k = 0; k < 2; ++k) dst[m][k] = *(const LAS bf16x8*)(lds + PG8_SA(b, h) + aoff + m * 2048 + k * 1024); } while (0)
; #define PG8_LDB(dst, b, h) do { _Pragma("unroll") for (int n = 0; n < 2; ++n) _Pragma("unroll") for (int k = 0; k < 2; ++k) dst[n][k] = *(const LAS bf16x8*)(lds + PG8_SB(b, h) + boff + n * 2048 + k * 1024); } while (0)
; #define PG8_MMA(ai, bj, At, Bt) do { __builtin_amdgcn_s_setprio(1); _Pragma("unroll") for (int m = 0; m < 4; ++m) _Pragma("unroll") for (int n = 0; n < 2; ++n) _Pragma("unroll") for (int k = 0; k < 2; ++k) \
;         acc[ai][bj][m][n] = __builtin_amdgcn_mfma_f32_16x16x32_bf16(Bt[n][k], At[m][k], acc[ai][bj][m][n], 0, 0, 0); __builtin_amdgcn_s_setprio(0); } while (0)
; #define PG8_WAIT_V(n) asm volatile("s_waitcnt vmcnt(" #n ")" ::: "memory")
; #define PG8_WAIT_L(n) asm volatile("s_waitcnt lgkmcnt(" #n ")" ::: "memory")
; #define PG8_BAR __builtin_amdgcn_s_barrier()
; #define PG8_SCHED __builtin_amdgcn_sched_barrier(0)
; template <class Epi, class Sched, bool ALIGN_EPI = false, bool SP2 = false>
; __device__ __forceinline__ void gemm_phase(LAS unsigned char* lds, const Gemm g, const Sched S, const Epi E) {
;     ...
;             PG8_WAIT_V(8); PG8_WAIT_L(0); PG8_BAR; PG8_MMA(1, 0, At, B0); PG8_MMA(1, 1, At, B1); PG8_BAR; PG8_SCHED;
;             PG8_LDB(B0, 1, 0); PG8_LDB(B1, 1, 1); PG8_SCHED; PG8_LDA(At, 1, 0); PG8_STAGE(PG8_SA(0, 1), a2 + hstep, voffA);
;             PG8_WAIT_V(8); PG8_WAIT_L(0); PG8_BAR; PG8_MMA(0, 0, At, B0); PG8_MMA(0, 1, At, B1); PG8_BAR; PG8_SCHED;
	s_waitcnt lgkmcnt(0)
	v_mfma_f32_16x16x32_bf16 v[60:63], v[144:147], v[176:179], v[60:63]
	v_mfma_f32_16x16x32_bf16 v[56:59], v[152:155], v[176:179], v[56:59]
	v_mfma_f32_16x16x32_bf16 v[44:47], v[144:147], v[184:187], v[44:47]
	v_mfma_f32_16x16x32_bf16 v[40:43], v[152:155], v[184:187], v[40:43]
	v_mfma_f32_16x16x32_bf16 v[28:31], v[144:147], v[230:233], v[28:31]
	v_mfma_f32_16x16x32_bf16 v[24:27], v[152:155], v[230:233], v[24:27]
	v_mfma_f32_16x16x32_bf16 v[12:15], v[144:147], v[238:241], v[12:15]
	v_mfma_f32_16x16x32_bf16 v[8:11], v[152:155], v[238:241], v[8:11]
	v_mfma_f32_16x16x32_bf16 v[60:63], v[148:151], v[180:183], v[60:63]
	v_mfma_f32_16x16x32_bf16 v[56:59], v[156:159], v[180:183], v[56:59]
	v_mfma_f32_16x16x32_bf16 v[44:47], v[148:151], v[188:191], v[44:47]
	v_mfma_f32_16x16x32_bf16 v[40:43], v[156:159], v[188:191], v[40:43]
	v_mfma_f32_16x16x32_bf16 v[28:31], v[148:151], v[234:237], v[28:31]
	v_mfma_f32_16x16x32_bf16 v[24:27], v[156:159], v[234:237], v[24:27]
	v_mfma_f32_16x16x32_bf16 v[12:15], v[148:151], v[242:245], v[12:15]
	v_mfma_f32_16x16x32_bf16 v[8:11], v[156:159], v[242:245], v[8:11]
	v_mfma_f32_16x16x32_bf16 v[52:55], v[160:163], v[176:179], v[52:55]
	v_mfma_f32_16x16x32_bf16 v[48:51], v[168:171], v[176:179], v[48:51]
	v_mfma_f32_16x16x32_bf16 v[36:39], v[160:163], v[184:187], v[36:39]
	v_mfma_f32_16x16x32_bf16 v[32:35], v[168:171], v[184:187], v[32:35]
	v_mfma_f32_16x16x32_bf16 v[20:23], v[160:163], v[230:233], v[20:23]
	v_mfma_f32_16x16x32_bf16 v[16:19], v[168:171], v[230:233], v[16:19]
	v_mfma_f32_16x16x32_bf16 v[4:7], v[160:163], v[238:241], v[4:7]
	v_mfma_f32_16x16x32_bf16 v[0:3], v[168:171], v[238:241], v[0:3]
	v_mfma_f32_16x16x32_bf16 v[52:55], v[164:167], v[180:183], v[52:55]
	v_mfma_f32_16x16x32_bf16 v[48:51], v[172:175], v[180:183], v[48:51]
	v_mfma_f32_16x16x32_bf16 v[36:39], v[164:167], v[188:191], v[36:39]
	v_mfma_f32_16x16x32_bf16 v[32:35], v[172:175], v[188:191], v[32:35]
	v_mfma_f32_16x16x32_bf16 v[20:23], v[164:167], v[234:237], v[20:23]
	v_mfma_f32_16x16x32_bf16 v[16:19], v[172:175], v[234:237], v[16:19]
	v_mfma_f32_16x16x32_bf16 v[4:7], v[164:167], v[242:245], v[4:7]
	v_mfma_f32_16x16x32_bf16 v[0:3], v[172:175], v[242:245], v[0:3]
	s_barrier
	s_add_i32 s58, 0, 0x18000
	s_add_i32 s59, 0, 0x1c000
	v_add_u32_e32 v156, s58, v214
	v_add_u32_e32 v172, s59, v214
	ds_read_b128 v[144:147], v156
	ds_read_b128 v[148:151], v156 offset:1024
	ds_read_b128 v[152:155], v156 offset:2048
	ds_read_b128 v[156:159], v156 offset:3072
	ds_read_b128 v[160:163], v172
	ds_read_b128 v[164:167], v172 offset:1024
	ds_read_b128 v[168:171], v172 offset:2048
	ds_read_b128 v[172:175], v172 offset:3072
	s_add_u32 s44, s44, 0x80000
	s_addc_u32 s45, s45, 0
	s_mov_b32 m0, s28
	v_lshl_add_u64 v[208:209], s[44:45], 0, v[194:195]
	ds_read_b128 v[176:179], v218 offset:32768
	ds_read_b128 v[180:183], v218 offset:33792
	ds_read_b128 v[184:187], v218 offset:34816
	ds_read_b128 v[188:191], v218 offset:35840
	ds_read_b128 v[230:233], v218 offset:36864
	ds_read_b128 v[234:237], v218 offset:37888
	ds_read_b128 v[238:241], v218 offset:38912
	ds_read_b128 v[242:245], v218 offset:39936
	global_load_lds_dwordx4 v[208:209], off
	v_lshl_add_u64 v[208:209], s[44:45], 0, v[196:197]
	s_mov_b32 m0, s29
	s_nop 0
	global_load_lds_dwordx4 v[208:209], off
	s_waitcnt vmcnt(8)
	s_waitcnt lgkmcnt(0)
	s_barrier
	s_waitcnt lgkmcnt(0)
	v_mfma_f32_16x16x32_bf16 v[124:127], v[144:147], v[176:179], v[124:127]
	v_mfma_f32_16x16x32_bf16 v[120:123], v[152:155], v[176:179], v[120:123]
	v_mfma_f32_16x16x32_bf16 v[108:111], v[144:147], v[184:187], v[108:111]
	v_mfma_f32_16x16x32_bf16 v[104:107], v[152:155], v[184:187], v[104:107]
	v_mfma_f32_16x16x32_bf16 v[92:95], v[144:147], v[230:233], v[92:95]
	v_mfma_f32_16x16x32_bf16 v[88:91], v[152:155], v[230:233], v[88:91]
	v_mfma_f32_16x16x32_bf16 v[76:79], v[144:147], v[238:241], v[76:79]
	v_mfma_f32_16x16x32_bf16 v[72:75], v[152:155], v[238:241], v[72:75]
	v_mfma_f32_16x16x32_bf16 v[124:127], v[148:151], v[180:183], v[124:127]
	v_mfma_f32_16x16x32_bf16 v[120:123], v[156:159], v[180:183], v[120:123]
	v_mfma_f32_16x16x32_bf16 v[108:111], v[148:151], v[188:191], v[108:111]
	v_mfma_f32_16x16x32_bf16 v[104:107], v[156:159], v[188:191], v[104:107]
	v_mfma_f32_16x16x32_bf16 v[92:95], v[148:151], v[234:237], v[92:95]
	v_mfma_f32_16x16x32_bf16 v[88:91], v[156:159], v[234:237], v[88:91]
	v_mfma_f32_16x16x32_bf16 v[76:79], v[148:151], v[242:245], v[76:79]
	v_mfma_f32_16x16x32_bf16 v[72:75], v[156:159], v[242:245], v[72:75]
	v_mfma_f32_16x16x32_bf16 v[116:119], v[160:163], v[176:179], v[116:119]
	v_mfma_f32_16x16x32_bf16 v[112:115], v[168:171], v[176:179], v[112:115]
	v_mfma_f32_16x16x32_bf16 v[100:103], v[160:163], v[184:187], v[100:103]
	v_mfma_f32_16x16x32_bf16 v[96:99], v[168:171], v[184:187], v[96:99]
	v_mfma_f32_16x16x32_bf16 v[84:87], v[160:163], v[230:233], v[84:87]
	v_mfma_f32_16x16x32_bf16 v[80:83], v[168:171], v[230:233], v[80:83]
	v_mfma_f32_16x16x32_bf16 v[68:71], v[160:163], v[238:241], v[68:71]
	v_mfma_f32_16x16x32_bf16 v[64:67], v[168:171], v[238:241], v[64:67]
	v_mfma_f32_16x16x32_bf16 v[116:119], v[164:167], v[180:183], v[116:119]
	v_mfma_f32_16x16x32_bf16 v[112:115], v[172:175], v[180:183], v[112:115]
	v_mfma_f32_16x16x32_bf16 v[100:103], v[164:167], v[188:191], v[100:103]
	v_mfma_f32_16x16x32_bf16 v[96:99], v[172:175], v[188:191], v[96:99]
	v_mfma_f32_16x16x32_bf16 v[84:87], v[164:167], v[234:237], v[84:87]
	v_mfma_f32_16x16x32_bf16 v[80:83], v[172:175], v[234:237], v[80:83]
	v_mfma_f32_16x16x32_bf16 v[68:71], v[164:167], v[242:245], v[68:71]
	v_mfma_f32_16x16x32_bf16 v[64:67], v[172:175], v[242:245], v[64:67]
	s_barrier
; #define PG8_STAGE(bufoff, gbase, voff) do { _Pragma("unroll") for (int _i = 0; _i < 2; ++_i) \
;         __builtin_amdgcn_global_load_lds((const unsigned*)((const char*)(gbase) + (voff)[_i]), (LAS unsigned*)(lds + (bufoff) + ldsw + _i * 8192), 16, 0, 0); } while (0)
; #define PG8_LDA(dst, b, h) do { _Pragma("unroll") for (int m = 0; m < 4; ++m) _Pragma("unroll") for (int k = 0; k < 2; ++k) dst[m][k] = *(const LAS bf16x8*)(lds + PG8_SA(b, h) + aoff + m * 2048 + k * 1024); } while (0)
; #define PG8_MMA(ai, bj, At, Bt) do { __builtin_amdgcn_s_setprio(1); _Pragma("unroll") for (int m = 0; m < 4; ++m) _Pragma("unroll") for (int n = 0; n < 2; ++n) _Pragma("unroll") for (int k = 0; k < 2; ++k) \
;         acc[ai][bj][m][n] = __builtin_amdgcn_mfma_f32_16x16x32_bf16(Bt[n][k], At[m][k], acc[ai][bj][m][n], 0, 0, 0); __builtin_amdgcn_s_setprio(0); } while (0)
; #define PG8_WAIT_V(n) asm volatile("s_waitcnt vmcnt(" #n ")" ::: "memory")
; #define PG8_WAIT_L(n) asm volatile("s_waitcnt lgkmcnt(" #n ")" ::: "memory")
; #define PG8_BAR __builtin_amdgcn_s_barrier()
; #define PG8_SCHED __builtin_amdgcn_sched_barrier(0)
; template <class Epi, class Sched, bool ALIGN_EPI = false, bool SP2 = false>
; __device__ __forceinline__ void gemm_phase(LAS unsigned char* lds, const Gemm g, const Sched S, const Epi E) {
;     ...
;         for (int t = 0; t < nt; t += 2) {
;             const bool last = (t == nt - 2);
;             const char* a1 = cA + (size_t)(t + 1) * kstep;
;             const char* a2 = last ? nA : cA + (size_t)(t + 2) * kstep; const char* b2 = last ? nB : cB + (size_t)(t + 2) * kstep;
;             const char* a3 = a2 + kstep; const char* b3 = b2 + kstep;
;     ...
;             PG8_LDA(At, 1, 1); PG8_STAGE(PG8_SB(1, 0), b3, voffB); PG8_STAGE(PG8_SB(1, 1), b3 + hstep, voffB); PG8_STAGE(PG8_SA(1, 0), a3, voffA);
;             PG8_WAIT_V(8); PG8_WAIT_L(0); PG8_BAR; PG8_MMA(1, 0, At, B0); PG8_MMA(1, 1, At, B1); PG8_BAR; PG8_SCHED;
	s_add_i32 s44, s58, s8
	v_lshl_add_u64 v[208:209], v[246:247], 0, s[20:21]
	s_mov_b32 m0, s44
	ds_read_b128 v[176:179], v218 offset:49152
	ds_read_b128 v[180:183], v218 offset:50176
	ds_read_b128 v[184:187], v218 offset:51200
	ds_read_b128 v[188:191], v218 offset:52224
	ds_read_b128 v[230:233], v218 offset:53248
	ds_read_b128 v[234:237], v218 offset:54272
	ds_read_b128 v[238:241], v218 offset:55296
	ds_read_b128 v[242:245], v218 offset:56320
	global_load_lds_dwordx4 v[208:209], off
	s_add_i32 m0, s44, 0x2000
	s_add_u32 s42, s42, 0x80080
	v_lshl_add_u64 v[208:209], v[248:249], 0, s[20:21]
	s_addc_u32 s43, s43, 0
	s_add_i32 s44, s59, s8
	global_load_lds_dwordx4 v[208:209], off
	v_lshl_add_u64 v[208:209], s[42:43], 0, v[194:195]
	s_mov_b32 m0, s44
	s_nop 0
	global_load_lds_dwordx4 v[208:209], off
	v_lshl_add_u64 v[208:209], s[42:43], 0, v[196:197]
	s_add_i32 m0, s44, 0x2000
	s_nop 0
	global_load_lds_dwordx4 v[208:209], off
	v_lshl_add_u64 v[208:209], v[250:251], 0, s[20:21]
	s_mov_b32 m0, s41
	s_nop 0
	global_load_lds_dwordx4 v[208:209], off
	v_lshl_add_u64 v[208:209], v[252:253], 0, s[20:21]
	s_mov_b32 m0, s46
	s_nop 0
	global_load_lds_dwordx4 v[208:209], off
	s_waitcnt vmcnt(8)
	s_waitcnt lgkmcnt(0)
	s_barrier
	s_waitcnt lgkmcnt(0)
	v_mfma_f32_16x16x32_bf16 v[60:63], v[144:147], v[176:179], v[60:63]
	v_mfma_f32_16x16x32_bf16 v[56:59], v[152:155], v[176:179], v[56:59]
	v_mfma_f32_16x16x32_bf16 v[44:47], v[144:147], v[184:187], v[44:47]
	v_mfma_f32_16x16x32_bf16 v[40:43], v[152:155], v[184:187], v[40:43]
	v_mfma_f32_16x16x32_bf16 v[28:31], v[144:147], v[230:233], v[28:31]
	v_mfma_f32_16x16x32_bf16 v[24:27], v[152:155], v[230:233], v[24:27]
	v_mfma_f32_16x16x32_bf16 v[12:15], v[144:147], v[238:241], v[12:15]
	v_mfma_f32_16x16x32_bf16 v[8:11], v[152:155], v[238:241], v[8:11]
	v_mfma_f32_16x16x32_bf16 v[60:63], v[148:151], v[180:183], v[60:63]
	v_mfma_f32_16x16x32_bf16 v[56:59], v[156:159], v[180:183], v[56:59]
	v_mfma_f32_16x16x32_bf16 v[44:47], v[148:151], v[188:191], v[44:47]
	v_mfma_f32_16x16x32_bf16 v[40:43], v[156:159], v[188:191], v[40:43]
	v_mfma_f32_16x16x32_bf16 v[28:31], v[148:151], v[234:237], v[28:31]
	v_mfma_f32_16x16x32_bf16 v[24:27], v[156:159], v[234:237], v[24:27]
	v_mfma_f32_16x16x32_bf16 v[12:15], v[148:151], v[242:245], v[12:15]
	v_mfma_f32_16x16x32_bf16 v[8:11], v[156:159], v[242:245], v[8:11]
	v_mfma_f32_16x16x32_bf16 v[52:55], v[160:163], v[176:179], v[52:55]
	v_mfma_f32_16x16x32_bf16 v[48:51], v[168:171], v[176:179], v[48:51]
	v_mfma_f32_16x16x32_bf16 v[36:39], v[160:163], v[184:187], v[36:39]
	v_mfma_f32_16x16x32_bf16 v[32:35], v[168:171], v[184:187], v[32:35]
	v_mfma_f32_16x16x32_bf16 v[20:23], v[160:163], v[230:233], v[20:23]
	v_mfma_f32_16x16x32_bf16 v[16:19], v[168:171], v[230:233], v[16:19]
	v_mfma_f32_16x16x32_bf16 v[4:7], v[160:163], v[238:241], v[4:7]
	v_mfma_f32_16x16x32_bf16 v[0:3], v[168:171], v[238:241], v[0:3]
	v_mfma_f32_16x16x32_bf16 v[52:55], v[164:167], v[180:183], v[52:55]
	v_mfma_f32_16x16x32_bf16 v[48:51], v[172:175], v[180:183], v[48:51]
	v_mfma_f32_16x16x32_bf16 v[36:39], v[164:167], v[188:191], v[36:39]
	v_mfma_f32_16x16x32_bf16 v[32:35], v[172:175], v[188:191], v[32:35]
	v_mfma_f32_16x16x32_bf16 v[20:23], v[164:167], v[234:237], v[20:23]
	v_mfma_f32_16x16x32_bf16 v[16:19], v[172:175], v[234:237], v[16:19]
	v_mfma_f32_16x16x32_bf16 v[4:7], v[164:167], v[242:245], v[4:7]
	v_mfma_f32_16x16x32_bf16 v[0:3], v[172:175], v[242:245], v[0:3]
	s_barrier
	s_add_i32 s57, s57, 2
	s_add_u32 s4, s4, 0x100
	s_addc_u32 s5, s5, 0
	s_add_u32 s55, s55, 0x100
	s_addc_u32 s56, s56, 0
	s_cmp_gt_u32 s57, 29
	s_cbranch_scc1 .LBB0_999

; #define PG8_STAGE(bufoff, gbase, voff) do { _Pragma("unroll") for (int _i = 0; _i < 2; ++_i) \
;         __builtin_amdgcn_global_load_lds((const unsigned*)((const char*)(gbase) + (voff)[_i]), (LAS unsigned*)(lds + (bufoff) + ldsw + _i * 8192), 16, 0, 0); } while (0)
; #define PG8_LDA(dst, b, h) do { _Pragma("unroll") for (int m = 0; m < 4; ++m) _Pragma("unroll") for (int k = 0; k < 2; ++k) dst[m][k] = *(const LAS bf16x8*)(lds + PG8_SA(b, h) + aoff + m * 2048 + k * 1024); } while (0)
; #define PG8_LDB(dst, b, h) do { _Pragma("unroll") for (int n = 0; n < 2; ++n) _Pragma("unroll") for (int k = 0; k < 2; ++k) dst[n][k] = *(const LAS bf16x8*)(lds + PG8_SB(b, h) + boff + n * 2048 + k * 1024); } while (0)
; #define PG8_WAIT_V(n) asm volatile("s_waitcnt vmcnt(" #n ")" ::: "memory")
; #define PG8_WAIT_L(n) asm volatile("s_waitcnt lgkmcnt(" #n ")" ::: "memory")
; #define PG8_BAR __builtin_amdgcn_s_barrier()
; #define PG8_SCHED __builtin_amdgcn_sched_barrier(0)
; template <class Epi, class Sched, bool ALIGN_EPI = false, bool SP2 = false>
; __device__ __forceinline__ void gemm_phase(LAS unsigned char* lds, const Gemm g, const Sched S, const Epi E) {
;     ...
;         const char* nA = has_next ? (const char*)g.A + (size_t)nxt.pm * tstep : cA; const char* nB = has_next ? (const char*)g.Bt + (size_t)nxt.pn * tstep : cB;
;         for (int t = 0; t < nt; t += 2) {
;             const bool last = (t == nt - 2);
;             const char* a1 = cA + (size_t)(t + 1) * kstep;
;             const char* a2 = last ? nA : cA + (size_t)(t + 2) * kstep; const char* b2 = last ? nB : cB + (size_t)(t + 2) * kstep;
;             const char* a3 = a2 + kstep; const char* b3 = b2 + kstep;
;             if (last && has_next) S.a_ready(nxt);
;             if (last) E.prefetch(cur, wr, fr, pre);
;             if constexpr (SP2) {
;             PG8_LDB(B0, 0, 0); PG8_LDB(B1, 0, 1); PG8_SCHED; PG8_LDA(At, 0, 0); PG8_STAGE(PG8_SA(1, 1), a1 + hstep, voffA);
;             PG8_WAIT_V(8); PG8_WAIT_L(0); PG8_BAR; PG8_MMA(0, 0, At, B0); PG8_MMA(0, 1, At, B1); PG8_BAR; PG8_SCHED;
;             PG8_LDA(At, 0, 1); PG8_STAGE(PG8_SB(0, 0), b2, voffB); PG8_STAGE(PG8_SB(0, 1), b2 + hstep, voffB); PG8_STAGE(PG8_SA(0, 0), a2, voffA);
;             PG8_WAIT_V(8); PG8_WAIT_L(0); PG8_BAR; PG8_MMA(1, 0, At, B0); PG8_MMA(1, 1, At, B1); PG8_BAR; PG8_SCHED;
.LBB0_1288:
	v_add_u32_e32 v145, s45, v149
	ds_read_b128 v[162:165], v145
	ds_read_b128 v[166:169], v145 offset:1024
	ds_read_b128 v[170:173], v145 offset:2048
	ds_read_b128 v[174:177], v145 offset:3072
	v_add_u32_e32 v145, s46, v149
	ds_read_b128 v[178:181], v145
	ds_read_b128 v[182:185], v145 offset:1024
	ds_read_b128 v[186:189], v145 offset:2048
	ds_read_b128 v[194:197], v145 offset:3072
	s_add_u32 s38, s34, 0xfff80080
	s_addc_u32 s39, s35, -1
	s_and_b64 s[36:37], s[36:37], exec
	s_cselect_b32 s39, s23, s39
	s_cselect_b32 s38, s49, s38
	s_cselect_b32 s37, s21, s52
	s_cselect_b32 s36, s50, s51
	v_lshl_add_u64 v[190:191], s[34:35], 0, v[136:137]
	s_add_i32 m0, s30, 0xc000
	ds_read_b128 v[198:201], v151
	ds_read_b128 v[202:205], v151 offset:1024
	ds_read_b128 v[206:209], v151 offset:2048
	ds_read_b128 v[210:213], v151 offset:3072
	ds_read_b128 v[214:217], v151 offset:4096
	ds_read_b128 v[218:221], v151 offset:5120
	ds_read_b128 v[222:225], v151 offset:6144
	ds_read_b128 v[226:229], v151 offset:7168
	global_load_lds_dwordx4 v[190:191], off
	v_lshl_add_u64 v[190:191], s[34:35], 0, v[138:139]
	s_add_i32 m0, s30, 0xe000
	s_nop 0
	global_load_lds_dwordx4 v[190:191], off
	s_waitcnt vmcnt(8)
	s_waitcnt lgkmcnt(0)
	s_barrier
	s_waitcnt lgkmcnt(0)
	v_mfma_f32_16x16x32_bf16 v[124:127], v[162:165], v[198:201], v[124:127]
	v_mfma_f32_16x16x32_bf16 v[120:123], v[170:173], v[198:201], v[120:123]
	v_mfma_f32_16x16x32_bf16 v[108:111], v[162:165], v[206:209], v[108:111]
	v_mfma_f32_16x16x32_bf16 v[104:107], v[170:173], v[206:209], v[104:107]
	v_mfma_f32_16x16x32_bf16 v[92:95], v[162:165], v[214:217], v[92:95]
	v_mfma_f32_16x16x32_bf16 v[88:91], v[170:173], v[214:217], v[88:91]
	v_mfma_f32_16x16x32_bf16 v[76:79], v[162:165], v[222:225], v[76:79]
	v_mfma_f32_16x16x32_bf16 v[72:75], v[170:173], v[222:225], v[72:75]
	v_mfma_f32_16x16x32_bf16 v[124:127], v[166:169], v[202:205], v[124:127]
	v_mfma_f32_16x16x32_bf16 v[120:123], v[174:177], v[202:205], v[120:123]
	v_mfma_f32_16x16x32_bf16 v[108:111], v[166:169], v[210:213], v[108:111]
	v_mfma_f32_16x16x32_bf16 v[104:107], v[174:177], v[210:213], v[104:107]
	v_mfma_f32_16x16x32_bf16 v[92:95], v[166:169], v[218:221], v[92:95]
	v_mfma_f32_16x16x32_bf16 v[88:91], v[174:177], v[218:221], v[88:91]
	v_mfma_f32_16x16x32_bf16 v[76:79], v[166:169], v[226:229], v[76:79]
	v_mfma_f32_16x16x32_bf16 v[72:75], v[174:177], v[226:229], v[72:75]
	v_mfma_f32_16x16x32_bf16 v[116:119], v[178:181], v[198:201], v[116:119]
	v_mfma_f32_16x16x32_bf16 v[112:115], v[186:189], v[198:201], v[112:115]
	v_mfma_f32_16x16x32_bf16 v[100:103], v[178:181], v[206:209], v[100:103]
	v_mfma_f32_16x16x32_bf16 v[96:99], v[186:189], v[206:209], v[96:99]
	v_mfma_f32_16x16x32_bf16 v[84:87], v[178:181], v[214:217], v[84:87]
	v_mfma_f32_16x16x32_bf16 v[80:83], v[186:189], v[214:217], v[80:83]
	v_mfma_f32_16x16x32_bf16 v[68:71], v[178:181], v[222:225], v[68:71]
	v_mfma_f32_16x16x32_bf16 v[64:67], v[186:189], v[222:225], v[64:67]
	v_mfma_f32_16x16x32_bf16 v[116:119], v[182:185], v[202:205], v[116:119]
	v_mfma_f32_16x16x32_bf16 v[112:115], v[194:197], v[202:205], v[112:115]
	v_mfma_f32_16x16x32_bf16 v[100:103], v[182:185], v[210:213], v[100:103]
	v_mfma_f32_16x16x32_bf16 v[96:99], v[194:197], v[210:213], v[96:99]
	v_mfma_f32_16x16x32_bf16 v[84:87], v[182:185], v[218:221], v[84:87]
	v_mfma_f32_16x16x32_bf16 v[80:83], v[194:197], v[218:221], v[80:83]
	v_mfma_f32_16x16x32_bf16 v[68:71], v[182:185], v[226:229], v[68:71]
	v_mfma_f32_16x16x32_bf16 v[64:67], v[194:197], v[226:229], v[64:67]
	s_barrier
	s_add_i32 s54, s45, s11
	v_lshl_add_u64 v[190:191], s[36:37], 0, v[132:133]
	s_mov_b32 m0, s54
	ds_read_b128 v[198:201], v151 offset:16384
	ds_read_b128 v[202:205], v151 offset:17408
	ds_read_b128 v[206:209], v151 offset:18432
	ds_read_b128 v[210:213], v151 offset:19456
	ds_read_b128 v[214:217], v151 offset:20480
	ds_read_b128 v[218:221], v151 offset:21504
	ds_read_b128 v[222:225], v151 offset:22528
	ds_read_b128 v[226:229], v151 offset:23552
	global_load_lds_dwordx4 v[190:191], off
	s_add_i32 m0, s54, 0x2000
	s_add_u32 s54, s36, 0x80000
	v_lshl_add_u64 v[230:231], s[36:37], 0, v[128:129]
	s_addc_u32 s55, s37, 0
	s_add_i32 s56, s46, s11
	global_load_lds_dwordx4 v[230:231], off
	v_lshl_add_u64 v[232:233], s[54:55], 0, v[132:133]
	s_mov_b32 m0, s56
	v_lshl_add_u64 v[234:235], s[38:39], 0, v[130:131]
	global_load_lds_dwordx4 v[232:233], off
	v_lshl_add_u64 v[232:233], s[54:55], 0, v[128:129]
	s_add_i32 m0, s56, 0x2000
	s_nop 0
	global_load_lds_dwordx4 v[232:233], off
	v_lshl_add_u64 v[232:233], s[38:39], 0, v[134:135]
	s_mov_b32 m0, s30
	s_nop 0
	global_load_lds_dwordx4 v[232:233], off
	s_mov_b32 m0, s31
	s_nop 0
	global_load_lds_dwordx4 v[234:235], off
	s_waitcnt vmcnt(8)
	s_waitcnt lgkmcnt(0)
	s_barrier
; #define PG8_STAGE(bufoff, gbase, voff) do { _Pragma("unroll") for (int _i = 0; _i < 2; ++_i) \
;         __builtin_amdgcn_global_load_lds((const unsigned*)((const char*)(gbase) + (voff)[_i]), (LAS unsigned*)(lds + (bufoff) + ldsw + _i * 8192), 16, 0, 0); } while (0)
; #define PG8_LDA(dst, b, h) do { _Pragma("unroll") for (int m = 0; m < 4; ++m) _Pragma("unroll") for (int k = 0; k < 2; ++k) dst[m][k] = *(const LAS bf16x8*)(lds + PG8_SA(b, h) + aoff + m * 2048 + k * 1024); } while (0)
; #define PG8_LDB(dst, b, h) do { _Pragma("unroll") for (int n = 0; n < 2; ++n) _Pragma("unroll") for (int k = 0; k < 2; ++k) dst[n][k] = *(const LAS bf16x8*)(lds + PG8_SB(b, h) + boff + n * 2048 + k * 1024); } while (0)
; #define PG8_MMA(ai, bj, At, Bt) do { __builtin_amdgcn_s_setprio(1); _Pragma("unroll") for (int m = 0; m < 4; ++m) _Pragma("unroll") for (int n = 0; n < 2; ++n) _Pragma("unroll") for (int k = 0; k < 2; ++k) \
;         acc[ai][bj][m][n] = __builtin_amdgcn_mfma_f32_16x16x32_bf16(Bt[n][k], At[m][k], acc[ai][bj][m][n], 0, 0, 0); __builtin_amdgcn_s_setprio(0); } while (0)
; #define PG8_WAIT_V(n) asm volatile("s_waitcnt vmcnt(" #n ")" ::: "memory")
; #define PG8_WAIT_L(n) asm volatile("s_waitcnt lgkmcnt(" #n ")" ::: "memory")
; #define PG8_BAR __builtin_amdgcn_s_barrier()
; #define PG8_SCHED __builtin_amdgcn_sched_barrier(0)
; template <class Epi, class Sched, bool ALIGN_EPI = false, bool SP2 = false>
; __device__ __forceinline__ void gemm_phase(LAS unsigned char* lds, const Gemm g, const Sched S, const Epi E) {
;     ...
;             PG8_WAIT_V(8); PG8_WAIT_L(0); PG8_BAR; PG8_MMA(0, 0, At, B0); PG8_MMA(0, 1, At, B1); PG8_BAR; PG8_SCHED;
;             PG8_LDA(At, 0, 1); PG8_STAGE(PG8_SB(0, 0), b2, voffB); PG8_STAGE(PG8_SB(0, 1), b2 + hstep, voffB); PG8_STAGE(PG8_SA(0, 0), a2, voffA);
;             PG8_WAIT_V(8); PG8_WAIT_L(0); PG8_BAR; PG8_MMA(1, 0, At, B0); PG8_MMA(1, 1, At, B1); PG8_BAR; PG8_SCHED;
;             PG8_LDB(B0, 1, 0); PG8_LDB(B1, 1, 1); PG8_SCHED; PG8_LDA(At, 1, 0); PG8_STAGE(PG8_SA(0, 1), a2 + hstep, voffA);
;             PG8_WAIT_V(8); PG8_WAIT_L(0); PG8_BAR; PG8_MMA(0, 0, At, B0); PG8_MMA(0, 1, At, B1); PG8_BAR; PG8_SCHED;
	s_waitcnt lgkmcnt(0)
	v_mfma_f32_16x16x32_bf16 v[60:63], v[162:165], v[198:201], v[60:63]
	v_mfma_f32_16x16x32_bf16 v[56:59], v[170:173], v[198:201], v[56:59]
	v_mfma_f32_16x16x32_bf16 v[44:47], v[162:165], v[206:209], v[44:47]
	v_mfma_f32_16x16x32_bf16 v[40:43], v[170:173], v[206:209], v[40:43]
	v_mfma_f32_16x16x32_bf16 v[28:31], v[162:165], v[214:217], v[28:31]
	v_mfma_f32_16x16x32_bf16 v[24:27], v[170:173], v[214:217], v[24:27]
	v_mfma_f32_16x16x32_bf16 v[12:15], v[162:165], v[222:225], v[12:15]
	v_mfma_f32_16x16x32_bf16 v[8:11], v[170:173], v[222:225], v[8:11]
	v_mfma_f32_16x16x32_bf16 v[60:63], v[166:169], v[202:205], v[60:63]
	v_mfma_f32_16x16x32_bf16 v[56:59], v[174:177], v[202:205], v[56:59]
	v_mfma_f32_16x16x32_bf16 v[44:47], v[166:169], v[210:213], v[44:47]
	v_mfma_f32_16x16x32_bf16 v[40:43], v[174:177], v[210:213], v[40:43]
	v_mfma_f32_16x16x32_bf16 v[28:31], v[166:169], v[218:221], v[28:31]
	v_mfma_f32_16x16x32_bf16 v[24:27], v[174:177], v[218:221], v[24:27]
	v_mfma_f32_16x16x32_bf16 v[12:15], v[166:169], v[226:229], v[12:15]
	v_mfma_f32_16x16x32_bf16 v[8:11], v[174:177], v[226:229], v[8:11]
	v_mfma_f32_16x16x32_bf16 v[52:55], v[178:181], v[198:201], v[52:55]
	v_mfma_f32_16x16x32_bf16 v[48:51], v[186:189], v[198:201], v[48:51]
	v_mfma_f32_16x16x32_bf16 v[36:39], v[178:181], v[206:209], v[36:39]
	v_mfma_f32_16x16x32_bf16 v[32:35], v[186:189], v[206:209], v[32:35]
	v_mfma_f32_16x16x32_bf16 v[20:23], v[178:181], v[214:217], v[20:23]
	v_mfma_f32_16x16x32_bf16 v[16:19], v[186:189], v[214:217], v[16:19]
	v_mfma_f32_16x16x32_bf16 v[4:7], v[178:181], v[222:225], v[4:7]
	v_mfma_f32_16x16x32_bf16 v[0:3], v[186:189], v[222:225], v[0:3]
	v_mfma_f32_16x16x32_bf16 v[52:55], v[182:185], v[202:205], v[52:55]
	v_mfma_f32_16x16x32_bf16 v[48:51], v[194:197], v[202:205], v[48:51]
	v_mfma_f32_16x16x32_bf16 v[36:39], v[182:185], v[210:213], v[36:39]
	v_mfma_f32_16x16x32_bf16 v[32:35], v[194:197], v[210:213], v[32:35]
	v_mfma_f32_16x16x32_bf16 v[20:23], v[182:185], v[218:221], v[20:23]
	v_mfma_f32_16x16x32_bf16 v[16:19], v[194:197], v[218:221], v[16:19]
	v_mfma_f32_16x16x32_bf16 v[4:7], v[182:185], v[226:229], v[4:7]
	v_mfma_f32_16x16x32_bf16 v[0:3], v[194:197], v[226:229], v[0:3]
	s_barrier
	s_add_i32 s54, 0, 0x18000
	v_add_u32_e32 v145, s54, v149
	s_add_i32 s55, 0, 0x1c000
	ds_read_b128 v[162:165], v145
	ds_read_b128 v[166:169], v145 offset:1024
	ds_read_b128 v[170:173], v145 offset:2048
	ds_read_b128 v[174:177], v145 offset:3072
	v_add_u32_e32 v145, s55, v149
	ds_read_b128 v[178:181], v145
	ds_read_b128 v[182:185], v145 offset:1024
	ds_read_b128 v[186:189], v145 offset:2048
	ds_read_b128 v[194:197], v145 offset:3072
	s_add_u32 s38, s38, 0x80000
	s_addc_u32 s39, s39, 0
	s_mov_b32 m0, s33
	v_lshl_add_u64 v[236:237], s[38:39], 0, v[134:135]
	ds_read_b128 v[198:201], v151 offset:32768
	ds_read_b128 v[202:205], v151 offset:33792
	ds_read_b128 v[206:209], v151 offset:34816
	ds_read_b128 v[210:213], v151 offset:35840
	ds_read_b128 v[214:217], v151 offset:36864
	ds_read_b128 v[218:221], v151 offset:37888
	ds_read_b128 v[222:225], v151 offset:38912
	ds_read_b128 v[226:229], v151 offset:39936
	global_load_lds_dwordx4 v[236:237], off
	v_lshl_add_u64 v[236:237], s[38:39], 0, v[130:131]
	s_mov_b32 m0, s40
	s_nop 0
	global_load_lds_dwordx4 v[236:237], off
	s_waitcnt vmcnt(8)
	s_waitcnt lgkmcnt(0)
	s_barrier
	s_waitcnt lgkmcnt(0)
	v_mfma_f32_16x16x32_bf16 v[124:127], v[162:165], v[198:201], v[124:127]
	v_mfma_f32_16x16x32_bf16 v[120:123], v[170:173], v[198:201], v[120:123]
	v_mfma_f32_16x16x32_bf16 v[108:111], v[162:165], v[206:209], v[108:111]
	v_mfma_f32_16x16x32_bf16 v[104:107], v[170:173], v[206:209], v[104:107]
	v_mfma_f32_16x16x32_bf16 v[92:95], v[162:165], v[214:217], v[92:95]
	v_mfma_f32_16x16x32_bf16 v[88:91], v[170:173], v[214:217], v[88:91]
	v_mfma_f32_16x16x32_bf16 v[76:79], v[162:165], v[222:225], v[76:79]
	v_mfma_f32_16x16x32_bf16 v[72:75], v[170:173], v[222:225], v[72:75]
	v_mfma_f32_16x16x32_bf16 v[124:127], v[166:169], v[202:205], v[124:127]
	v_mfma_f32_16x16x32_bf16 v[120:123], v[174:177], v[202:205], v[120:123]
	v_mfma_f32_16x16x32_bf16 v[108:111], v[166:169], v[210:213], v[108:111]
	v_mfma_f32_16x16x32_bf16 v[104:107], v[174:177], v[210:213], v[104:107]
	v_mfma_f32_16x16x32_bf16 v[92:95], v[166:169], v[218:221], v[92:95]
	v_mfma_f32_16x16x32_bf16 v[88:91], v[174:177], v[218:221], v[88:91]
	v_mfma_f32_16x16x32_bf16 v[76:79], v[166:169], v[226:229], v[76:79]
	v_mfma_f32_16x16x32_bf16 v[72:75], v[174:177], v[226:229], v[72:75]
	v_mfma_f32_16x16x32_bf16 v[116:119], v[178:181], v[198:201], v[116:119]
	v_mfma_f32_16x16x32_bf16 v[112:115], v[186:189], v[198:201], v[112:115]
	v_mfma_f32_16x16x32_bf16 v[100:103], v[178:181], v[206:209], v[100:103]
	v_mfma_f32_16x16x32_bf16 v[96:99], v[186:189], v[206:209], v[96:99]
	v_mfma_f32_16x16x32_bf16 v[84:87], v[178:181], v[214:217], v[84:87]
	v_mfma_f32_16x16x32_bf16 v[80:83], v[186:189], v[214:217], v[80:83]
	v_mfma_f32_16x16x32_bf16 v[68:71], v[178:181], v[222:225], v[68:71]
	v_mfma_f32_16x16x32_bf16 v[64:67], v[186:189], v[222:225], v[64:67]
	v_mfma_f32_16x16x32_bf16 v[116:119], v[182:185], v[202:205], v[116:119]
	v_mfma_f32_16x16x32_bf16 v[112:115], v[194:197], v[202:205], v[112:115]
	v_mfma_f32_16x16x32_bf16 v[100:103], v[182:185], v[210:213], v[100:103]
	v_mfma_f32_16x16x32_bf16 v[96:99], v[194:197], v[210:213], v[96:99]
	v_mfma_f32_16x16x32_bf16 v[84:87], v[182:185], v[218:221], v[84:87]
	v_mfma_f32_16x16x32_bf16 v[80:83], v[194:197], v[218:221], v[80:83]
	v_mfma_f32_16x16x32_bf16 v[68:71], v[182:185], v[226:229], v[68:71]
	v_mfma_f32_16x16x32_bf16 v[64:67], v[194:197], v[226:229], v[64:67]
	s_barrier
; #define PG8_STAGE(bufoff, gbase, voff) do { _Pragma("unroll") for (int _i = 0; _i < 2; ++_i) \
;         __builtin_amdgcn_global_load_lds((const unsigned*)((const char*)(gbase) + (voff)[_i]), (LAS unsigned*)(lds + (bufoff) + ldsw + _i * 8192), 16, 0, 0); } while (0)
; #define PG8_LDA(dst, b, h) do { _Pragma("unroll") for (int m = 0; m < 4; ++m) _Pragma("unroll") for (int k = 0; k < 2; ++k) dst[m][k] = *(const LAS bf16x8*)(lds + PG8_SA(b, h) + aoff + m * 2048 + k * 1024); } while (0)
; #define PG8_MMA(ai, bj, At, Bt) do { __builtin_amdgcn_s_setprio(1); _Pragma("unroll") for (int m = 0; m < 4; ++m) _Pragma("unroll") for (int n = 0; n < 2; ++n) _Pragma("unroll") for (int k = 0; k < 2; ++k) \
;         acc[ai][bj][m][n] = __builtin_amdgcn_mfma_f32_16x16x32_bf16(Bt[n][k], At[m][k], acc[ai][bj][m][n], 0, 0, 0); __builtin_amdgcn_s_setprio(0); } while (0)
; #define PG8_WAIT_V(n) asm volatile("s_waitcnt vmcnt(" #n ")" ::: "memory")
; #define PG8_WAIT_L(n) asm volatile("s_waitcnt lgkmcnt(" #n ")" ::: "memory")
; #define PG8_BAR __builtin_amdgcn_s_barrier()
; #define PG8_SCHED __builtin_amdgcn_sched_barrier(0)
; template <class Epi, class Sched, bool ALIGN_EPI = false, bool SP2 = false>
; __device__ __forceinline__ void gemm_phase(LAS unsigned char* lds, const Gemm g, const Sched S, const Epi E) {
;     ...
;         for (int t = 0; t < nt; t += 2) {
;     ...
;             PG8_LDA(At, 1, 1); PG8_STAGE(PG8_SB(1, 0), b3, voffB); PG8_STAGE(PG8_SB(1, 1), b3 + hstep, voffB); PG8_STAGE(PG8_SA(1, 0), a3, voffA);
;             PG8_WAIT_V(8); PG8_WAIT_L(0); PG8_BAR; PG8_MMA(1, 0, At, B0); PG8_MMA(1, 1, At, B1); PG8_BAR; PG8_SCHED;
	s_add_i32 s38, s54, s11
	v_lshl_add_u64 v[190:191], v[190:191], 0, s[14:15]
	s_mov_b32 m0, s38
	ds_read_b128 v[198:201], v151 offset:49152
	ds_read_b128 v[202:205], v151 offset:50176
	ds_read_b128 v[206:209], v151 offset:51200
	ds_read_b128 v[210:213], v151 offset:52224
	ds_read_b128 v[214:217], v151 offset:53248
	ds_read_b128 v[218:221], v151 offset:54272
	ds_read_b128 v[222:225], v151 offset:55296
	ds_read_b128 v[226:229], v151 offset:56320
	global_load_lds_dwordx4 v[190:191], off
	s_add_i32 m0, s38, 0x2000
	s_add_u32 s36, s36, 0x80080
	v_lshl_add_u64 v[190:191], v[230:231], 0, s[14:15]
	s_addc_u32 s37, s37, 0
	s_add_i32 s38, s55, s11
	global_load_lds_dwordx4 v[190:191], off
	v_lshl_add_u64 v[190:191], s[36:37], 0, v[132:133]
	s_mov_b32 m0, s38
	s_nop 0
	global_load_lds_dwordx4 v[190:191], off
	v_lshl_add_u64 v[190:191], s[36:37], 0, v[128:129]
	s_add_i32 m0, s38, 0x2000
	s_nop 0
	global_load_lds_dwordx4 v[190:191], off
	v_lshl_add_u64 v[190:191], v[232:233], 0, s[14:15]
	s_mov_b32 m0, s42
	s_nop 0
	global_load_lds_dwordx4 v[190:191], off
	v_lshl_add_u64 v[190:191], v[234:235], 0, s[14:15]
	s_mov_b32 m0, s43
	s_nop 0
	global_load_lds_dwordx4 v[190:191], off
	s_waitcnt vmcnt(8)
	s_waitcnt lgkmcnt(0)
	s_barrier
	s_waitcnt lgkmcnt(0)
	v_mfma_f32_16x16x32_bf16 v[60:63], v[162:165], v[198:201], v[60:63]
	v_mfma_f32_16x16x32_bf16 v[56:59], v[170:173], v[198:201], v[56:59]
	v_mfma_f32_16x16x32_bf16 v[44:47], v[162:165], v[206:209], v[44:47]
	v_mfma_f32_16x16x32_bf16 v[40:43], v[170:173], v[206:209], v[40:43]
	v_mfma_f32_16x16x32_bf16 v[28:31], v[162:165], v[214:217], v[28:31]
	v_mfma_f32_16x16x32_bf16 v[24:27], v[170:173], v[214:217], v[24:27]
	v_mfma_f32_16x16x32_bf16 v[12:15], v[162:165], v[222:225], v[12:15]
	v_mfma_f32_16x16x32_bf16 v[8:11], v[170:173], v[222:225], v[8:11]
	v_mfma_f32_16x16x32_bf16 v[60:63], v[166:169], v[202:205], v[60:63]
	v_mfma_f32_16x16x32_bf16 v[56:59], v[174:177], v[202:205], v[56:59]
	v_mfma_f32_16x16x32_bf16 v[44:47], v[166:169], v[210:213], v[44:47]
	v_mfma_f32_16x16x32_bf16 v[40:43], v[174:177], v[210:213], v[40:43]
	v_mfma_f32_16x16x32_bf16 v[28:31], v[166:169], v[218:221], v[28:31]
	v_mfma_f32_16x16x32_bf16 v[24:27], v[174:177], v[218:221], v[24:27]
	v_mfma_f32_16x16x32_bf16 v[12:15], v[166:169], v[226:229], v[12:15]
	v_mfma_f32_16x16x32_bf16 v[8:11], v[174:177], v[226:229], v[8:11]
	v_mfma_f32_16x16x32_bf16 v[52:55], v[178:181], v[198:201], v[52:55]
	v_mfma_f32_16x16x32_bf16 v[48:51], v[186:189], v[198:201], v[48:51]
	v_mfma_f32_16x16x32_bf16 v[36:39], v[178:181], v[206:209], v[36:39]
	v_mfma_f32_16x16x32_bf16 v[32:35], v[186:189], v[206:209], v[32:35]
	v_mfma_f32_16x16x32_bf16 v[20:23], v[178:181], v[214:217], v[20:23]
	v_mfma_f32_16x16x32_bf16 v[16:19], v[186:189], v[214:217], v[16:19]
	v_mfma_f32_16x16x32_bf16 v[4:7], v[178:181], v[222:225], v[4:7]
	v_mfma_f32_16x16x32_bf16 v[0:3], v[186:189], v[222:225], v[0:3]
	v_mfma_f32_16x16x32_bf16 v[52:55], v[182:185], v[202:205], v[52:55]
	v_mfma_f32_16x16x32_bf16 v[48:51], v[194:197], v[202:205], v[48:51]
	v_mfma_f32_16x16x32_bf16 v[36:39], v[182:185], v[210:213], v[36:39]
	v_mfma_f32_16x16x32_bf16 v[32:35], v[194:197], v[210:213], v[32:35]
	v_mfma_f32_16x16x32_bf16 v[20:23], v[182:185], v[218:221], v[20:23]
	v_mfma_f32_16x16x32_bf16 v[16:19], v[194:197], v[218:221], v[16:19]
	v_mfma_f32_16x16x32_bf16 v[4:7], v[182:185], v[226:229], v[4:7]
	v_mfma_f32_16x16x32_bf16 v[0:3], v[194:197], v[226:229], v[0:3]
	s_barrier
	s_add_i32 s53, s53, 2
	s_add_u32 s34, s34, 0x100
	s_addc_u32 s35, s35, 0
	s_add_u32 s51, s51, 0x100
	s_addc_u32 s52, s52, 0
	s_cmp_gt_u32 s53, 29
	s_cbranch_scc1 .LBB0_1291

; #define PG8_STAGE(bufoff, gbase, voff) do { _Pragma("unroll") for (int _i = 0; _i < 2; ++_i) \
;         __builtin_amdgcn_global_load_lds((const unsigned*)((const char*)(gbase) + (voff)[_i]), (LAS unsigned*)(lds + (bufoff) + ldsw + _i * 8192), 16, 0, 0); } while (0)
; #define PG8_LDA(dst, b, h) do { _Pragma("unroll") for (int m = 0; m < 4; ++m) _Pragma("unroll") for (int k = 0; k < 2; ++k) dst[m][k] = *(const LAS bf16x8*)(lds + PG8_SA(b, h) + aoff + m * 2048 + k * 1024); } while (0)
; #define PG8_LDB(dst, b, h) do { _Pragma("unroll") for (int n = 0; n < 2; ++n) _Pragma("unroll") for (int k = 0; k < 2; ++k) dst[n][k] = *(const LAS bf16x8*)(lds + PG8_SB(b, h) + boff + n * 2048 + k * 1024); } while (0)
; #define PG8_MMA(ai, bj, At, Bt) do { __builtin_amdgcn_s_setprio(1); _Pragma("unroll") for (int m = 0; m < 4; ++m) _Pragma("unroll") for (int n = 0; n < 2; ++n) _Pragma("unroll") for (int k = 0; k < 2; ++k) \
;         acc[ai][bj][m][n] = __builtin_amdgcn_mfma_f32_16x16x32_bf16(Bt[n][k], At[m][k], acc[ai][bj][m][n], 0, 0, 0); __builtin_amdgcn_s_setprio(0); } while (0)
; #define PG8_WAIT_V(n) asm volatile("s_waitcnt vmcnt(" #n ")" ::: "memory")
; #define PG8_WAIT_L(n) asm volatile("s_waitcnt lgkmcnt(" #n ")" ::: "memory")
; #define PG8_BAR __builtin_amdgcn_s_barrier()
; template <class Epi, class Sched, bool ALIGN_EPI = false, bool SP2 = false>
; __device__ __forceinline__ void gemm_phase(LAS unsigned char* lds, const Gemm g, const Sched S, const Epi E) {
;     ...
;         for (int t = 0; t < nt; t += 2) {
;             const bool last = (t == nt - 2);
;             const char* a1 = cA + (size_t)(t + 1) * kstep;
;             const char* a2 = last ? nA : cA + (size_t)(t + 2) * kstep; const char* b2 = last ? nB : cB + (size_t)(t + 2) * kstep;
;             const char* a3 = a2 + kstep; const char* b3 = b2 + kstep;
;             if (last && has_next) S.a_ready(nxt);
;             if (last) E.prefetch(cur, wr, fr, pre);
;             if constexpr (SP2) {
;             PG8_LDB(B0, 0, 0); PG8_LDB(B1, 0, 1); PG8_SCHED; PG8_LDA(At, 0, 0); PG8_STAGE(PG8_SA(1, 1), a1 + hstep, voffA);
;             PG8_WAIT_V(8); PG8_WAIT_L(0); PG8_BAR; PG8_MMA(0, 0, At, B0); PG8_MMA(0, 1, At, B1); PG8_BAR; PG8_SCHED;
;             PG8_LDA(At, 0, 1); PG8_STAGE(PG8_SB(0, 0), b2, voffB); PG8_STAGE(PG8_SB(0, 1), b2 + hstep, voffB); PG8_STAGE(PG8_SA(0, 0), a2, voffA);
.LBB0_1375:
	ds_read_b128 v[140:143], v183
	ds_read_b128 v[144:147], v183 offset:1024
	ds_read_b128 v[148:151], v183 offset:2048
	ds_read_b128 v[152:155], v183 offset:3072
	ds_read_b128 v[156:159], v184
	ds_read_b128 v[160:163], v184 offset:1024
	ds_read_b128 v[164:167], v184 offset:2048
	ds_read_b128 v[168:171], v184 offset:3072
	s_add_u32 s34, s26, 0xffea8080
	s_addc_u32 s35, s27, -1
	s_cmpk_eq_i32 s50, 0x52
	s_cselect_b32 s37, s1, s35
	s_cselect_b32 s36, s0, s34
	s_cselect_b32 s35, s25, s49
	s_cselect_b32 s34, s24, s48
	v_lshl_add_u64 v[214:215], s[26:27], 0, v[132:133]
	s_add_i32 m0, s28, 0xc000
	ds_read_b128 v[172:175], v185
	ds_read_b128 v[176:179], v185 offset:1024
	ds_read_b128 v[188:191], v185 offset:2048
	ds_read_b128 v[194:197], v185 offset:3072
	ds_read_b128 v[198:201], v185 offset:4096
	ds_read_b128 v[202:205], v185 offset:5120
	ds_read_b128 v[206:209], v185 offset:6144
	ds_read_b128 v[210:213], v185 offset:7168
	global_load_lds_dwordx4 v[214:215], off
	v_lshl_add_u64 v[214:215], s[26:27], 0, v[134:135]
	s_add_i32 m0, s28, 0xe000
	s_nop 0
	global_load_lds_dwordx4 v[214:215], off
	s_waitcnt vmcnt(8)
	s_waitcnt lgkmcnt(0)
	s_barrier
	s_waitcnt lgkmcnt(0)
	v_mfma_f32_16x16x32_bf16 v[124:127], v[140:143], v[172:175], v[124:127]
	v_mfma_f32_16x16x32_bf16 v[120:123], v[148:151], v[172:175], v[120:123]
	v_mfma_f32_16x16x32_bf16 v[108:111], v[140:143], v[188:191], v[108:111]
	v_mfma_f32_16x16x32_bf16 v[104:107], v[148:151], v[188:191], v[104:107]
	v_mfma_f32_16x16x32_bf16 v[92:95], v[140:143], v[198:201], v[92:95]
	v_mfma_f32_16x16x32_bf16 v[88:91], v[148:151], v[198:201], v[88:91]
	v_mfma_f32_16x16x32_bf16 v[76:79], v[140:143], v[206:209], v[76:79]
	v_mfma_f32_16x16x32_bf16 v[72:75], v[148:151], v[206:209], v[72:75]
	v_mfma_f32_16x16x32_bf16 v[124:127], v[144:147], v[176:179], v[124:127]
	v_mfma_f32_16x16x32_bf16 v[120:123], v[152:155], v[176:179], v[120:123]
	v_mfma_f32_16x16x32_bf16 v[108:111], v[144:147], v[194:197], v[108:111]
	v_mfma_f32_16x16x32_bf16 v[104:107], v[152:155], v[194:197], v[104:107]
	v_mfma_f32_16x16x32_bf16 v[92:95], v[144:147], v[202:205], v[92:95]
	v_mfma_f32_16x16x32_bf16 v[88:91], v[152:155], v[202:205], v[88:91]
	v_mfma_f32_16x16x32_bf16 v[76:79], v[144:147], v[210:213], v[76:79]
	v_mfma_f32_16x16x32_bf16 v[72:75], v[152:155], v[210:213], v[72:75]
	v_mfma_f32_16x16x32_bf16 v[116:119], v[156:159], v[172:175], v[116:119]
	v_mfma_f32_16x16x32_bf16 v[112:115], v[164:167], v[172:175], v[112:115]
	v_mfma_f32_16x16x32_bf16 v[100:103], v[156:159], v[188:191], v[100:103]
	v_mfma_f32_16x16x32_bf16 v[96:99], v[164:167], v[188:191], v[96:99]
	v_mfma_f32_16x16x32_bf16 v[84:87], v[156:159], v[198:201], v[84:87]
	v_mfma_f32_16x16x32_bf16 v[80:83], v[164:167], v[198:201], v[80:83]
	v_mfma_f32_16x16x32_bf16 v[68:71], v[156:159], v[206:209], v[68:71]
	v_mfma_f32_16x16x32_bf16 v[64:67], v[164:167], v[206:209], v[64:67]
	v_mfma_f32_16x16x32_bf16 v[116:119], v[160:163], v[176:179], v[116:119]
	v_mfma_f32_16x16x32_bf16 v[112:115], v[168:171], v[176:179], v[112:115]
	v_mfma_f32_16x16x32_bf16 v[100:103], v[160:163], v[194:197], v[100:103]
	v_mfma_f32_16x16x32_bf16 v[96:99], v[168:171], v[194:197], v[96:99]
	v_mfma_f32_16x16x32_bf16 v[84:87], v[160:163], v[202:205], v[84:87]
	v_mfma_f32_16x16x32_bf16 v[80:83], v[168:171], v[202:205], v[80:83]
	v_mfma_f32_16x16x32_bf16 v[68:71], v[160:163], v[210:213], v[68:71]
	v_mfma_f32_16x16x32_bf16 v[64:67], v[168:171], v[210:213], v[64:67]
	s_barrier
	s_add_i32 s51, s42, s11
	v_lshl_add_u64 v[214:215], s[34:35], 0, v[128:129]
	s_mov_b32 m0, s51
	ds_read_b128 v[172:175], v185 offset:16384
	ds_read_b128 v[176:179], v185 offset:17408
	ds_read_b128 v[188:191], v185 offset:18432
	ds_read_b128 v[194:197], v185 offset:19456
	ds_read_b128 v[198:201], v185 offset:20480
	ds_read_b128 v[202:205], v185 offset:21504
	ds_read_b128 v[206:209], v185 offset:22528
	ds_read_b128 v[210:213], v185 offset:23552
	global_load_lds_dwordx4 v[214:215], off
	s_add_i32 m0, s51, 0x2000
	s_add_u32 s52, s34, 0x158000
	v_lshl_add_u64 v[216:217], s[34:35], 0, v[130:131]
	s_addc_u32 s53, s35, 0
	s_add_i32 s51, s43, s11
	global_load_lds_dwordx4 v[216:217], off
	v_lshl_add_u64 v[218:219], s[52:53], 0, v[128:129]
	s_mov_b32 m0, s51
	v_lshl_add_u64 v[220:221], s[36:37], 0, v[130:131]
	global_load_lds_dwordx4 v[218:219], off
	v_lshl_add_u64 v[218:219], s[52:53], 0, v[130:131]
	s_add_i32 m0, s51, 0x2000
	s_nop 0
	global_load_lds_dwordx4 v[218:219], off
	v_lshl_add_u64 v[218:219], s[36:37], 0, v[128:129]
	s_mov_b32 m0, s28
	s_nop 0
	global_load_lds_dwordx4 v[218:219], off
	s_mov_b32 m0, s29
	s_nop 0
	global_load_lds_dwordx4 v[220:221], off
	s_waitcnt vmcnt(8)
	s_waitcnt lgkmcnt(0)
	s_barrier
; #define PG8_STAGE(bufoff, gbase, voff) do { _Pragma("unroll") for (int _i = 0; _i < 2; ++_i) \
;         __builtin_amdgcn_global_load_lds((const unsigned*)((const char*)(gbase) + (voff)[_i]), (LAS unsigned*)(lds + (bufoff) + ldsw + _i * 8192), 16, 0, 0); } while (0)
; #define PG8_LDA(dst, b, h) do { _Pragma("unroll") for (int m = 0; m < 4; ++m) _Pragma("unroll") for (int k = 0; k < 2; ++k) dst[m][k] = *(const LAS bf16x8*)(lds + PG8_SA(b, h) + aoff + m * 2048 + k * 1024); } while (0)
; #define PG8_LDB(dst, b, h) do { _Pragma("unroll") for (int n = 0; n < 2; ++n) _Pragma("unroll") for (int k = 0; k < 2; ++k) dst[n][k] = *(const LAS bf16x8*)(lds + PG8_SB(b, h) + boff + n * 2048 + k * 1024); } while (0)
; #define PG8_MMA(ai, bj, At, Bt) do { __builtin_amdgcn_s_setprio(1); _Pragma("unroll") for (int m = 0; m < 4; ++m) _Pragma("unroll") for (int n = 0; n < 2; ++n) _Pragma("unroll") for (int k = 0; k < 2; ++k) \
;         acc[ai][bj][m][n] = __builtin_amdgcn_mfma_f32_16x16x32_bf16(Bt[n][k], At[m][k], acc[ai][bj][m][n], 0, 0, 0); __builtin_amdgcn_s_setprio(0); } while (0)
; #define PG8_WAIT_V(n) asm volatile("s_waitcnt vmcnt(" #n ")" ::: "memory")
; #define PG8_WAIT_L(n) asm volatile("s_waitcnt lgkmcnt(" #n ")" ::: "memory")
; #define PG8_BAR __builtin_amdgcn_s_barrier()
; #define PG8_SCHED __builtin_amdgcn_sched_barrier(0)
; template <class Epi, class Sched, bool ALIGN_EPI = false, bool SP2 = false>
; __device__ __forceinline__ void gemm_phase(LAS unsigned char* lds, const Gemm g, const Sched S, const Epi E) {
;     ...
;             PG8_WAIT_V(8); PG8_WAIT_L(0); PG8_BAR; PG8_MMA(1, 0, At, B0); PG8_MMA(1, 1, At, B1); PG8_BAR; PG8_SCHED;
;             PG8_LDB(B0, 1, 0); PG8_LDB(B1, 1, 1); PG8_SCHED; PG8_LDA(At, 1, 0); PG8_STAGE(PG8_SA(0, 1), a2 + hstep, voffA);
;             PG8_WAIT_V(8); PG8_WAIT_L(0); PG8_BAR; PG8_MMA(0, 0, At, B0); PG8_MMA(0, 1, At, B1); PG8_BAR; PG8_SCHED;
	s_waitcnt lgkmcnt(0)
	v_mfma_f32_16x16x32_bf16 v[60:63], v[140:143], v[172:175], v[60:63]
	v_mfma_f32_16x16x32_bf16 v[56:59], v[148:151], v[172:175], v[56:59]
	v_mfma_f32_16x16x32_bf16 v[44:47], v[140:143], v[188:191], v[44:47]
	v_mfma_f32_16x16x32_bf16 v[40:43], v[148:151], v[188:191], v[40:43]
	v_mfma_f32_16x16x32_bf16 v[28:31], v[140:143], v[198:201], v[28:31]
	v_mfma_f32_16x16x32_bf16 v[24:27], v[148:151], v[198:201], v[24:27]
	v_mfma_f32_16x16x32_bf16 v[12:15], v[140:143], v[206:209], v[12:15]
	v_mfma_f32_16x16x32_bf16 v[8:11], v[148:151], v[206:209], v[8:11]
	v_mfma_f32_16x16x32_bf16 v[60:63], v[144:147], v[176:179], v[60:63]
	v_mfma_f32_16x16x32_bf16 v[56:59], v[152:155], v[176:179], v[56:59]
	v_mfma_f32_16x16x32_bf16 v[44:47], v[144:147], v[194:197], v[44:47]
	v_mfma_f32_16x16x32_bf16 v[40:43], v[152:155], v[194:197], v[40:43]
	v_mfma_f32_16x16x32_bf16 v[28:31], v[144:147], v[202:205], v[28:31]
	v_mfma_f32_16x16x32_bf16 v[24:27], v[152:155], v[202:205], v[24:27]
	v_mfma_f32_16x16x32_bf16 v[12:15], v[144:147], v[210:213], v[12:15]
	v_mfma_f32_16x16x32_bf16 v[8:11], v[152:155], v[210:213], v[8:11]
	v_mfma_f32_16x16x32_bf16 v[52:55], v[156:159], v[172:175], v[52:55]
	v_mfma_f32_16x16x32_bf16 v[48:51], v[164:167], v[172:175], v[48:51]
	v_mfma_f32_16x16x32_bf16 v[36:39], v[156:159], v[188:191], v[36:39]
	v_mfma_f32_16x16x32_bf16 v[32:35], v[164:167], v[188:191], v[32:35]
	v_mfma_f32_16x16x32_bf16 v[20:23], v[156:159], v[198:201], v[20:23]
	v_mfma_f32_16x16x32_bf16 v[16:19], v[164:167], v[198:201], v[16:19]
	v_mfma_f32_16x16x32_bf16 v[4:7], v[156:159], v[206:209], v[4:7]
	v_mfma_f32_16x16x32_bf16 v[0:3], v[164:167], v[206:209], v[0:3]
	v_mfma_f32_16x16x32_bf16 v[52:55], v[160:163], v[176:179], v[52:55]
	v_mfma_f32_16x16x32_bf16 v[48:51], v[168:171], v[176:179], v[48:51]
	v_mfma_f32_16x16x32_bf16 v[36:39], v[160:163], v[194:197], v[36:39]
	v_mfma_f32_16x16x32_bf16 v[32:35], v[168:171], v[194:197], v[32:35]
	v_mfma_f32_16x16x32_bf16 v[20:23], v[160:163], v[202:205], v[20:23]
	v_mfma_f32_16x16x32_bf16 v[16:19], v[168:171], v[202:205], v[16:19]
	v_mfma_f32_16x16x32_bf16 v[4:7], v[160:163], v[210:213], v[4:7]
	v_mfma_f32_16x16x32_bf16 v[0:3], v[168:171], v[210:213], v[0:3]
	s_barrier
	s_add_i32 s51, 0, 0x18000
	s_add_i32 s52, 0, 0x1c000
	v_add_u32_e32 v152, s51, v181
	v_add_u32_e32 v168, s52, v181
	ds_read_b128 v[140:143], v152
	ds_read_b128 v[144:147], v152 offset:1024
	ds_read_b128 v[148:151], v152 offset:2048
	ds_read_b128 v[152:155], v152 offset:3072
	ds_read_b128 v[156:159], v168
	ds_read_b128 v[160:163], v168 offset:1024
	ds_read_b128 v[164:167], v168 offset:2048
	ds_read_b128 v[168:171], v168 offset:3072
	s_add_u32 s36, s36, 0x158000
	s_addc_u32 s37, s37, 0
	s_mov_b32 m0, s30
	v_lshl_add_u64 v[222:223], s[36:37], 0, v[128:129]
	ds_read_b128 v[172:175], v185 offset:32768
	ds_read_b128 v[176:179], v185 offset:33792
	ds_read_b128 v[188:191], v185 offset:34816
	ds_read_b128 v[194:197], v185 offset:35840
	ds_read_b128 v[198:201], v185 offset:36864
	ds_read_b128 v[202:205], v185 offset:37888
	ds_read_b128 v[206:209], v185 offset:38912
	ds_read_b128 v[210:213], v185 offset:39936
	global_load_lds_dwordx4 v[222:223], off
	v_lshl_add_u64 v[222:223], s[36:37], 0, v[130:131]
	s_mov_b32 m0, s31
	s_nop 0
	global_load_lds_dwordx4 v[222:223], off
	s_waitcnt vmcnt(8)
	s_waitcnt lgkmcnt(0)
	s_barrier
	s_waitcnt lgkmcnt(0)
	v_mfma_f32_16x16x32_bf16 v[124:127], v[140:143], v[172:175], v[124:127]
	v_mfma_f32_16x16x32_bf16 v[120:123], v[148:151], v[172:175], v[120:123]
	v_mfma_f32_16x16x32_bf16 v[108:111], v[140:143], v[188:191], v[108:111]
	v_mfma_f32_16x16x32_bf16 v[104:107], v[148:151], v[188:191], v[104:107]
	v_mfma_f32_16x16x32_bf16 v[92:95], v[140:143], v[198:201], v[92:95]
	v_mfma_f32_16x16x32_bf16 v[88:91], v[148:151], v[198:201], v[88:91]
	v_mfma_f32_16x16x32_bf16 v[76:79], v[140:143], v[206:209], v[76:79]
	v_mfma_f32_16x16x32_bf16 v[72:75], v[148:151], v[206:209], v[72:75]
	v_mfma_f32_16x16x32_bf16 v[124:127], v[144:147], v[176:179], v[124:127]
	v_mfma_f32_16x16x32_bf16 v[120:123], v[152:155], v[176:179], v[120:123]
	v_mfma_f32_16x16x32_bf16 v[108:111], v[144:147], v[194:197], v[108:111]
	v_mfma_f32_16x16x32_bf16 v[104:107], v[152:155], v[194:197], v[104:107]
	v_mfma_f32_16x16x32_bf16 v[92:95], v[144:147], v[202:205], v[92:95]
	v_mfma_f32_16x16x32_bf16 v[88:91], v[152:155], v[202:205], v[88:91]
	v_mfma_f32_16x16x32_bf16 v[76:79], v[144:147], v[210:213], v[76:79]
	v_mfma_f32_16x16x32_bf16 v[72:75], v[152:155], v[210:213], v[72:75]
	v_mfma_f32_16x16x32_bf16 v[116:119], v[156:159], v[172:175], v[116:119]
	v_mfma_f32_16x16x32_bf16 v[112:115], v[164:167], v[172:175], v[112:115]
	v_mfma_f32_16x16x32_bf16 v[100:103], v[156:159], v[188:191], v[100:103]
	v_mfma_f32_16x16x32_bf16 v[96:99], v[164:167], v[188:191], v[96:99]
	v_mfma_f32_16x16x32_bf16 v[84:87], v[156:159], v[198:201], v[84:87]
	v_mfma_f32_16x16x32_bf16 v[80:83], v[164:167], v[198:201], v[80:83]
	v_mfma_f32_16x16x32_bf16 v[68:71], v[156:159], v[206:209], v[68:71]
	v_mfma_f32_16x16x32_bf16 v[64:67], v[164:167], v[206:209], v[64:67]
	v_mfma_f32_16x16x32_bf16 v[116:119], v[160:163], v[176:179], v[116:119]
	v_mfma_f32_16x16x32_bf16 v[112:115], v[168:171], v[176:179], v[112:115]
	v_mfma_f32_16x16x32_bf16 v[100:103], v[160:163], v[194:197], v[100:103]
	v_mfma_f32_16x16x32_bf16 v[96:99], v[168:171], v[194:197], v[96:99]
	v_mfma_f32_16x16x32_bf16 v[84:87], v[160:163], v[202:205], v[84:87]
	v_mfma_f32_16x16x32_bf16 v[80:83], v[168:171], v[202:205], v[80:83]
	v_mfma_f32_16x16x32_bf16 v[68:71], v[160:163], v[210:213], v[68:71]
	v_mfma_f32_16x16x32_bf16 v[64:67], v[168:171], v[210:213], v[64:67]
	s_barrier
; #define PG8_STAGE(bufoff, gbase, voff) do { _Pragma("unroll") for (int _i = 0; _i < 2; ++_i) \
;         __builtin_amdgcn_global_load_lds((const unsigned*)((const char*)(gbase) + (voff)[_i]), (LAS unsigned*)(lds + (bufoff) + ldsw + _i * 8192), 16, 0, 0); } while (0)
; #define PG8_LDA(dst, b, h) do { _Pragma("unroll") for (int m = 0; m < 4; ++m) _Pragma("unroll") for (int k = 0; k < 2; ++k) dst[m][k] = *(const LAS bf16x8*)(lds + PG8_SA(b, h) + aoff + m * 2048 + k * 1024); } while (0)
; #define PG8_MMA(ai, bj, At, Bt) do { __builtin_amdgcn_s_setprio(1); _Pragma("unroll") for (int m = 0; m < 4; ++m) _Pragma("unroll") for (int n = 0; n < 2; ++n) _Pragma("unroll") for (int k = 0; k < 2; ++k) \
;         acc[ai][bj][m][n] = __builtin_amdgcn_mfma_f32_16x16x32_bf16(Bt[n][k], At[m][k], acc[ai][bj][m][n], 0, 0, 0); __builtin_amdgcn_s_setprio(0); } while (0)
; #define PG8_WAIT_V(n) asm volatile("s_waitcnt vmcnt(" #n ")" ::: "memory")
; #define PG8_WAIT_L(n) asm volatile("s_waitcnt lgkmcnt(" #n ")" ::: "memory")
; #define PG8_BAR __builtin_amdgcn_s_barrier()
; #define PG8_SCHED __builtin_amdgcn_sched_barrier(0)
; template <class Epi, class Sched, bool ALIGN_EPI = false, bool SP2 = false>
; __device__ __forceinline__ void gemm_phase(LAS unsigned char* lds, const Gemm g, const Sched S, const Epi E) {
;     ...
;         for (int t = 0; t < nt; t += 2) {
;     ...
;             PG8_LDA(At, 1, 1); PG8_STAGE(PG8_SB(1, 0), b3, voffB); PG8_STAGE(PG8_SB(1, 1), b3 + hstep, voffB); PG8_STAGE(PG8_SA(1, 0), a3, voffA);
;             PG8_WAIT_V(8); PG8_WAIT_L(0); PG8_BAR; PG8_MMA(1, 0, At, B0); PG8_MMA(1, 1, At, B1); PG8_BAR; PG8_SCHED;
	s_add_i32 s36, s51, s11
	v_lshl_add_u64 v[214:215], v[214:215], 0, s[20:21]
	s_mov_b32 m0, s36
	ds_read_b128 v[172:175], v185 offset:49152
	ds_read_b128 v[176:179], v185 offset:50176
	ds_read_b128 v[188:191], v185 offset:51200
	ds_read_b128 v[194:197], v185 offset:52224
	ds_read_b128 v[198:201], v185 offset:53248
	ds_read_b128 v[202:205], v185 offset:54272
	ds_read_b128 v[206:209], v185 offset:55296
	ds_read_b128 v[210:213], v185 offset:56320
	global_load_lds_dwordx4 v[214:215], off
	s_add_i32 m0, s36, 0x2000
	s_add_u32 s34, s34, 0x158080
	v_lshl_add_u64 v[214:215], v[216:217], 0, s[20:21]
	s_addc_u32 s35, s35, 0
	s_add_i32 s36, s52, s11
	global_load_lds_dwordx4 v[214:215], off
	v_lshl_add_u64 v[214:215], s[34:35], 0, v[128:129]
	s_mov_b32 m0, s36
	s_nop 0
	global_load_lds_dwordx4 v[214:215], off
	v_lshl_add_u64 v[214:215], s[34:35], 0, v[130:131]
	s_add_i32 m0, s36, 0x2000
	s_nop 0
	global_load_lds_dwordx4 v[214:215], off
	v_lshl_add_u64 v[214:215], v[218:219], 0, s[20:21]
	s_mov_b32 m0, s39
	s_nop 0
	global_load_lds_dwordx4 v[214:215], off
	v_lshl_add_u64 v[214:215], v[220:221], 0, s[20:21]
	s_mov_b32 m0, s40
	s_nop 0
	global_load_lds_dwordx4 v[214:215], off
	s_waitcnt vmcnt(8)
	s_waitcnt lgkmcnt(0)
	s_barrier
	s_waitcnt lgkmcnt(0)
	v_mfma_f32_16x16x32_bf16 v[60:63], v[140:143], v[172:175], v[60:63]
	v_mfma_f32_16x16x32_bf16 v[56:59], v[148:151], v[172:175], v[56:59]
	v_mfma_f32_16x16x32_bf16 v[44:47], v[140:143], v[188:191], v[44:47]
	v_mfma_f32_16x16x32_bf16 v[40:43], v[148:151], v[188:191], v[40:43]
	v_mfma_f32_16x16x32_bf16 v[28:31], v[140:143], v[198:201], v[28:31]
	v_mfma_f32_16x16x32_bf16 v[24:27], v[148:151], v[198:201], v[24:27]
	v_mfma_f32_16x16x32_bf16 v[12:15], v[140:143], v[206:209], v[12:15]
	v_mfma_f32_16x16x32_bf16 v[8:11], v[148:151], v[206:209], v[8:11]
	v_mfma_f32_16x16x32_bf16 v[60:63], v[144:147], v[176:179], v[60:63]
	v_mfma_f32_16x16x32_bf16 v[56:59], v[152:155], v[176:179], v[56:59]
	v_mfma_f32_16x16x32_bf16 v[44:47], v[144:147], v[194:197], v[44:47]
	v_mfma_f32_16x16x32_bf16 v[40:43], v[152:155], v[194:197], v[40:43]
	v_mfma_f32_16x16x32_bf16 v[28:31], v[144:147], v[202:205], v[28:31]
	v_mfma_f32_16x16x32_bf16 v[24:27], v[152:155], v[202:205], v[24:27]
	v_mfma_f32_16x16x32_bf16 v[12:15], v[144:147], v[210:213], v[12:15]
	v_mfma_f32_16x16x32_bf16 v[8:11], v[152:155], v[210:213], v[8:11]
	v_mfma_f32_16x16x32_bf16 v[52:55], v[156:159], v[172:175], v[52:55]
	v_mfma_f32_16x16x32_bf16 v[48:51], v[164:167], v[172:175], v[48:51]
	v_mfma_f32_16x16x32_bf16 v[36:39], v[156:159], v[188:191], v[36:39]
	v_mfma_f32_16x16x32_bf16 v[32:35], v[164:167], v[188:191], v[32:35]
	v_mfma_f32_16x16x32_bf16 v[20:23], v[156:159], v[198:201], v[20:23]
	v_mfma_f32_16x16x32_bf16 v[16:19], v[164:167], v[198:201], v[16:19]
	v_mfma_f32_16x16x32_bf16 v[4:7], v[156:159], v[206:209], v[4:7]
	v_mfma_f32_16x16x32_bf16 v[0:3], v[164:167], v[206:209], v[0:3]
	v_mfma_f32_16x16x32_bf16 v[52:55], v[160:163], v[176:179], v[52:55]
	v_mfma_f32_16x16x32_bf16 v[48:51], v[168:171], v[176:179], v[48:51]
	v_mfma_f32_16x16x32_bf16 v[36:39], v[160:163], v[194:197], v[36:39]
	v_mfma_f32_16x16x32_bf16 v[32:35], v[168:171], v[194:197], v[32:35]
	v_mfma_f32_16x16x32_bf16 v[20:23], v[160:163], v[202:205], v[20:23]
	v_mfma_f32_16x16x32_bf16 v[16:19], v[168:171], v[202:205], v[16:19]
	v_mfma_f32_16x16x32_bf16 v[4:7], v[160:163], v[210:213], v[4:7]
	v_mfma_f32_16x16x32_bf16 v[0:3], v[168:171], v[210:213], v[0:3]
	s_barrier
	s_add_i32 s50, s50, 2
	s_add_u32 s26, s26, 0x100
	s_addc_u32 s27, s27, 0
	s_add_u32 s48, s48, 0x100
	s_addc_u32 s49, s49, 0
	s_cmpk_gt_u32 s50, 0x53
	s_cbranch_scc0 .LBB0_1375
	s_and_b64 vcc, exec, s[22:23]
	s_cbranch_vccz .LBB0_1378
	s_barrier
